# attention tile loops rotated: next tile's slot/address/DMA-flag setup computed before the barrier so the first QK MFMA follows the barrier directly (on v5)
# speedup vs baseline: 1.0025x; 1.0025x over previous
; #define LAS __attribute__((address_space(3)))
; __device__ __forceinline__ int v_rd_base(int lane) { return ((lane & 3) << 3) | (((lane >> 2) & 3) << 6) | (((lane >> 4) & 1) << 5) | (((lane >> 5) & 1) << 8); }
; #define VMW0() asm volatile("s_waitcnt vmcnt(0)" ::: "memory")
; template <int DQK, bool DOUBLE> ...
;     ...
;     const int wid = __builtin_amdgcn_readfirstlane(tid >> 6), lane = tid & 63, r32 = lane & 31, hi = lane >> 5;
;     LAS char* V_lds = lds; LAS char* K_lds = lds + K_OFF;
;     bf16x8 qr[DQK / 16];
;     { const bf16_t* Qw = Q + (size_t)(wid * 32 + r32) * ldq + hi * 8;
; #pragma unroll
;       for (int d0 = 0; d0 < DQK / 16; ++d0) qr[d0] = *(const bf16x8*)(Qw + d0 * 16); }
; #pragma unroll
;     for (int d = 0; d < 4; ++d) o[d] = f32x16{};
;     l_reg = 0.f;
;     int vrow[2], vcol[2], krow[NLD], kcol[NLD];
; #pragma unroll
;     for (int i = 0; i < 2; ++i) { const int q = tid + 512 * i, sub = q >> 5, within = q & 31, kk = (sub >> 2) * 8 + (within >> 2);
;         vrow[i] = kk; vcol[i] = (sub & 3) * 32 + (within & 3) * 8; }
; #pragma unroll
;     for (int i = 0; i < NLD; ++i) { const int q = tid + 512 * i, row = q / NCH, chp = q % NCH; const int x = (RB == 256) ? (row & 15) : ((row >> 1) & 7);
;         krow[i] = row; kcol[i] = (chp ^ x) * 8; }
;     const unsigned vb0 = (unsigned)(uintptr_t)V_lds + v_rd_base(lane);
;     int ka[8];
; #pragma unroll
;     for (int q = 0; q < 8; ++q) ka[q] = kswz<RB>(r32, q * 32 + hi * 16);
;     ...
;     bf16x8 pa0, pa1, pa2, pa3;
;     __syncthreads();
;     DMA(0, 0); DMA(1, 1); VMW0(); __syncthreads();
.LBB0_139:
	v_mov_b32_e32 v164, v186
	s_lshl_b32 s45, s70, 8
	v_readfirstlane_b32 s2, v164
	s_ashr_i32 s73, s2, 6
	s_and_b32 s2, s2, 0x3fffffc0
	s_lshl_b32 s2, s2, 2
	s_add_i32 s90, s2, 0
	s_lshl_b32 s2, s73, 5
	s_add_i32 s46, s45, 0x4000
	s_lshl_b32 s44, s70, 12
	s_add_i32 s90, s90, 0x1e000
	s_ashr_i32 s31, s30, 31
	s_ashr_i32 s3, s2, 31
	s_add_u32 s36, s2, s30
	s_addc_u32 s37, s3, s31
	v_and_b32_e32 v182, 63, v164
	v_and_b32_e32 v181, 31, v164
	v_bfe_u32 v176, v164, 5, 1
	s_mov_b64 s[56:57], -1
	s_mov_b64 s[48:49], 0
	s_cmp_lt_i32 s69, 1
	s_mulk_i32 s73, 0x4200
	s_mov_b64 s[50:51], 0
	s_cbranch_scc1 .LBB0_151
	s_cmp_eq_u32 s69, 1
	s_mov_b64 s[50:51], -1
	s_cbranch_scc0 .LBB0_150
	s_mul_i32 s3, s30, 0xc00
	v_readlane_b32 s4, v251, 32
	s_mul_hi_i32 s2, s30, 0xc00
	v_readlane_b32 s5, v251, 33
	s_add_u32 s4, s4, s3
	s_addc_u32 s5, s5, s2
	s_mul_i32 s2, s72, 0xc0
	s_ashr_i32 s3, s2, 31
	s_lshl_b64 s[2:3], s[2:3], 1
	s_add_u32 s4, s4, s2
	s_addc_u32 s5, s5, s3
	v_readlane_b32 s20, v251, 34
	v_readlane_b32 s21, v251, 35
	s_add_u32 s56, s20, s2
	s_addc_u32 s57, s21, s3
	s_lshl_b32 s50, s72, 7
	s_ashr_i32 s51, s50, 31
	s_lshl_b64 s[2:3], s[50:51], 1
	v_readlane_b32 s20, v251, 38
	v_readlane_b32 s21, v251, 39
	s_add_u32 s58, s20, s2
	v_readfirstlane_b32 s2, v164
	s_addc_u32 s59, s21, s3
	s_ashr_i32 s20, s2, 6
	v_lshl_or_b32 v1, s20, 5, v181
	v_mov_b64_e32 v[2:3], s[4:5]
	s_movk_i32 s41, 0xc00
	v_mad_i64_i32 v[2:3], s[2:3], v1, s41, v[2:3]
	v_lshlrev_b32_e32 v166, 4, v176
	v_mov_b32_e32 v167, v177
	v_lshl_add_u64 v[2:3], v[2:3], 0, v[166:167]
	global_load_dword v0, v177, s[14:15] offset:8
	global_load_dwordx4 v[112:115], v[2:3], off
	global_load_dwordx4 v[116:119], v[2:3], off offset:32
	global_load_dwordx4 v[120:123], v[2:3], off offset:64
	global_load_dwordx4 v[124:127], v[2:3], off offset:96
	s_waitcnt lgkmcnt(0)
	global_load_dwordx4 v[128:131], v[2:3], off offset:128
	global_load_dwordx4 v[132:135], v[2:3], off offset:160
	global_load_dwordx4 v[136:139], v[2:3], off offset:192
	global_load_dwordx4 v[140:143], v[2:3], off offset:224
	global_load_dwordx4 v[144:147], v[2:3], off offset:256
	global_load_dwordx4 v[148:151], v[2:3], off offset:288
	global_load_dwordx4 v[152:155], v[2:3], off offset:320
	global_load_dwordx4 v[156:159], v[2:3], off offset:352
	v_and_b32_e32 v2, 0x60, v164
	v_lshlrev_b32_e32 v3, 3, v164
	v_lshrrev_b32_e32 v1, 2, v164
	v_and_or_b32 v3, v3, 24, v2
	v_ashrrev_i32_e32 v2, 4, v164
	v_add_u32_e32 v4, 0x200, v164
	v_bfi_b32 v168, -8, v2, v1
	v_ashrrev_i32_e32 v2, 4, v4
	s_mov_b32 s2, 0x2aaaaaab
	v_bfi_b32 v170, -8, v2, v1
	v_mul_hi_i32 v1, v164, s2
	v_lshrrev_b32_e32 v2, 31, v1
	v_ashrrev_i32_e32 v1, 2, v1
	v_add_u32_e32 v172, v1, v2
	v_mul_lo_u32 v1, v172, 24
	v_sub_u32_e32 v1, v164, v1
	v_lshrrev_b32_e32 v2, 1, v172
	v_bitop3_b32 v1, v2, v1, 7 bitop3:0x6c
	v_lshlrev_b32_e32 v2, 3, v1
	v_mul_hi_i32 v1, v4, s2
	v_lshrrev_b32_e32 v5, 31, v1
	v_ashrrev_i32_e32 v1, 2, v1
	v_add_u32_e32 v174, v1, v5
	v_mul_lo_u32 v1, v174, 24
	v_sub_u32_e32 v1, v4, v1
	v_lshrrev_b32_e32 v4, 1, v174
	v_bitop3_b32 v1, v4, v1, 7 bitop3:0x6c
	s_ashr_i32 s47, s46, 31
	v_ashrrev_i32_e32 v169, 31, v168
	v_lshlrev_b32_e32 v4, 3, v1
	v_add_u32_e32 v1, 0x400, v164
	v_lshl_add_u64 v[8:9], v[168:169], 0, s[46:47]
	v_mul_hi_i32 v5, v1, s2
	s_lshl_b32 s2, s20, 10
	v_lshlrev_b64 v[8:9], 11, v[8:9]
	s_add_i32 s3, s2, 0
	v_lshl_add_u64 v[8:9], s[58:59], 0, v[8:9]
	v_lshlrev_b32_e32 v80, 1, v3
	v_mov_b32_e32 v81, v177
	v_lshl_add_u64 v[8:9], v[8:9], 0, v[80:81]
	s_mov_b32 m0, s3
	v_ashrrev_i32_e32 v171, 31, v170
	s_barrier
	global_load_lds_dwordx4 v[8:9], off
	v_lshl_add_u64 v[8:9], v[170:171], 0, s[46:47]
	v_lshlrev_b64 v[8:9], 11, v[8:9]
	v_lshl_add_u64 v[8:9], s[58:59], 0, v[8:9]
	s_add_i32 s21, s3, 0x2000
	v_lshl_add_u64 v[8:9], v[8:9], 0, v[80:81]
	s_mov_b32 m0, s21
	v_ashrrev_i32_e32 v173, 31, v172
	global_load_lds_dwordx4 v[8:9], off
	v_lshl_add_u64 v[8:9], v[172:173], 0, s[46:47]
	v_mov_b64_e32 v[84:85], s[56:57]
	v_lshrrev_b32_e32 v6, 31, v5
	v_ashrrev_i32_e32 v5, 2, v5
	v_mad_u64_u32 v[10:11], s[4:5], v8, s41, v[84:85]
	v_ashrrev_i32_e32 v3, 31, v2
	v_add_u32_e32 v192, v5, v6
	s_add_i32 s20, s3, 0xc000
	v_mad_i32_i24 v11, v9, s41, v11
	v_lshlrev_b64 v[82:83], 1, v[2:3]
	v_mul_lo_u32 v5, v192, 24
	v_lshl_add_u64 v[2:3], v[10:11], 0, v[82:83]
	s_mov_b32 m0, s20
	v_ashrrev_i32_e32 v175, 31, v174
	v_sub_u32_e32 v1, v1, v5
	v_lshrrev_b32_e32 v5, 1, v192
	global_load_lds_dwordx4 v[2:3], off
	v_lshl_add_u64 v[2:3], v[174:175], 0, s[46:47]
	v_bitop3_b32 v1, v5, v1, 7 bitop3:0x6c
	v_mad_u64_u32 v[8:9], s[4:5], v2, s41, v[84:85]
	v_ashrrev_i32_e32 v5, 31, v4
	v_mad_i32_i24 v9, v3, s41, v9
	v_lshlrev_b64 v[86:87], 1, v[4:5]
	s_add_i32 s33, s3, 0xe000
	v_lshl_add_u64 v[2:3], v[8:9], 0, v[86:87]
	s_mov_b32 m0, s33
	v_ashrrev_i32_e32 v193, 31, v192
	v_lshlrev_b32_e32 v6, 3, v1
	global_load_lds_dwordx4 v[2:3], off
	v_lshl_add_u64 v[2:3], v[192:193], 0, s[46:47]
	v_mad_u64_u32 v[4:5], s[4:5], v2, s41, v[84:85]
	v_ashrrev_i32_e32 v7, 31, v6
	v_mad_i32_i24 v5, v3, s41, v5
	v_lshlrev_b64 v[88:89], 1, v[6:7]
	s_add_i32 s35, s3, 0x10000
	s_add_i32 s4, s45, 0x4040
	v_lshl_add_u64 v[2:3], v[4:5], 0, v[88:89]
	s_mov_b32 m0, s35
	s_ashr_i32 s5, s4, 31
	global_load_lds_dwordx4 v[2:3], off
	v_lshl_add_u64 v[2:3], v[168:169], 0, s[4:5]
	v_lshlrev_b64 v[2:3], 11, v[2:3]
	v_lshl_add_u64 v[2:3], s[58:59], 0, v[2:3]
	s_add_i32 m0, s3, 0x4000
	v_lshl_add_u64 v[2:3], v[2:3], 0, v[80:81]
	global_load_lds_dwordx4 v[2:3], off
	v_lshl_add_u64 v[2:3], v[170:171], 0, s[4:5]
	v_lshlrev_b64 v[2:3], 11, v[2:3]
	v_lshl_add_u64 v[2:3], s[58:59], 0, v[2:3]
	v_lshl_add_u64 v[2:3], v[2:3], 0, v[80:81]
	s_add_i32 m0, s3, 0x6000
	v_mul_u32_u24_e32 v1, 0x180, v181
	global_load_lds_dwordx4 v[2:3], off
	v_lshl_add_u64 v[2:3], v[172:173], 0, s[4:5]
	v_mad_u64_u32 v[4:5], s[42:43], v2, s41, v[84:85]
	v_mad_i32_i24 v5, v3, s41, v5
	s_add_i32 m0, s3, 0x12000
	v_lshl_add_u64 v[2:3], v[4:5], 0, v[82:83]
	global_load_lds_dwordx4 v[2:3], off
	v_lshl_add_u64 v[2:3], v[174:175], 0, s[4:5]
	v_mad_u64_u32 v[4:5], s[42:43], v2, s41, v[84:85]
	v_mad_i32_i24 v5, v3, s41, v5
	v_lshl_add_u64 v[2:3], v[4:5], 0, v[86:87]
	s_add_i32 m0, s3, 0x14000
	s_waitcnt vmcnt(0)
	v_mov_b32_e32 v6, v0
	global_load_lds_dwordx4 v[2:3], off
	v_lshl_add_u64 v[2:3], v[192:193], 0, s[4:5]
	v_mad_u64_u32 v[4:5], s[4:5], v2, s41, v[84:85]
	v_mad_i32_i24 v5, v3, s41, v5
	s_add_i32 s4, s45, 0x4080
	v_lshl_add_u64 v[2:3], v[4:5], 0, v[88:89]
	s_add_i32 m0, s3, 0x16000
	s_ashr_i32 s5, s4, 31
	global_load_lds_dwordx4 v[2:3], off
	v_lshl_add_u64 v[2:3], v[168:169], 0, s[4:5]
	v_lshlrev_b64 v[2:3], 11, v[2:3]
	v_lshl_add_u64 v[2:3], s[58:59], 0, v[2:3]
	s_add_i32 m0, s3, 0x8000
	v_lshl_add_u64 v[2:3], v[2:3], 0, v[80:81]
	s_waitcnt vmcnt(0)
	s_waitcnt vmcnt(0) lgkmcnt(0)
	s_barrier
; #define LAS __attribute__((address_space(3)))
; #define SBAR() __builtin_amdgcn_sched_barrier(0)
; template <int DQK>
; __device__ __forceinline__ void qkt(f32x16& p0, f32x16& p1, const LAS char* Ks, const bf16x8 (&qr)[DQK / 16], const int (&ka)[8], float nMB) {
;     constexpr int RB = DQK * 2, NA = (RB == 256) ? 8 : 4;
; #pragma unroll
;     for (int r = 0; r < 16; ++r) { p0[r] = nMB; p1[r] = nMB; }
; #pragma unroll
;     for (int d0 = 0; d0 < DQK / 16; ++d0) {
;         const LAS char* a = Ks + ka[d0 % NA] + (d0 / NA) * (NA * 32);
;         const bf16x8 b0 = *(const LAS bf16x8*)(a);
;         const bf16x8 b1 = *(const LAS bf16x8*)(a + 32 * RB);
;         p0 = __builtin_amdgcn_mfma_f32_32x32x16_bf16(b0, qr[d0], p0, 0, 0, 0);
;         p1 = __builtin_amdgcn_mfma_f32_32x32x16_bf16(b1, qr[d0], p1, 0, 0, 0); }
; }
; template <int DQK, bool DOUBLE> ...
;     ...
;         DMA(2, 2);
;         int bc = 0, bn = 1, bf = 2;
;         for (int j = 0; j < NT; ++j) {
;             SBAR(); qkt<DQK>(p0, p1, K_lds + bc * K_STRIDE, qr, ka, nMB);
;             partialSM(p0, p1); finishSM(p0, p1, l_reg, pa0, pa1, pa2, pa3); SBAR();
	global_load_lds_dwordx4 v[2:3], off
	v_lshl_add_u64 v[2:3], v[170:171], 0, s[4:5]
	v_lshlrev_b64 v[2:3], 11, v[2:3]
	v_lshl_add_u64 v[2:3], s[58:59], 0, v[2:3]
	v_lshl_add_u64 v[2:3], v[2:3], 0, v[80:81]
	s_add_i32 m0, s3, 0xa000
	v_mov_b32_e32 v7, v0
	global_load_lds_dwordx4 v[2:3], off
	v_lshl_add_u64 v[2:3], v[172:173], 0, s[4:5]
	v_mad_u64_u32 v[4:5], s[42:43], v2, s41, v[84:85]
	v_mad_i32_i24 v5, v3, s41, v5
	s_add_i32 m0, s3, 0x18000
	v_lshl_add_u64 v[2:3], v[4:5], 0, v[82:83]
	global_load_lds_dwordx4 v[2:3], off
	v_lshl_add_u64 v[2:3], v[174:175], 0, s[4:5]
	v_mad_u64_u32 v[4:5], s[42:43], v2, s41, v[84:85]
	v_mad_i32_i24 v5, v3, s41, v5
	v_lshl_add_u64 v[2:3], v[4:5], 0, v[86:87]
	s_add_i32 m0, s3, 0x1a000
	s_movk_i32 s42, 0x118
	global_load_lds_dwordx4 v[2:3], off
	v_lshl_add_u64 v[2:3], v[192:193], 0, s[4:5]
	v_mad_u64_u32 v[4:5], s[4:5], v2, s41, v[84:85]
	v_mad_i32_i24 v5, v3, s41, v5
	v_lshl_add_u64 v[2:3], v[4:5], 0, v[88:89]
	s_add_i32 m0, s3, 0x1c000
	s_mov_b32 s5, 1
	global_load_lds_dwordx4 v[2:3], off
	v_lshlrev_b32_e32 v2, 3, v181
	v_and_b32_e32 v2, 0x70, v2
	v_or_b32_e32 v3, 32, v166
	v_bitop3_b32 v165, v3, v1, v2 bitop3:0xde
	v_or_b32_e32 v3, 64, v166
	v_bitop3_b32 v167, v3, v1, v2 bitop3:0xde
	v_or_b32_e32 v3, 0x60, v166
	v_bitop3_b32 v161, v166, v1, v2 bitop3:0xde
	v_bitop3_b32 v187, v3, v1, v2 bitop3:0xde
	v_lshlrev_b32_e32 v1, 1, v182
	v_and_b32_e32 v1, 32, v1
	v_lshlrev_b32_e32 v2, 3, v182
	v_lshlrev_b32_e32 v3, 4, v182
	v_and_b32_e32 v16, 0xc0, v3
	v_and_or_b32 v17, v2, s42, v1
	s_mov_b32 s4, 2
	v_mov_b32_e32 v1, v0
	v_mov_b32_e32 v2, v0
	v_mov_b32_e32 v3, v0
	v_mov_b32_e32 v4, v0
	v_mov_b32_e32 v5, v0
	v_mov_b32_e32 v8, v0
	v_mov_b32_e32 v9, v0
	v_mov_b32_e32 v10, v0
	v_mov_b32_e32 v11, v0
	v_mov_b32_e32 v12, v0
	v_mov_b32_e32 v13, v0
	v_mov_b32_e32 v14, v0
	v_mov_b32_e32 v15, v0
	v_add3_u32 v191, v16, 0, v17
	s_add_i32 s60, s45, 0x40c0
	v_add_u32_e32 v56, 0, v161
	ds_read_b128 v[16:19], v56 offset:49152
	ds_read_b128 v[48:51], v56 offset:61440
	v_add_u32_e32 v57, 0, v165
	v_add_u32_e32 v58, 0, v167
	v_add_u32_e32 v59, 0, v187
	s_waitcnt lgkmcnt(0)
	v_mfma_f32_32x32x16_bf16 v[32:47], v[16:19], v[112:115], v[0:15]
	v_mfma_f32_32x32x16_bf16 v[16:31], v[48:51], v[112:115], v[0:15]
	ds_read_b128 v[48:51], v57 offset:49152
	ds_read_b128 v[52:55], v57 offset:61440
	s_waitcnt lgkmcnt(0)
	v_mfma_f32_32x32x16_bf16 v[32:47], v[48:51], v[116:119], v[32:47]
	v_mfma_f32_32x32x16_bf16 v[16:31], v[52:55], v[116:119], v[16:31]
	ds_read_b128 v[48:51], v58 offset:49152
	ds_read_b128 v[52:55], v58 offset:61440
	s_waitcnt lgkmcnt(0)
	v_mfma_f32_32x32x16_bf16 v[32:47], v[48:51], v[120:123], v[32:47]
	v_mfma_f32_32x32x16_bf16 v[16:31], v[52:55], v[120:123], v[16:31]
	ds_read_b128 v[48:51], v59 offset:49152
	ds_read_b128 v[52:55], v59 offset:61440
	s_waitcnt lgkmcnt(0)
	v_mfma_f32_32x32x16_bf16 v[32:47], v[48:51], v[124:127], v[32:47]
	v_mfma_f32_32x32x16_bf16 v[16:31], v[52:55], v[124:127], v[16:31]
	ds_read_b128 v[48:51], v56 offset:49280
	ds_read_b128 v[52:55], v56 offset:61568
	s_waitcnt lgkmcnt(0)
	v_mfma_f32_32x32x16_bf16 v[32:47], v[48:51], v[128:131], v[32:47]
	v_mfma_f32_32x32x16_bf16 v[16:31], v[52:55], v[128:131], v[16:31]
	ds_read_b128 v[48:51], v57 offset:49280
	ds_read_b128 v[52:55], v57 offset:61568
	s_waitcnt lgkmcnt(0)
	v_mfma_f32_32x32x16_bf16 v[32:47], v[48:51], v[132:135], v[32:47]
	v_mfma_f32_32x32x16_bf16 v[16:31], v[52:55], v[132:135], v[16:31]
	ds_read_b128 v[48:51], v58 offset:49280
	ds_read_b128 v[52:55], v58 offset:61568
	s_waitcnt lgkmcnt(0)
	v_mfma_f32_32x32x16_bf16 v[32:47], v[48:51], v[136:139], v[32:47]
	v_mfma_f32_32x32x16_bf16 v[16:31], v[52:55], v[136:139], v[16:31]
	ds_read_b128 v[48:51], v59 offset:49280
	ds_read_b128 v[52:55], v59 offset:61568
	s_waitcnt lgkmcnt(0)
	v_mfma_f32_32x32x16_bf16 v[32:47], v[48:51], v[140:143], v[32:47]
	v_mfma_f32_32x32x16_bf16 v[16:31], v[52:55], v[140:143], v[16:31]
	ds_read_b128 v[48:51], v56 offset:49408
	ds_read_b128 v[52:55], v56 offset:61696
	s_waitcnt lgkmcnt(0)
	v_mfma_f32_32x32x16_bf16 v[32:47], v[48:51], v[144:147], v[32:47]
	v_mfma_f32_32x32x16_bf16 v[16:31], v[52:55], v[144:147], v[16:31]
	ds_read_b128 v[48:51], v57 offset:49408
	ds_read_b128 v[52:55], v57 offset:61696
	s_waitcnt lgkmcnt(0)
	v_mfma_f32_32x32x16_bf16 v[32:47], v[48:51], v[148:151], v[32:47]
	v_mfma_f32_32x32x16_bf16 v[16:31], v[52:55], v[148:151], v[16:31]
	ds_read_b128 v[48:51], v58 offset:49408
	ds_read_b128 v[52:55], v58 offset:61696
	s_waitcnt lgkmcnt(0)
	v_mfma_f32_32x32x16_bf16 v[32:47], v[48:51], v[152:155], v[32:47]
	v_mfma_f32_32x32x16_bf16 v[16:31], v[52:55], v[152:155], v[16:31]
	ds_read_b128 v[48:51], v59 offset:49408
	ds_read_b128 v[52:55], v59 offset:61696
	s_waitcnt lgkmcnt(0)
; #define SBAR() __builtin_amdgcn_sched_barrier(0)
; #define PK8(P, BASE, OUT) do { u32x4 w = {cvt_pk_bf16(P[BASE + 0], P[BASE + 1]), cvt_pk_bf16(P[BASE + 2], P[BASE + 3]), cvt_pk_bf16(P[BASE + 4], P[BASE + 5]), cvt_pk_bf16(P[BASE + 6], P[BASE + 7])}; \
;     OUT = *reinterpret_cast<bf16x8*>(&w); } while (0)
; template <int D0> __device__ __forceinline__ void pv_one(f32x16& od, unsigned vb, bf16x8 pa0, bf16x8 pa1, bf16x8 pa2, bf16x8 pa3) {
;     const s16x4 l0 = tr_read<v_rd_off(D0, 0, 0)>(vb), h0 = tr_read<v_rd_off(D0, 0, 1)>(vb), l1 = tr_read<v_rd_off(D0, 1, 0)>(vb), h1 = tr_read<v_rd_off(D0, 1, 1)>(vb);
;     const s16x4 l2 = tr_read<v_rd_off(D0, 2, 0)>(vb), h2 = tr_read<v_rd_off(D0, 2, 1)>(vb), l3 = tr_read<v_rd_off(D0, 3, 0)>(vb), h3 = tr_read<v_rd_off(D0, 3, 1)>(vb);
;     asm volatile("s_waitcnt lgkmcnt(0)" ::: "memory"); SBAR();
;     ...
;     od = __builtin_amdgcn_mfma_f32_32x32x16_bf16(pa0, PK(l0, h0), od, 0, 0, 0);
;     od = __builtin_amdgcn_mfma_f32_32x32x16_bf16(pa1, PK(l1, h1), od, 0, 0, 0);
;     od = __builtin_amdgcn_mfma_f32_32x32x16_bf16(pa2, PK(l2, h2), od, 0, 0, 0);
;     od = __builtin_amdgcn_mfma_f32_32x32x16_bf16(pa3, PK(l3, h3), od, 0, 0, 0);
;     ...
; }
; __device__ __forceinline__ void pv_d0(f32x16 (&o)[4], unsigned vb, bf16x8 pa0, bf16x8 pa1, bf16x8 pa2, bf16x8 pa3) {
;     pv_one<0>(o[0], vb, pa0, pa1, pa2, pa3); pv_one<1>(o[1], vb, pa0, pa1, pa2, pa3); pv_one<2>(o[2], vb, pa0, pa1, pa2, pa3); pv_one<3>(o[3], vb, pa0, pa1, pa2, pa3);
; }
; __device__ __forceinline__ void partialSM(f32x16& p0, f32x16& p1) {
; #pragma unroll
;     for (int r = 0; r < 16; ++r) p0[r] = __builtin_amdgcn_exp2f(p0[r]);
; }
; __device__ __forceinline__ void finishSM(f32x16& p0, f32x16& p1, float& l_reg, bf16x8& pa0, bf16x8& pa1, bf16x8& pa2, bf16x8& pa3) {
; #pragma unroll
;     for (int r = 0; r < 16; ++r) p1[r] = __builtin_amdgcn_exp2f(p1[r]);
;     float ps = 0;
; #pragma unroll
;     for (int r = 0; r < 16; ++r) ps += p0[r];
; #pragma unroll
;     for (int r = 0; r < 16; ++r) ps += p1[r];
;     l_reg += ps;
;     ...
;     PK8(p0, 0, pa0); PK8(p0, 8, pa1); PK8(p1, 0, pa2); PK8(p1, 8, pa3);
;     ...
; }
	v_mfma_f32_32x32x16_bf16 v[32:47], v[48:51], v[156:159], v[32:47]
	v_mfma_f32_32x32x16_bf16 v[16:31], v[52:55], v[156:159], v[16:31]
	s_nop 10
	v_exp_f32_e32 v32, v32
	v_exp_f32_e32 v33, v33
	v_exp_f32_e32 v34, v34
	v_exp_f32_e32 v35, v35
	v_exp_f32_e32 v36, v36
	v_add_f32_e32 v48, 0, v32
	v_exp_f32_e32 v37, v37
	v_add_f32_e32 v48, v33, v48
	v_exp_f32_e32 v38, v38
	v_add_f32_e32 v48, v34, v48
	v_exp_f32_e32 v39, v39
	v_add_f32_e32 v48, v35, v48
	v_exp_f32_e32 v40, v40
	v_add_f32_e32 v48, v36, v48
	v_exp_f32_e32 v41, v41
	v_add_f32_e32 v48, v37, v48
	v_exp_f32_e32 v42, v42
	v_add_f32_e32 v48, v38, v48
	v_exp_f32_e32 v43, v43
	v_add_f32_e32 v48, v39, v48
	v_exp_f32_e32 v44, v44
	v_add_f32_e32 v48, v40, v48
	v_exp_f32_e32 v45, v45
	v_add_f32_e32 v48, v41, v48
	v_exp_f32_e32 v46, v46
	v_add_f32_e32 v48, v42, v48
	v_exp_f32_e32 v47, v47
	v_add_f32_e32 v48, v43, v48
	v_exp_f32_e32 v16, v16
	v_add_f32_e32 v48, v44, v48
	v_exp_f32_e32 v17, v17
	v_add_f32_e32 v48, v45, v48
	v_exp_f32_e32 v18, v18
	v_add_f32_e32 v48, v46, v48
	v_exp_f32_e32 v19, v19
	v_add_f32_e32 v48, v47, v48
	v_exp_f32_e32 v20, v20
	v_add_f32_e32 v48, v16, v48
	v_exp_f32_e32 v21, v21
	v_add_f32_e32 v48, v17, v48
	v_exp_f32_e32 v22, v22
	v_add_f32_e32 v48, v18, v48
	v_exp_f32_e32 v23, v23
	v_add_f32_e32 v48, v19, v48
	v_exp_f32_e32 v24, v24
	v_add_f32_e32 v48, v20, v48
	v_exp_f32_e32 v25, v25
	v_add_f32_e32 v48, v21, v48
	v_exp_f32_e32 v26, v26
	v_add_f32_e32 v48, v22, v48
	v_exp_f32_e32 v27, v27
	v_add_f32_e32 v48, v23, v48
	v_exp_f32_e32 v28, v28
	v_add_f32_e32 v48, v24, v48
	v_exp_f32_e32 v29, v29
	v_add_f32_e32 v48, v25, v48
	v_exp_f32_e32 v30, v30
	v_add_f32_e32 v48, v26, v48
	v_exp_f32_e32 v31, v31
	v_add_f32_e32 v48, v27, v48
	v_add_f32_e32 v48, v28, v48
	v_add_f32_e32 v48, v29, v48
	v_add_f32_e32 v48, v30, v48
	v_add_f32_e32 v48, v31, v48
	v_add_f32_e32 v202, 0, v48
	v_cvt_pk_bf16_f32 v64, v32, v33
	v_cvt_pk_bf16_f32 v65, v34, v35
	v_cvt_pk_bf16_f32 v66, v36, v37
	v_cvt_pk_bf16_f32 v67, v38, v39
	v_cvt_pk_bf16_f32 v90, v40, v41
	v_cvt_pk_bf16_f32 v91, v42, v43
	v_cvt_pk_bf16_f32 v92, v44, v45
	v_cvt_pk_bf16_f32 v93, v46, v47
	v_cvt_pk_bf16_f32 v94, v16, v17
	v_cvt_pk_bf16_f32 v95, v18, v19
	v_cvt_pk_bf16_f32 v96, v20, v21
	v_cvt_pk_bf16_f32 v97, v22, v23
	v_cvt_pk_bf16_f32 v98, v24, v25
	v_cvt_pk_bf16_f32 v99, v26, v27
	v_cvt_pk_bf16_f32 v100, v28, v29
	v_cvt_pk_bf16_f32 v101, v30, v31
	ds_read_b64_tr_b16 v[16:17], v191 offset:0
	ds_read_b64_tr_b16 v[18:19], v191 offset:0x800
	ds_read_b64_tr_b16 v[32:33], v191 offset:0x1000
	ds_read_b64_tr_b16 v[34:35], v191 offset:0x1800
	ds_read_b64_tr_b16 v[36:37], v191 offset:0x2000
	ds_read_b64_tr_b16 v[38:39], v191 offset:0x2800
	ds_read_b64_tr_b16 v[40:41], v191 offset:0x3000
	ds_read_b64_tr_b16 v[42:43], v191 offset:0x3800
	s_waitcnt lgkmcnt(0)
	s_nop 0
	v_mfma_f32_32x32x16_bf16 v[16:31], v[64:67], v[16:19], 0
	v_mfma_f32_32x32x16_bf16 v[16:31], v[90:93], v[32:35], v[16:31]
	ds_read_b64_tr_b16 v[32:33], v191 offset:0x200
	ds_read_b64_tr_b16 v[34:35], v191 offset:0xa00
	ds_read_b64_tr_b16 v[48:49], v191 offset:0x1200
	ds_read_b64_tr_b16 v[50:51], v191 offset:0x1a00
	ds_read_b64_tr_b16 v[52:53], v191 offset:0x2200
	ds_read_b64_tr_b16 v[54:55], v191 offset:0x2a00
	ds_read_b64_tr_b16 v[56:57], v191 offset:0x3200
	v_mfma_f32_32x32x16_bf16 v[16:31], v[94:97], v[36:39], v[16:31]
	ds_read_b64_tr_b16 v[58:59], v191 offset:0x3a00
	s_waitcnt lgkmcnt(0)
	v_mfma_f32_32x32x16_bf16 v[16:31], v[98:101], v[40:43], v[16:31]
	v_mfma_f32_32x32x16_bf16 v[32:47], v[64:67], v[32:35], 0
	v_mfma_f32_32x32x16_bf16 v[32:47], v[90:93], v[48:51], v[32:47]
	ds_read_b64_tr_b16 v[48:49], v191 offset:0x400
	ds_read_b64_tr_b16 v[50:51], v191 offset:0xc00
	ds_read_b64_tr_b16 v[68:69], v191 offset:0x1400
	ds_read_b64_tr_b16 v[70:71], v191 offset:0x1c00
	ds_read_b64_tr_b16 v[72:73], v191 offset:0x2400
	ds_read_b64_tr_b16 v[74:75], v191 offset:0x2c00
	ds_read_b64_tr_b16 v[76:77], v191 offset:0x3400
	v_mfma_f32_32x32x16_bf16 v[32:47], v[94:97], v[52:55], v[32:47]
	ds_read_b64_tr_b16 v[78:79], v191 offset:0x3c00
	s_waitcnt lgkmcnt(0)
	v_mfma_f32_32x32x16_bf16 v[32:47], v[98:101], v[56:59], v[32:47]
	v_mfma_f32_32x32x16_bf16 v[48:63], v[64:67], v[48:51], 0
	v_mfma_f32_32x32x16_bf16 v[48:63], v[90:93], v[68:71], v[48:63]
	ds_read_b64_tr_b16 v[68:69], v191 offset:0x600
	ds_read_b64_tr_b16 v[70:71], v191 offset:0xe00
	ds_read_b64_tr_b16 v[102:103], v191 offset:0x1600
	ds_read_b64_tr_b16 v[104:105], v191 offset:0x1e00
	ds_read_b64_tr_b16 v[106:107], v191 offset:0x2600
	ds_read_b64_tr_b16 v[108:109], v191 offset:0x2e00
	ds_read_b64_tr_b16 v[194:195], v191 offset:0x3600
	v_mfma_f32_32x32x16_bf16 v[48:63], v[94:97], v[72:75], v[48:63]
	ds_read_b64_tr_b16 v[196:197], v191 offset:0x3e00
	s_waitcnt lgkmcnt(0)
	v_mfma_f32_32x32x16_bf16 v[48:63], v[98:101], v[76:79], v[48:63]
	v_mfma_f32_32x32x16_bf16 v[64:79], v[64:67], v[68:71], 0
	s_ashr_i32 s61, s60, 31
	v_lshl_add_u64 v[110:111], v[168:169], 0, s[60:61]
	v_lshlrev_b64 v[110:111], 11, v[110:111]
	v_lshl_add_u64 v[110:111], s[58:59], 0, v[110:111]
	s_mov_b32 m0, s3
	v_lshl_add_u64 v[110:111], v[110:111], 0, v[80:81]
	s_waitcnt vmcnt(0)
	s_waitcnt vmcnt(0)
	s_barrier
; #define SBAR() __builtin_amdgcn_sched_barrier(0)
; #define VMW0() asm volatile("s_waitcnt vmcnt(0)" ::: "memory")
; template <int DQK, bool DOUBLE> ...
;     ...
;         for (int j = 0; j < NT; ++j) {
;             SBAR(); qkt<DQK>(p0, p1, K_lds + bc * K_STRIDE, qr, ka, nMB);
;             partialSM(p0, p1); finishSM(p0, p1, l_reg, pa0, pa1, pa2, pa3); SBAR();
;             pv_d0(o, vb0 + bc * V_BYTES, pa0, pa1, pa2, pa3);
;             if (j + 1 < NT) { VMW0(); __syncthreads(); if (j + 3 < NT) DMA(j + 3, bc); }
;             { const int _t = bc; bc = bn; bn = bf; bf = _t; }
	global_load_lds_dwordx4 v[110:111], off
	v_lshl_add_u64 v[110:111], v[170:171], 0, s[60:61]
	v_mfma_f32_32x32x16_bf16 v[64:79], v[90:93], v[102:105], v[64:79]
	v_lshlrev_b64 v[90:91], 11, v[110:111]
	v_lshl_add_u64 v[90:91], s[58:59], 0, v[90:91]
	v_lshl_add_u64 v[90:91], v[90:91], 0, v[80:81]
	s_mov_b32 m0, s21
	v_lshl_add_u64 v[198:199], s[56:57], 0, v[86:87]
	global_load_lds_dwordx4 v[90:91], off
	v_lshl_add_u64 v[90:91], v[172:173], 0, s[60:61]
	v_mad_u64_u32 v[92:93], s[42:43], v90, s41, v[84:85]
	v_mad_i32_i24 v93, v91, s41, v93
	v_lshl_add_u64 v[90:91], v[92:93], 0, v[82:83]
	s_mov_b32 m0, s20
	v_mfma_f32_32x32x16_bf16 v[64:79], v[94:97], v[106:109], v[64:79]
	global_load_lds_dwordx4 v[90:91], off
	v_lshl_add_u64 v[90:91], v[174:175], 0, s[60:61]
	v_mad_u64_u32 v[92:93], s[20:21], v90, s41, v[84:85]
	v_mad_i32_i24 v93, v91, s41, v93
	v_lshl_add_u64 v[90:91], v[92:93], 0, v[86:87]
	s_mov_b32 m0, s33
	v_mfma_f32_32x32x16_bf16 v[64:79], v[98:101], v[194:197], v[64:79]
	global_load_lds_dwordx4 v[90:91], off
	v_lshl_add_u64 v[90:91], v[192:193], 0, s[60:61]
	v_mad_u64_u32 v[84:85], s[20:21], v90, s41, v[84:85]
	v_mad_i32_i24 v85, v91, s41, v85
	v_lshl_add_u64 v[84:85], v[84:85], 0, v[88:89]
	s_mov_b32 m0, s35
	v_lshl_add_u64 v[194:195], s[58:59], 0, v[80:81]
	global_load_lds_dwordx4 v[84:85], off
	v_lshl_add_u64 v[196:197], s[56:57], 0, v[82:83]
	v_lshl_add_u64 v[200:201], s[56:57], 0, v[88:89]
	s_add_i32 s20, s71, -1
	s_mov_b32 s21, 0
	s_mov_b32 s56, s44
	s_mov_b32 s35, 0
	s_waitcnt lgkmcnt(0)
	s_mov_b32 s33, s4
	s_mov_b32 s4, s35
	s_mul_i32 s35, s5, 0x6000
	s_add_i32 s35, s35, 0
	s_lshl_b32 s41, s5, 14
	s_lshl_b32 s100, s4, 14
	s_add_i32 s100, s100, s3
	s_mul_i32 s101, s4, 0x6000
	s_add_i32 s101, s101, s2
	s_mov_b64 vcc, 0
	v_add_u32_e32 v203, s41, v191
	s_mul_i32 s42, s5, 0x6000
	v_add_u32_e32 v206, s42, v161
	v_add_u32_e32 v207, s42, v165
	v_add_u32_e32 v208, s42, v167
	v_add_u32_e32 v209, s42, v187
	ds_read_b128 v[220:223], v206 offset:49152
	ds_read_b128 v[238:241], v207 offset:49152
	ds_read_b128 v[242:245], v208 offset:49152
.LBB0_142:
	s_waitcnt lgkmcnt(2)
	v_mfma_f32_32x32x16_bf16 v[96:111], v[220:223], v[112:115], v[0:15]
	ds_read_b128 v[246:249], v209 offset:49152
	s_waitcnt lgkmcnt(2)
	v_mfma_f32_32x32x16_bf16 v[96:111], v[238:241], v[116:119], v[96:111]
	ds_read_b128 v[220:223], v206 offset:49280
	s_cbranch_vccz .Lattn_dma_B_1
	s_ashr_i32 s57, s56, 31
	v_lshl_add_u64 v[184:185], s[56:57], 0, v[168:169]
	v_lshlrev_b64 v[184:185], 11, v[184:185]
	v_lshl_add_u64 v[184:185], v[194:195], 0, v[184:185]
	s_mov_b32 m0, s100
	s_nop 0
	global_load_lds_dwordx4 v[184:185], off

; template <int D0> __device__ __forceinline__ void pv_one(f32x16& od, unsigned vb, bf16x8 pa0, bf16x8 pa1, bf16x8 pa2, bf16x8 pa3) {
;     const s16x4 l0 = tr_read<v_rd_off(D0, 0, 0)>(vb), h0 = tr_read<v_rd_off(D0, 0, 1)>(vb), l1 = tr_read<v_rd_off(D0, 1, 0)>(vb), h1 = tr_read<v_rd_off(D0, 1, 1)>(vb);
;     const s16x4 l2 = tr_read<v_rd_off(D0, 2, 0)>(vb), h2 = tr_read<v_rd_off(D0, 2, 1)>(vb), l3 = tr_read<v_rd_off(D0, 3, 0)>(vb), h3 = tr_read<v_rd_off(D0, 3, 1)>(vb);
;     asm volatile("s_waitcnt lgkmcnt(0)" ::: "memory"); SBAR();
;     ...
;     od = __builtin_amdgcn_mfma_f32_32x32x16_bf16(pa0, PK(l0, h0), od, 0, 0, 0);
;     od = __builtin_amdgcn_mfma_f32_32x32x16_bf16(pa1, PK(l1, h1), od, 0, 0, 0);
;     od = __builtin_amdgcn_mfma_f32_32x32x16_bf16(pa2, PK(l2, h2), od, 0, 0, 0);
;     od = __builtin_amdgcn_mfma_f32_32x32x16_bf16(pa3, PK(l3, h3), od, 0, 0, 0);
;     ...
; }
; __device__ __forceinline__ void pv_d0(f32x16 (&o)[4], unsigned vb, bf16x8 pa0, bf16x8 pa1, bf16x8 pa2, bf16x8 pa3) {
;     pv_one<0>(o[0], vb, pa0, pa1, pa2, pa3); pv_one<1>(o[1], vb, pa0, pa1, pa2, pa3); pv_one<2>(o[2], vb, pa0, pa1, pa2, pa3); pv_one<3>(o[3], vb, pa0, pa1, pa2, pa3);
; }
; __device__ __forceinline__ void partialSM(f32x16& p0, f32x16& p1) {
; #pragma unroll
;     for (int r = 0; r < 16; ++r) p0[r] = __builtin_amdgcn_exp2f(p0[r]);
; }
; __device__ __forceinline__ void finishSM(f32x16& p0, f32x16& p1, float& l_reg, bf16x8& pa0, bf16x8& pa1, bf16x8& pa2, bf16x8& pa3) {
; #pragma unroll
;     for (int r = 0; r < 16; ++r) p1[r] = __builtin_amdgcn_exp2f(p1[r]);
;     float ps = 0;
; #pragma unroll
;     for (int r = 0; r < 16; ++r) ps += p0[r];
; #pragma unroll
;     for (int r = 0; r < 16; ++r) ps += p1[r];
;     l_reg += ps;
;     ...
;     PK8(p0, 0, pa0); PK8(p0, 8, pa1); PK8(p1, 0, pa2); PK8(p1, 8, pa3);
;     ...
; }
; template <int DQK>
; __device__ __forceinline__ void qkt(f32x16& p0, f32x16& p1, const LAS char* Ks, const bf16x8 (&qr)[DQK / 16], const int (&ka)[8], float nMB) {
;     constexpr int RB = DQK * 2, NA = (RB == 256) ? 8 : 4;
; #pragma unroll
;     for (int r = 0; r < 16; ++r) { p0[r] = nMB; p1[r] = nMB; }
; #pragma unroll
;     for (int d0 = 0; d0 < DQK / 16; ++d0) {
;         const LAS char* a = Ks + ka[d0 % NA] + (d0 / NA) * (NA * 32);
;         const bf16x8 b0 = *(const LAS bf16x8*)(a);
;         const bf16x8 b1 = *(const LAS bf16x8*)(a + 32 * RB);
.Lattn_dma_B_5:
	s_waitcnt lgkmcnt(2)
	v_mfma_f32_32x32x16_bf16 v[96:111], v[242:245], v[136:139], v[96:111]
	ds_read_b128 v[238:241], v207 offset:49408
	s_waitcnt lgkmcnt(2)
	v_mfma_f32_32x32x16_bf16 v[96:111], v[246:249], v[140:143], v[96:111]
	ds_read_b128 v[242:245], v208 offset:49408
	s_waitcnt lgkmcnt(2)
	v_mfma_f32_32x32x16_bf16 v[96:111], v[220:223], v[144:147], v[96:111]
	ds_read_b128 v[246:249], v209 offset:49408
	s_waitcnt lgkmcnt(2)
	v_mfma_f32_32x32x16_bf16 v[96:111], v[238:241], v[148:151], v[96:111]
	ds_read_b128 v[220:223], v206 offset:61440
	s_waitcnt lgkmcnt(2)
	v_mfma_f32_32x32x16_bf16 v[96:111], v[242:245], v[152:155], v[96:111]
	ds_read_b128 v[238:241], v207 offset:61440
	s_waitcnt lgkmcnt(2)
	v_mfma_f32_32x32x16_bf16 v[96:111], v[246:249], v[156:159], v[96:111]
	ds_read_b128 v[242:245], v208 offset:61440
	s_waitcnt lgkmcnt(2)
	v_mfma_f32_32x32x16_bf16 v[80:95], v[220:223], v[112:115], v[0:15]
	ds_read_b128 v[246:249], v209 offset:61440
	s_waitcnt lgkmcnt(2)
	v_mfma_f32_32x32x16_bf16 v[80:95], v[238:241], v[116:119], v[80:95]
	ds_read_b128 v[220:223], v206 offset:61568
	s_nop 4
	s_nop 3
	v_exp_f32_e32 v96, v96
	v_exp_f32_e32 v97, v97
	v_exp_f32_e32 v104, v104
	s_waitcnt lgkmcnt(2)
	v_mfma_f32_32x32x16_bf16 v[80:95], v[242:245], v[120:123], v[80:95]
	ds_read_b128 v[238:241], v207 offset:61568
	v_exp_f32_e32 v98, v98
	v_exp_f32_e32 v105, v105
	s_waitcnt lgkmcnt(2)
	v_mfma_f32_32x32x16_bf16 v[80:95], v[246:249], v[124:127], v[80:95]
	ds_read_b128 v[242:245], v208 offset:61568
	v_exp_f32_e32 v99, v99
	v_exp_f32_e32 v106, v106
	s_waitcnt lgkmcnt(2)
	v_mfma_f32_32x32x16_bf16 v[80:95], v[220:223], v[128:131], v[80:95]
	ds_read_b128 v[246:249], v209 offset:61568
	v_exp_f32_e32 v100, v100
	v_exp_f32_e32 v107, v107
	s_waitcnt lgkmcnt(2)
	v_mfma_f32_32x32x16_bf16 v[80:95], v[238:241], v[132:135], v[80:95]
	ds_read_b128 v[220:223], v206 offset:61696
	v_exp_f32_e32 v101, v101
	v_exp_f32_e32 v108, v108
	s_waitcnt lgkmcnt(2)
	v_mfma_f32_32x32x16_bf16 v[80:95], v[242:245], v[136:139], v[80:95]
	ds_read_b128 v[238:241], v207 offset:61696
	v_exp_f32_e32 v102, v102
	v_exp_f32_e32 v109, v109
	s_waitcnt lgkmcnt(2)
	v_mfma_f32_32x32x16_bf16 v[80:95], v[246:249], v[140:143], v[80:95]
	ds_read_b128 v[242:245], v208 offset:61696
	v_exp_f32_e32 v103, v103
	v_exp_f32_e32 v110, v110
	s_waitcnt lgkmcnt(2)
	v_mfma_f32_32x32x16_bf16 v[80:95], v[220:223], v[144:147], v[80:95]
	ds_read_b128 v[246:249], v209 offset:61696
	v_exp_f32_e32 v111, v111
	s_waitcnt lgkmcnt(2)
	v_mfma_f32_32x32x16_bf16 v[80:95], v[238:241], v[148:151], v[80:95]
	ds_read_b64_tr_b16 v[220:221], v203 offset:0
	ds_read_b64_tr_b16 v[222:223], v203 offset:2048
	v_cvt_pk_bf16_f32 v204, v96, v97
	v_cvt_pk_bf16_f32 v205, v98, v99
	v_cvt_pk_bf16_f32 v208, v104, v105
	s_waitcnt lgkmcnt(3)
	v_mfma_f32_32x32x16_bf16 v[80:95], v[242:245], v[152:155], v[80:95]
	ds_read_b64_tr_b16 v[238:239], v203 offset:512
	ds_read_b64_tr_b16 v[240:241], v203 offset:2560
	v_cvt_pk_bf16_f32 v206, v100, v101
	v_cvt_pk_bf16_f32 v209, v106, v107
	s_waitcnt lgkmcnt(4)
	v_mfma_f32_32x32x16_bf16 v[80:95], v[246:249], v[156:159], v[80:95]
	ds_read_b64_tr_b16 v[242:243], v203 offset:1024
	ds_read_b64_tr_b16 v[244:245], v203 offset:3072
	v_cvt_pk_bf16_f32 v207, v102, v103
	v_cvt_pk_bf16_f32 v210, v108, v109
	v_add_f32_e32 v96, 0, v96
	v_add_f32_e32 v96, v97, v96
	s_waitcnt lgkmcnt(4)
	v_mfma_f32_32x32x16_bf16 v[16:31], v[204:207], v[220:223], v[16:31]
	ds_read_b64_tr_b16 v[246:247], v203 offset:1536
	ds_read_b64_tr_b16 v[248:249], v203 offset:3584
	v_cvt_pk_bf16_f32 v211, v110, v111
	v_add_f32_e32 v96, v98, v96
	v_add_f32_e32 v96, v99, v96
	v_add_f32_e32 v96, v100, v96
	s_waitcnt lgkmcnt(4)
	v_mfma_f32_32x32x16_bf16 v[32:47], v[204:207], v[238:241], v[32:47]
	ds_read_b64_tr_b16 v[220:221], v203 offset:4096
	ds_read_b64_tr_b16 v[222:223], v203 offset:6144
	v_exp_f32_e32 v80, v80
	v_exp_f32_e32 v81, v81
	v_exp_f32_e32 v88, v88
	v_exp_f32_e32 v89, v89
	v_add_f32_e32 v96, v101, v96
	v_add_f32_e32 v96, v102, v96
	s_waitcnt lgkmcnt(4)
	v_mfma_f32_32x32x16_bf16 v[48:63], v[204:207], v[242:245], v[48:63]
	ds_read_b64_tr_b16 v[238:239], v203 offset:4608
	ds_read_b64_tr_b16 v[240:241], v203 offset:6656
	v_exp_f32_e32 v82, v82
	v_exp_f32_e32 v83, v83
	v_exp_f32_e32 v90, v90
	v_add_f32_e32 v96, v103, v96
	v_add_f32_e32 v96, v104, v96
	s_waitcnt lgkmcnt(4)
; #define SBAR() __builtin_amdgcn_sched_barrier(0)
; #define VMW0() asm volatile("s_waitcnt vmcnt(0)" ::: "memory")
; template <int D0> __device__ __forceinline__ void pv_one(f32x16& od, unsigned vb, bf16x8 pa0, bf16x8 pa1, bf16x8 pa2, bf16x8 pa3) {
;     const s16x4 l0 = tr_read<v_rd_off(D0, 0, 0)>(vb), h0 = tr_read<v_rd_off(D0, 0, 1)>(vb), l1 = tr_read<v_rd_off(D0, 1, 0)>(vb), h1 = tr_read<v_rd_off(D0, 1, 1)>(vb);
;     const s16x4 l2 = tr_read<v_rd_off(D0, 2, 0)>(vb), h2 = tr_read<v_rd_off(D0, 2, 1)>(vb), l3 = tr_read<v_rd_off(D0, 3, 0)>(vb), h3 = tr_read<v_rd_off(D0, 3, 1)>(vb);
;     asm volatile("s_waitcnt lgkmcnt(0)" ::: "memory"); SBAR();
;     ...
;     od = __builtin_amdgcn_mfma_f32_32x32x16_bf16(pa0, PK(l0, h0), od, 0, 0, 0);
;     od = __builtin_amdgcn_mfma_f32_32x32x16_bf16(pa1, PK(l1, h1), od, 0, 0, 0);
;     od = __builtin_amdgcn_mfma_f32_32x32x16_bf16(pa2, PK(l2, h2), od, 0, 0, 0);
;     od = __builtin_amdgcn_mfma_f32_32x32x16_bf16(pa3, PK(l3, h3), od, 0, 0, 0);
;     ...
; }
; __device__ __forceinline__ void pv_d0(f32x16 (&o)[4], unsigned vb, bf16x8 pa0, bf16x8 pa1, bf16x8 pa2, bf16x8 pa3) {
;     pv_one<0>(o[0], vb, pa0, pa1, pa2, pa3); pv_one<1>(o[1], vb, pa0, pa1, pa2, pa3); pv_one<2>(o[2], vb, pa0, pa1, pa2, pa3); pv_one<3>(o[3], vb, pa0, pa1, pa2, pa3);
; }
; template <int DQK, bool DOUBLE> ...
;     ...
;         for (int j = 0; j < NT; ++j) {
;             SBAR(); qkt<DQK>(p0, p1, K_lds + bc * K_STRIDE, qr, ka, nMB);
;             partialSM(p0, p1); finishSM(p0, p1, l_reg, pa0, pa1, pa2, pa3); SBAR();
;             pv_d0(o, vb0 + bc * V_BYTES, pa0, pa1, pa2, pa3);
;             if (j + 1 < NT) { VMW0(); __syncthreads(); if (j + 3 < NT) DMA(j + 3, bc); }
;             { const int _t = bc; bc = bn; bn = bf; bf = _t; }
;         }
	v_mfma_f32_32x32x16_bf16 v[64:79], v[204:207], v[246:249], v[64:79]
	ds_read_b64_tr_b16 v[242:243], v203 offset:5120
	ds_read_b64_tr_b16 v[244:245], v203 offset:7168
	v_exp_f32_e32 v84, v84
	v_exp_f32_e32 v85, v85
	v_exp_f32_e32 v91, v91
	v_add_f32_e32 v96, v105, v96
	v_add_f32_e32 v96, v106, v96
	s_waitcnt lgkmcnt(4)
	v_mfma_f32_32x32x16_bf16 v[16:31], v[208:211], v[220:223], v[16:31]
	ds_read_b64_tr_b16 v[246:247], v203 offset:5632
	ds_read_b64_tr_b16 v[248:249], v203 offset:7680
	v_exp_f32_e32 v86, v86
	v_exp_f32_e32 v87, v87
	v_exp_f32_e32 v92, v92
	v_add_f32_e32 v96, v107, v96
	v_add_f32_e32 v96, v108, v96
	s_waitcnt lgkmcnt(4)
	v_mfma_f32_32x32x16_bf16 v[32:47], v[208:211], v[238:241], v[32:47]
	ds_read_b64_tr_b16 v[220:221], v203 offset:8192
	ds_read_b64_tr_b16 v[222:223], v203 offset:10240
	v_cvt_pk_bf16_f32 v212, v80, v81
	v_cvt_pk_bf16_f32 v213, v82, v83
	v_exp_f32_e32 v93, v93
	v_add_f32_e32 v96, v109, v96
	v_add_f32_e32 v96, v110, v96
	s_waitcnt lgkmcnt(4)
	v_mfma_f32_32x32x16_bf16 v[48:63], v[208:211], v[242:245], v[48:63]
	ds_read_b64_tr_b16 v[238:239], v203 offset:8704
	ds_read_b64_tr_b16 v[240:241], v203 offset:10752
	v_cvt_pk_bf16_f32 v214, v84, v85
	v_exp_f32_e32 v94, v94
	v_add_f32_e32 v96, v111, v96
	s_waitcnt lgkmcnt(4)
	v_mfma_f32_32x32x16_bf16 v[64:79], v[208:211], v[246:249], v[64:79]
	ds_read_b64_tr_b16 v[242:243], v203 offset:9216
	ds_read_b64_tr_b16 v[244:245], v203 offset:11264
	v_cvt_pk_bf16_f32 v215, v86, v87
	v_exp_f32_e32 v95, v95
	v_add_f32_e32 v80, v80, v96
	v_add_f32_e32 v80, v81, v80
	s_waitcnt lgkmcnt(4)
	v_mfma_f32_32x32x16_bf16 v[16:31], v[212:215], v[220:223], v[16:31]
	ds_read_b64_tr_b16 v[246:247], v203 offset:9728
	ds_read_b64_tr_b16 v[248:249], v203 offset:11776
	v_cvt_pk_bf16_f32 v216, v88, v89
	v_add_f32_e32 v80, v82, v80
	v_add_f32_e32 v80, v83, v80
	v_add_f32_e32 v80, v84, v80
	s_waitcnt lgkmcnt(4)
	v_mfma_f32_32x32x16_bf16 v[32:47], v[212:215], v[238:241], v[32:47]
	ds_read_b64_tr_b16 v[220:221], v203 offset:12288
	ds_read_b64_tr_b16 v[222:223], v203 offset:14336
	v_cvt_pk_bf16_f32 v217, v90, v91
	v_add_f32_e32 v80, v85, v80
	v_add_f32_e32 v80, v86, v80
	v_add_f32_e32 v80, v87, v80
	s_waitcnt lgkmcnt(4)
	v_mfma_f32_32x32x16_bf16 v[48:63], v[212:215], v[242:245], v[48:63]
	ds_read_b64_tr_b16 v[238:239], v203 offset:12800
	ds_read_b64_tr_b16 v[240:241], v203 offset:14848
	v_cvt_pk_bf16_f32 v218, v92, v93
	s_waitcnt lgkmcnt(4)
	v_mfma_f32_32x32x16_bf16 v[64:79], v[212:215], v[246:249], v[64:79]
	ds_read_b64_tr_b16 v[242:243], v203 offset:13312
	ds_read_b64_tr_b16 v[244:245], v203 offset:15360
	v_cvt_pk_bf16_f32 v219, v94, v95
	v_add_f32_e32 v80, v88, v80
	v_add_f32_e32 v80, v89, v80
	v_add_f32_e32 v80, v90, v80
	s_waitcnt lgkmcnt(4)
	v_mfma_f32_32x32x16_bf16 v[16:31], v[216:219], v[220:223], v[16:31]
	ds_read_b64_tr_b16 v[246:247], v203 offset:13824
	ds_read_b64_tr_b16 v[248:249], v203 offset:15872
	s_mul_i32 s42, s33, 0x6000
	v_add_u32_e32 v206, s42, v161
	v_add_u32_e32 v207, s42, v165
	v_add_u32_e32 v208, s42, v167
	v_add_u32_e32 v209, s42, v187
	v_add_f32_e32 v80, v91, v80
	v_add_f32_e32 v80, v92, v80
	v_add_f32_e32 v80, v93, v80
	v_add_f32_e32 v80, v94, v80
	s_waitcnt lgkmcnt(4)
	v_mfma_f32_32x32x16_bf16 v[32:47], v[216:219], v[238:241], v[32:47]
	ds_read_b128 v[220:223], v206 offset:49152
	v_add_f32_e32 v80, v95, v80
	s_waitcnt lgkmcnt(3)
	v_mfma_f32_32x32x16_bf16 v[48:63], v[216:219], v[242:245], v[48:63]
	ds_read_b128 v[238:241], v207 offset:49152
	s_waitcnt lgkmcnt(2)
	v_mfma_f32_32x32x16_bf16 v[64:79], v[216:219], v[246:249], v[64:79]
	ds_read_b128 v[242:245], v208 offset:49152
	s_mov_b32 s35, s5
	s_mov_b32 s5, s33
	s_mov_b32 s33, s4
	s_mov_b32 s4, s35
	s_mul_i32 s35, s5, 0x6000
	s_add_i32 s35, s35, 0
	s_lshl_b32 s41, s5, 14
	s_lshl_b32 s100, s4, 14
	s_add_i32 s100, s100, s3
	s_mul_i32 s101, s4, 0x6000
	s_add_i32 s101, s101, s2
	s_add_i32 s21, s21, 1
	s_add_i32 s42, s21, 3
	s_cmp_lt_i32 s42, s71
	s_cselect_b64 vcc, -1, 0
	v_add_u32_e32 v203, s41, v191
	v_add_f32_e32 v202, v202, v80
	s_cmp_lg_u32 s20, s21
	s_cbranch_scc0 .LBB0_147
	s_waitcnt vmcnt(0)
	s_barrier
	s_branch .LBB0_142

; #define LAS __attribute__((address_space(3)))
; __device__ __forceinline__ int v_rd_base(int lane) { return ((lane & 3) << 3) | (((lane >> 2) & 3) << 6) | (((lane >> 4) & 1) << 5) | (((lane >> 5) & 1) << 8); }
; #define VMW0() asm volatile("s_waitcnt vmcnt(0)" ::: "memory")
; template <int DQK, bool DOUBLE> ...
;     ...
;     const int wid = __builtin_amdgcn_readfirstlane(tid >> 6), lane = tid & 63, r32 = lane & 31, hi = lane >> 5;
;     LAS char* V_lds = lds; LAS char* K_lds = lds + K_OFF;
;     bf16x8 qr[DQK / 16];
;     { const bf16_t* Qw = Q + (size_t)(wid * 32 + r32) * ldq + hi * 8;
; #pragma unroll
;       for (int d0 = 0; d0 < DQK / 16; ++d0) qr[d0] = *(const bf16x8*)(Qw + d0 * 16); }
; #pragma unroll
;     for (int d = 0; d < 4; ++d) o[d] = f32x16{};
;     l_reg = 0.f;
;     int vrow[2], vcol[2], krow[NLD], kcol[NLD];
; #pragma unroll
;     for (int i = 0; i < 2; ++i) { const int q = tid + 512 * i, sub = q >> 5, within = q & 31, kk = (sub >> 2) * 8 + (within >> 2);
;         vrow[i] = kk; vcol[i] = (sub & 3) * 32 + (within & 3) * 8; }
; #pragma unroll
;     for (int i = 0; i < NLD; ++i) { const int q = tid + 512 * i, row = q / NCH, chp = q % NCH; const int x = (RB == 256) ? (row & 15) : ((row >> 1) & 7);
;         krow[i] = row; kcol[i] = (chp ^ x) * 8; }
;     const unsigned vb0 = (unsigned)(uintptr_t)V_lds + v_rd_base(lane);
;     int ka[8];
; #pragma unroll
;     for (int q = 0; q < 8; ++q) ka[q] = kswz<RB>(r32, q * 32 + hi * 16);
;     ...
;     bf16x8 pa0, pa1, pa2, pa3;
;     __syncthreads();
;     DMA(0, 0); DMA(1, 1); VMW0(); __syncthreads();
; __device__ __forceinline__ void attn_item(const AttnBufs& T, int type, int b, int h, int qrow0, int NT, LAS char* lds, int tid_) {
;     ...
;         f32x16 o[4]; float l_reg; float rli[16];
;         att::attn_pass<64, ATT_DBL>(T.QC + (size_t)qrow0 * 1024 + h * 128, 1024, T.KC + h * 128, 1024, T.VC + h * 128, 1024, rowc, rowl, NT,
;                            T.lamv[3], o, l_reg, lds, tid);
.LBB0_153:
	v_lshlrev_b32_e32 v144, 4, v176
	v_and_b32_e32 v4, 0x60, v164
	v_lshlrev_b32_e32 v5, 3, v164
	v_add_u32_e32 v194, 0x200, v164
	v_lshlrev_b32_e32 v6, 4, v182
	s_andn2_b64 vcc, exec, s[50:51]
	v_ashrrev_i32_e32 v195, 4, v164
	v_ashrrev_i32_e32 v165, 31, v164
	v_lshlrev_b32_e32 v174, 3, v182
	v_lshrrev_b32_e32 v196, 2, v164
	v_and_or_b32 v193, v5, 24, v4
	v_ashrrev_i32_e32 v197, 4, v194
	v_or_b32_e32 v187, 32, v144
	v_or_b32_e32 v191, 64, v144
	v_or_b32_e32 v192, 0x60, v144
	v_lshlrev_b32_e32 v175, 1, v182
	v_and_b32_e32 v173, 0xc0, v6
	s_cbranch_vccnz .LBB0_171
	s_lshl_b64 s[2:3], s[30:31], 11
	v_readlane_b32 s4, v251, 40
	v_readlane_b32 s5, v251, 41
	s_add_u32 s4, s4, s2
	s_addc_u32 s5, s5, s3
	s_lshl_b32 s48, s72, 7
	s_ashr_i32 s49, s48, 31
	s_lshl_b64 s[2:3], s[48:49], 1
	s_add_u32 s50, s4, s2
	s_addc_u32 s51, s5, s3
	v_readlane_b32 s4, v251, 42
	v_readlane_b32 s5, v251, 43
	s_add_u32 s60, s4, s2
	s_addc_u32 s61, s5, s3
	v_readlane_b32 s4, v251, 44
	v_readlane_b32 s5, v251, 45
	s_add_u32 s56, s4, s2
	v_readfirstlane_b32 s2, v164
	s_addc_u32 s57, s5, s3
	s_ashr_i32 s2, s2, 6
	v_lshl_or_b32 v2, s2, 5, v181
	v_ashrrev_i32_e32 v3, 31, v2
	v_lshlrev_b64 v[2:3], 11, v[2:3]
	v_lshrrev_b32_e32 v1, 29, v165
	v_lshl_add_u64 v[2:3], s[50:51], 0, v[2:3]
	v_mov_b32_e32 v145, v177
	v_add_u32_e32 v1, v164, v1
	v_lshl_add_u64 v[2:3], v[2:3], 0, v[144:145]
	v_ashrrev_i32_e32 v132, 3, v1
	v_and_b32_e32 v1, 0x1ffffff8, v1
	global_load_dword v0, v177, s[14:15] offset:12
	global_load_dwordx4 v[112:115], v[2:3], off
	global_load_dwordx4 v[116:119], v[2:3], off offset:32
	global_load_dwordx4 v[120:123], v[2:3], off offset:64
	global_load_dwordx4 v[124:127], v[2:3], off offset:96
	v_sub_u32_e32 v1, v164, v1
	v_lshrrev_b32_e32 v2, 1, v132
	v_bitop3_b32 v1, v2, v1, 7 bitop3:0x6c
	v_bfi_b32 v128, -8, v195, v196
	v_lshlrev_b32_e32 v2, 3, v1
	s_add_i32 s42, s45, 0x4040
	v_ashrrev_i32_e32 v129, 31, v128
	v_ashrrev_i32_e32 v3, 31, v2
	s_ashr_i32 s43, s42, 31
	v_lshlrev_b64 v[16:17], 1, v[2:3]
	v_lshl_add_u64 v[2:3], v[128:129], 0, s[42:43]
	v_bfi_b32 v130, -8, v197, v196
	v_lshlrev_b64 v[2:3], 11, v[2:3]
	s_ashr_i32 s47, s46, 31
	v_lshlrev_b32_e32 v80, 1, v193
	v_mov_b32_e32 v81, v177
	s_waitcnt lgkmcnt(0)
	v_ashrrev_i32_e32 v131, 31, v130
	v_lshl_add_u64 v[2:3], s[56:57], 0, v[2:3]
	v_lshl_add_u64 v[4:5], v[128:129], 0, s[46:47]
	v_lshl_add_u64 v[148:149], v[2:3], 0, v[80:81]
	v_lshl_add_u64 v[2:3], v[130:131], 0, s[42:43]
	v_lshlrev_b64 v[4:5], 11, v[4:5]
	v_lshlrev_b64 v[2:3], 11, v[2:3]
	v_lshl_add_u64 v[4:5], s[56:57], 0, v[4:5]
	v_ashrrev_i32_e32 v133, 31, v132
	v_lshl_add_u64 v[2:3], s[56:57], 0, v[2:3]
	v_lshl_add_u64 v[140:141], v[4:5], 0, v[80:81]
	v_lshl_add_u64 v[4:5], v[130:131], 0, s[46:47]
	v_lshl_add_u64 v[150:151], v[2:3], 0, v[80:81]
	v_lshl_add_u64 v[2:3], v[132:133], 0, s[42:43]
	v_lshlrev_b64 v[4:5], 11, v[4:5]
	v_lshlrev_b64 v[2:3], 11, v[2:3]
	s_add_i32 s42, s45, 0x4080
	s_lshl_b32 s3, s2, 10
	v_lshl_add_u64 v[4:5], s[56:57], 0, v[4:5]
	v_lshl_add_u64 v[2:3], s[60:61], 0, v[2:3]
	s_ashr_i32 s43, s42, 31
	s_add_i32 s4, s3, 0
	v_lshl_add_u64 v[142:143], v[4:5], 0, v[80:81]
	v_lshl_add_u64 v[4:5], v[132:133], 0, s[46:47]
	v_lshl_add_u64 v[152:153], v[2:3], 0, v[16:17]
	v_lshl_add_u64 v[2:3], v[128:129], 0, s[42:43]
	s_mov_b32 m0, s4
	s_add_i32 s2, s4, 0x2000
	v_lshlrev_b64 v[4:5], 11, v[4:5]
	v_lshlrev_b64 v[2:3], 11, v[2:3]
	s_barrier
	global_load_lds_dwordx4 v[140:141], off
	s_mov_b32 m0, s2
	v_lshl_add_u64 v[4:5], s[60:61], 0, v[4:5]
	s_add_i32 s21, s4, 0xc000
	v_lshl_add_u64 v[2:3], s[56:57], 0, v[2:3]
	global_load_lds_dwordx4 v[142:143], off
	v_lshl_add_u64 v[146:147], v[4:5], 0, v[16:17]
	s_mov_b32 m0, s21
	v_lshl_add_u64 v[154:155], v[2:3], 0, v[80:81]
	v_lshl_add_u64 v[2:3], v[130:131], 0, s[42:43]
	global_load_lds_dwordx4 v[146:147], off
	s_add_i32 m0, s4, 0x4000
	v_lshlrev_b64 v[2:3], 11, v[2:3]
	global_load_lds_dwordx4 v[148:149], off
	s_add_i32 m0, s4, 0x6000
	v_lshl_add_u64 v[2:3], s[56:57], 0, v[2:3]
	global_load_lds_dwordx4 v[150:151], off
	s_add_i32 m0, s4, 0x12000
	v_lshl_add_u64 v[156:157], v[2:3], 0, v[80:81]
	v_lshl_add_u64 v[2:3], v[132:133], 0, s[42:43]
	global_load_lds_dwordx4 v[152:153], off
	s_add_i32 m0, s4, 0x8000
	v_lshlrev_b64 v[2:3], 11, v[2:3]
	s_waitcnt vmcnt(0)
	s_waitcnt vmcnt(0) lgkmcnt(0)
	s_barrier
; #define LAS __attribute__((address_space(3)))
; #define SBAR() __builtin_amdgcn_sched_barrier(0)
; #define PK8(P, BASE, OUT) do { u32x4 w = {cvt_pk_bf16(P[BASE + 0], P[BASE + 1]), cvt_pk_bf16(P[BASE + 2], P[BASE + 3]), cvt_pk_bf16(P[BASE + 4], P[BASE + 5]), cvt_pk_bf16(P[BASE + 6], P[BASE + 7])}; \
;     OUT = *reinterpret_cast<bf16x8*>(&w); } while (0)
; __device__ __forceinline__ void partialSM(f32x16& p0, f32x16& p1) {
; #pragma unroll
;     for (int r = 0; r < 16; ++r) p0[r] = __builtin_amdgcn_exp2f(p0[r]);
; }
; __device__ __forceinline__ void finishSM(f32x16& p0, f32x16& p1, float& l_reg, bf16x8& pa0, bf16x8& pa1, bf16x8& pa2, bf16x8& pa3) {
; #pragma unroll
;     for (int r = 0; r < 16; ++r) p1[r] = __builtin_amdgcn_exp2f(p1[r]);
;     float ps = 0;
; #pragma unroll
;     for (int r = 0; r < 16; ++r) ps += p0[r];
; #pragma unroll
;     for (int r = 0; r < 16; ++r) ps += p1[r];
;     l_reg += ps;
;     ...
;     PK8(p0, 0, pa0); PK8(p0, 8, pa1); PK8(p1, 0, pa2); PK8(p1, 8, pa3);
;     ...
; }
; template <int DQK>
; __device__ __forceinline__ void qkt(f32x16& p0, f32x16& p1, const LAS char* Ks, const bf16x8 (&qr)[DQK / 16], const int (&ka)[8], float nMB) {
;     constexpr int RB = DQK * 2, NA = (RB == 256) ? 8 : 4;
; #pragma unroll
;     for (int r = 0; r < 16; ++r) { p0[r] = nMB; p1[r] = nMB; }
; #pragma unroll
;     for (int d0 = 0; d0 < DQK / 16; ++d0) {
;         const LAS char* a = Ks + ka[d0 % NA] + (d0 / NA) * (NA * 32);
;         const bf16x8 b0 = *(const LAS bf16x8*)(a);
;         const bf16x8 b1 = *(const LAS bf16x8*)(a + 32 * RB);
;         p0 = __builtin_amdgcn_mfma_f32_32x32x16_bf16(b0, qr[d0], p0, 0, 0, 0);
;         p1 = __builtin_amdgcn_mfma_f32_32x32x16_bf16(b1, qr[d0], p1, 0, 0, 0); }
; }
; template <int DQK, bool DOUBLE> ...
;     ...
;         DMA(2, 2);
;         int bc = 0, bn = 1, bf = 2;
;         for (int j = 0; j < NT; ++j) {
;             SBAR(); qkt<DQK>(p0, p1, K_lds + bc * K_STRIDE, qr, ka, nMB);
;             partialSM(p0, p1); finishSM(p0, p1, l_reg, pa0, pa1, pa2, pa3); SBAR();
	global_load_lds_dwordx4 v[154:155], off
	s_add_i32 m0, s4, 0xa000
	v_lshl_add_u64 v[2:3], s[60:61], 0, v[2:3]
	global_load_lds_dwordx4 v[156:157], off
	v_lshl_add_u64 v[158:159], v[2:3], 0, v[16:17]
	s_add_i32 m0, s4, 0x18000
	v_lshlrev_b32_e32 v2, 3, v181
	global_load_lds_dwordx4 v[158:159], off
	v_lshlrev_b32_e32 v1, 7, v181
	v_and_b32_e32 v2, 0x70, v2
	v_bitop3_b32 v145, v144, v1, v2 bitop3:0xde
	v_bitop3_b32 v161, v187, v1, v2 bitop3:0xde
	v_bitop3_b32 v198, v191, v1, v2 bitop3:0xde
	v_bitop3_b32 v199, v192, v1, v2 bitop3:0xde
	v_and_b32_e32 v1, 32, v175
	s_movk_i32 s33, 0x118
	v_and_or_b32 v18, v174, s33, v1
	s_mov_b32 s5, 1
	v_lshlrev_b32_e32 v172, 3, v176
	s_mov_b32 s20, 2
	v_mov_b32_e32 v1, v0
	v_mov_b32_e32 v2, v0
	v_mov_b32_e32 v3, v0
	v_mov_b32_e32 v4, v0
	v_mov_b32_e32 v5, v0
	v_mov_b32_e32 v6, v0
	v_mov_b32_e32 v7, v0
	v_mov_b32_e32 v8, v0
	v_mov_b32_e32 v9, v0
	v_mov_b32_e32 v10, v0
	v_mov_b32_e32 v11, v0
	v_mov_b32_e32 v12, v0
	v_mov_b32_e32 v13, v0
	v_mov_b32_e32 v14, v0
	v_mov_b32_e32 v15, v0
	v_add3_u32 v200, v173, 0, v18
	v_lshl_add_u64 v[134:135], s[60:61], 0, v[16:17]
	s_add_i32 s58, s45, 0x40c0
	v_add_u32_e32 v202, 0, v145
	ds_read_b128 v[16:19], v202 offset:49152
	ds_read_b128 v[48:51], v202 offset:53248
	v_add_u32_e32 v203, 0, v161
	v_add_u32_e32 v204, 0, v198
	v_add_u32_e32 v205, 0, v199
	s_waitcnt lgkmcnt(0)
	v_mfma_f32_32x32x16_bf16 v[32:47], v[16:19], v[112:115], v[0:15]
	v_mfma_f32_32x32x16_bf16 v[16:31], v[48:51], v[112:115], v[0:15]
	ds_read_b128 v[48:51], v203 offset:49152
	ds_read_b128 v[52:55], v203 offset:53248
	s_waitcnt lgkmcnt(0)
	v_mfma_f32_32x32x16_bf16 v[32:47], v[48:51], v[116:119], v[32:47]
	v_mfma_f32_32x32x16_bf16 v[16:31], v[52:55], v[116:119], v[16:31]
	ds_read_b128 v[48:51], v204 offset:49152
	ds_read_b128 v[52:55], v204 offset:53248
	s_waitcnt lgkmcnt(0)
	v_mfma_f32_32x32x16_bf16 v[32:47], v[48:51], v[120:123], v[32:47]
	v_mfma_f32_32x32x16_bf16 v[16:31], v[52:55], v[120:123], v[16:31]
	ds_read_b128 v[48:51], v205 offset:49152
	ds_read_b128 v[52:55], v205 offset:53248
	s_waitcnt lgkmcnt(0)
	v_mfma_f32_32x32x16_bf16 v[32:47], v[48:51], v[124:127], v[32:47]
	v_mfma_f32_32x32x16_bf16 v[16:31], v[52:55], v[124:127], v[16:31]
	s_nop 10
	v_exp_f32_e32 v32, v32
	v_exp_f32_e32 v33, v33
	v_exp_f32_e32 v34, v34
	v_exp_f32_e32 v35, v35
	v_exp_f32_e32 v36, v36
	v_add_f32_e32 v48, 0, v32
	v_exp_f32_e32 v37, v37
	v_add_f32_e32 v48, v33, v48
	v_exp_f32_e32 v38, v38
	v_add_f32_e32 v48, v34, v48
	v_exp_f32_e32 v39, v39
	v_add_f32_e32 v48, v35, v48
	v_exp_f32_e32 v40, v40
	v_add_f32_e32 v48, v36, v48
	v_exp_f32_e32 v41, v41
	v_add_f32_e32 v48, v37, v48
	v_exp_f32_e32 v42, v42
	v_add_f32_e32 v48, v38, v48
	v_exp_f32_e32 v43, v43
	v_add_f32_e32 v48, v39, v48
	v_exp_f32_e32 v44, v44
	v_add_f32_e32 v48, v40, v48
	v_exp_f32_e32 v45, v45
	v_add_f32_e32 v48, v41, v48
	v_exp_f32_e32 v46, v46
	v_add_f32_e32 v48, v42, v48
	v_exp_f32_e32 v47, v47
	v_add_f32_e32 v48, v43, v48
	v_exp_f32_e32 v16, v16
	v_add_f32_e32 v48, v44, v48
	v_exp_f32_e32 v17, v17
	v_add_f32_e32 v48, v45, v48
	v_exp_f32_e32 v18, v18
	v_add_f32_e32 v48, v46, v48
	v_exp_f32_e32 v19, v19
	v_add_f32_e32 v48, v47, v48
	v_exp_f32_e32 v20, v20
	v_add_f32_e32 v48, v16, v48
	v_exp_f32_e32 v21, v21
	v_add_f32_e32 v48, v17, v48
	v_exp_f32_e32 v22, v22
	v_add_f32_e32 v48, v18, v48
	v_exp_f32_e32 v23, v23
	v_add_f32_e32 v48, v19, v48
	v_exp_f32_e32 v24, v24
	v_add_f32_e32 v48, v20, v48
	v_exp_f32_e32 v25, v25
	v_add_f32_e32 v48, v21, v48
	v_exp_f32_e32 v26, v26
	v_add_f32_e32 v48, v22, v48
	v_exp_f32_e32 v27, v27
	v_add_f32_e32 v48, v23, v48
	v_exp_f32_e32 v28, v28
	v_add_f32_e32 v48, v24, v48
	v_exp_f32_e32 v29, v29
	v_add_f32_e32 v48, v25, v48
	v_exp_f32_e32 v30, v30
	v_add_f32_e32 v48, v26, v48
	v_exp_f32_e32 v31, v31
	v_add_f32_e32 v48, v27, v48
	v_add_f32_e32 v48, v28, v48
	v_add_f32_e32 v48, v29, v48
	v_add_f32_e32 v48, v30, v48
	v_add_f32_e32 v48, v31, v48
	v_add_f32_e32 v136, 0, v48
	v_cvt_pk_bf16_f32 v64, v32, v33
	v_cvt_pk_bf16_f32 v65, v34, v35
	v_cvt_pk_bf16_f32 v66, v36, v37
	v_cvt_pk_bf16_f32 v67, v38, v39
	v_cvt_pk_bf16_f32 v82, v40, v41
	v_cvt_pk_bf16_f32 v83, v42, v43
	v_cvt_pk_bf16_f32 v84, v44, v45
	v_cvt_pk_bf16_f32 v85, v46, v47
	v_cvt_pk_bf16_f32 v86, v16, v17
	v_cvt_pk_bf16_f32 v87, v18, v19
	v_cvt_pk_bf16_f32 v88, v20, v21
	v_cvt_pk_bf16_f32 v89, v22, v23
	v_cvt_pk_bf16_f32 v90, v24, v25
	v_cvt_pk_bf16_f32 v91, v26, v27
	v_cvt_pk_bf16_f32 v92, v28, v29
	v_cvt_pk_bf16_f32 v93, v30, v31
	ds_read_b64_tr_b16 v[16:17], v200 offset:0
	ds_read_b64_tr_b16 v[18:19], v200 offset:0x800
	ds_read_b64_tr_b16 v[32:33], v200 offset:0x1000
	ds_read_b64_tr_b16 v[34:35], v200 offset:0x1800
	ds_read_b64_tr_b16 v[36:37], v200 offset:0x2000
	ds_read_b64_tr_b16 v[38:39], v200 offset:0x2800
	ds_read_b64_tr_b16 v[40:41], v200 offset:0x3000
	ds_read_b64_tr_b16 v[42:43], v200 offset:0x3800
	s_waitcnt lgkmcnt(0)
; #define SBAR() __builtin_amdgcn_sched_barrier(0)
; #define VMW0() asm volatile("s_waitcnt vmcnt(0)" ::: "memory")
; template <int D0> __device__ __forceinline__ void pv_one(f32x16& od, unsigned vb, bf16x8 pa0, bf16x8 pa1, bf16x8 pa2, bf16x8 pa3) {
;     const s16x4 l0 = tr_read<v_rd_off(D0, 0, 0)>(vb), h0 = tr_read<v_rd_off(D0, 0, 1)>(vb), l1 = tr_read<v_rd_off(D0, 1, 0)>(vb), h1 = tr_read<v_rd_off(D0, 1, 1)>(vb);
;     const s16x4 l2 = tr_read<v_rd_off(D0, 2, 0)>(vb), h2 = tr_read<v_rd_off(D0, 2, 1)>(vb), l3 = tr_read<v_rd_off(D0, 3, 0)>(vb), h3 = tr_read<v_rd_off(D0, 3, 1)>(vb);
;     asm volatile("s_waitcnt lgkmcnt(0)" ::: "memory"); SBAR();
;     ...
;     od = __builtin_amdgcn_mfma_f32_32x32x16_bf16(pa0, PK(l0, h0), od, 0, 0, 0);
;     od = __builtin_amdgcn_mfma_f32_32x32x16_bf16(pa1, PK(l1, h1), od, 0, 0, 0);
;     od = __builtin_amdgcn_mfma_f32_32x32x16_bf16(pa2, PK(l2, h2), od, 0, 0, 0);
;     od = __builtin_amdgcn_mfma_f32_32x32x16_bf16(pa3, PK(l3, h3), od, 0, 0, 0);
;     ...
; }
; __device__ __forceinline__ void pv_d0(f32x16 (&o)[4], unsigned vb, bf16x8 pa0, bf16x8 pa1, bf16x8 pa2, bf16x8 pa3) {
;     pv_one<0>(o[0], vb, pa0, pa1, pa2, pa3); pv_one<1>(o[1], vb, pa0, pa1, pa2, pa3); pv_one<2>(o[2], vb, pa0, pa1, pa2, pa3); pv_one<3>(o[3], vb, pa0, pa1, pa2, pa3);
; }
; template <int DQK, bool DOUBLE> ...
;     ...
;         for (int j = 0; j < NT; ++j) {
;             SBAR(); qkt<DQK>(p0, p1, K_lds + bc * K_STRIDE, qr, ka, nMB);
;             partialSM(p0, p1); finishSM(p0, p1, l_reg, pa0, pa1, pa2, pa3); SBAR();
;             pv_d0(o, vb0 + bc * V_BYTES, pa0, pa1, pa2, pa3);
;             if (j + 1 < NT) { VMW0(); __syncthreads(); if (j + 3 < NT) DMA(j + 3, bc); }
;             { const int _t = bc; bc = bn; bn = bf; bf = _t; }
	s_nop 0
	v_mfma_f32_32x32x16_bf16 v[16:31], v[64:67], v[16:19], 0
	v_mfma_f32_32x32x16_bf16 v[16:31], v[82:85], v[32:35], v[16:31]
	ds_read_b64_tr_b16 v[32:33], v200 offset:0x200
	ds_read_b64_tr_b16 v[34:35], v200 offset:0xa00
	ds_read_b64_tr_b16 v[48:49], v200 offset:0x1200
	ds_read_b64_tr_b16 v[50:51], v200 offset:0x1a00
	ds_read_b64_tr_b16 v[52:53], v200 offset:0x2200
	ds_read_b64_tr_b16 v[54:55], v200 offset:0x2a00
	ds_read_b64_tr_b16 v[56:57], v200 offset:0x3200
	v_mfma_f32_32x32x16_bf16 v[16:31], v[86:89], v[36:39], v[16:31]
	ds_read_b64_tr_b16 v[58:59], v200 offset:0x3a00
	s_waitcnt lgkmcnt(0)
	v_mfma_f32_32x32x16_bf16 v[16:31], v[90:93], v[40:43], v[16:31]
	v_mfma_f32_32x32x16_bf16 v[32:47], v[64:67], v[32:35], 0
	v_mfma_f32_32x32x16_bf16 v[32:47], v[82:85], v[48:51], v[32:47]
	ds_read_b64_tr_b16 v[48:49], v200 offset:0x400
	ds_read_b64_tr_b16 v[50:51], v200 offset:0xc00
	ds_read_b64_tr_b16 v[68:69], v200 offset:0x1400
	ds_read_b64_tr_b16 v[70:71], v200 offset:0x1c00
	ds_read_b64_tr_b16 v[72:73], v200 offset:0x2400
	ds_read_b64_tr_b16 v[74:75], v200 offset:0x2c00
	ds_read_b64_tr_b16 v[76:77], v200 offset:0x3400
	v_mfma_f32_32x32x16_bf16 v[32:47], v[86:89], v[52:55], v[32:47]
	ds_read_b64_tr_b16 v[78:79], v200 offset:0x3c00
	s_waitcnt lgkmcnt(0)
	v_mfma_f32_32x32x16_bf16 v[32:47], v[90:93], v[56:59], v[32:47]
	v_mfma_f32_32x32x16_bf16 v[48:63], v[64:67], v[48:51], 0
	v_mfma_f32_32x32x16_bf16 v[48:63], v[82:85], v[68:71], v[48:63]
	ds_read_b64_tr_b16 v[68:69], v200 offset:0x600
	ds_read_b64_tr_b16 v[70:71], v200 offset:0xe00
	ds_read_b64_tr_b16 v[94:95], v200 offset:0x1600
	ds_read_b64_tr_b16 v[96:97], v200 offset:0x1e00
	ds_read_b64_tr_b16 v[98:99], v200 offset:0x2600
	ds_read_b64_tr_b16 v[100:101], v200 offset:0x2e00
	ds_read_b64_tr_b16 v[102:103], v200 offset:0x3600
	v_mfma_f32_32x32x16_bf16 v[48:63], v[86:89], v[72:75], v[48:63]
	ds_read_b64_tr_b16 v[104:105], v200 offset:0x3e00
	s_waitcnt lgkmcnt(0)
	v_mfma_f32_32x32x16_bf16 v[48:63], v[90:93], v[76:79], v[48:63]
	v_mfma_f32_32x32x16_bf16 v[64:79], v[64:67], v[68:71], 0
	s_ashr_i32 s59, s58, 31
	v_lshl_add_u64 v[106:107], v[128:129], 0, s[58:59]
	v_lshlrev_b64 v[106:107], 11, v[106:107]
	v_lshl_add_u64 v[106:107], s[56:57], 0, v[106:107]
	v_lshl_add_u64 v[166:167], v[106:107], 0, v[80:81]
	v_lshl_add_u64 v[106:107], v[130:131], 0, s[58:59]
	s_mov_b32 m0, s4
	v_mfma_f32_32x32x16_bf16 v[64:79], v[82:85], v[94:97], v[64:79]
	v_lshlrev_b64 v[82:83], 11, v[106:107]
	v_lshl_add_u64 v[82:83], s[56:57], 0, v[82:83]
	v_lshl_add_u64 v[168:169], v[82:83], 0, v[80:81]
	v_lshl_add_u64 v[82:83], v[132:133], 0, s[58:59]
	s_waitcnt vmcnt(0)
	s_waitcnt vmcnt(0)
	s_barrier
	global_load_lds_dwordx4 v[166:167], off
	s_mov_b32 m0, s2
	v_lshlrev_b64 v[82:83], 11, v[82:83]
	global_load_lds_dwordx4 v[168:169], off
	v_lshl_add_u64 v[170:171], v[134:135], 0, v[82:83]
	s_mov_b32 m0, s21
	v_mfma_f32_32x32x16_bf16 v[64:79], v[86:89], v[98:101], v[64:79]
	global_load_lds_dwordx4 v[170:171], off
	v_lshl_add_u64 v[138:139], s[56:57], 0, v[80:81]
	s_add_i32 s2, s71, -1
	s_mov_b32 s21, 0
	s_mov_b32 s56, s44
	s_mov_b32 s35, 0
	v_mfma_f32_32x32x16_bf16 v[64:79], v[90:93], v[102:105], v[64:79]
	s_waitcnt lgkmcnt(0)
	s_mov_b32 s33, s20
	s_mov_b32 s20, s35
	s_mul_i32 s35, s5, 0x6000
	s_add_i32 s35, s35, 0
	s_lshl_b32 s41, s5, 14
	s_lshl_b32 s100, s20, 14
	s_add_i32 s100, s100, s4
	s_mul_i32 s101, s20, 0x6000
	s_add_i32 s101, s101, s3
	s_mov_b64 vcc, 0
	v_add_u32_e32 v137, s41, v200
	s_mul_i32 s42, s5, 0x6000
	v_add_u32_e32 v206, s42, v145
	v_add_u32_e32 v207, s42, v161
	v_add_u32_e32 v208, s42, v198
	v_add_u32_e32 v209, s42, v199
	ds_read_b128 v[222:225], v206 offset:49152
	ds_read_b128 v[238:241], v207 offset:49152
	ds_read_b128 v[242:245], v208 offset:49152
.LBB0_155:
	s_waitcnt lgkmcnt(2)
	v_mfma_f32_32x32x16_bf16 v[96:111], v[222:225], v[112:115], v[0:15]
	ds_read_b128 v[246:249], v209 offset:49152
	s_waitcnt lgkmcnt(2)
	v_mfma_f32_32x32x16_bf16 v[96:111], v[238:241], v[116:119], v[96:111]
	ds_read_b128 v[222:225], v206 offset:53248
	s_cbranch_vccz .Lattn_dma_C1_1
	s_ashr_i32 s57, s56, 31
	v_lshl_add_u64 v[184:185], s[56:57], 0, v[128:129]
	v_lshlrev_b64 v[184:185], 11, v[184:185]
	v_lshl_add_u64 v[184:185], v[138:139], 0, v[184:185]
	s_mov_b32 m0, s100
	s_nop 0
	global_load_lds_dwordx4 v[184:185], off

; template <int D0> __device__ __forceinline__ void pv_one(f32x16& od, unsigned vb, bf16x8 pa0, bf16x8 pa1, bf16x8 pa2, bf16x8 pa3) {
;     const s16x4 l0 = tr_read<v_rd_off(D0, 0, 0)>(vb), h0 = tr_read<v_rd_off(D0, 0, 1)>(vb), l1 = tr_read<v_rd_off(D0, 1, 0)>(vb), h1 = tr_read<v_rd_off(D0, 1, 1)>(vb);
;     const s16x4 l2 = tr_read<v_rd_off(D0, 2, 0)>(vb), h2 = tr_read<v_rd_off(D0, 2, 1)>(vb), l3 = tr_read<v_rd_off(D0, 3, 0)>(vb), h3 = tr_read<v_rd_off(D0, 3, 1)>(vb);
;     asm volatile("s_waitcnt lgkmcnt(0)" ::: "memory"); SBAR();
;     ...
;     od = __builtin_amdgcn_mfma_f32_32x32x16_bf16(pa0, PK(l0, h0), od, 0, 0, 0);
;     od = __builtin_amdgcn_mfma_f32_32x32x16_bf16(pa1, PK(l1, h1), od, 0, 0, 0);
;     od = __builtin_amdgcn_mfma_f32_32x32x16_bf16(pa2, PK(l2, h2), od, 0, 0, 0);
;     od = __builtin_amdgcn_mfma_f32_32x32x16_bf16(pa3, PK(l3, h3), od, 0, 0, 0);
;     ...
; }
; __device__ __forceinline__ void pv_d0(f32x16 (&o)[4], unsigned vb, bf16x8 pa0, bf16x8 pa1, bf16x8 pa2, bf16x8 pa3) {
;     pv_one<0>(o[0], vb, pa0, pa1, pa2, pa3); pv_one<1>(o[1], vb, pa0, pa1, pa2, pa3); pv_one<2>(o[2], vb, pa0, pa1, pa2, pa3); pv_one<3>(o[3], vb, pa0, pa1, pa2, pa3);
; }
; __device__ __forceinline__ void partialSM(f32x16& p0, f32x16& p1) {
; #pragma unroll
;     for (int r = 0; r < 16; ++r) p0[r] = __builtin_amdgcn_exp2f(p0[r]);
; }
; __device__ __forceinline__ void finishSM(f32x16& p0, f32x16& p1, float& l_reg, bf16x8& pa0, bf16x8& pa1, bf16x8& pa2, bf16x8& pa3) {
; #pragma unroll
;     for (int r = 0; r < 16; ++r) p1[r] = __builtin_amdgcn_exp2f(p1[r]);
;     float ps = 0;
; #pragma unroll
;     for (int r = 0; r < 16; ++r) ps += p0[r];
; #pragma unroll
;     for (int r = 0; r < 16; ++r) ps += p1[r];
;     l_reg += ps;
;     ...
;     PK8(p0, 0, pa0); PK8(p0, 8, pa1); PK8(p1, 0, pa2); PK8(p1, 8, pa3);
;     ...
; }
; template <int DQK>
; __device__ __forceinline__ void qkt(f32x16& p0, f32x16& p1, const LAS char* Ks, const bf16x8 (&qr)[DQK / 16], const int (&ka)[8], float nMB) {
;     constexpr int RB = DQK * 2, NA = (RB == 256) ? 8 : 4;
; #pragma unroll
;     for (int r = 0; r < 16; ++r) { p0[r] = nMB; p1[r] = nMB; }
; #pragma unroll
;     for (int d0 = 0; d0 < DQK / 16; ++d0) {
;         const LAS char* a = Ks + ka[d0 % NA] + (d0 / NA) * (NA * 32);
;         const bf16x8 b0 = *(const LAS bf16x8*)(a);
;         const bf16x8 b1 = *(const LAS bf16x8*)(a + 32 * RB);
.Lattn_dma_C1_3:
	s_waitcnt lgkmcnt(2)
	v_mfma_f32_32x32x16_bf16 v[80:95], v[222:225], v[112:115], v[0:15]
	ds_read_b128 v[246:249], v209 offset:53248
	s_waitcnt lgkmcnt(2)
	v_mfma_f32_32x32x16_bf16 v[80:95], v[238:241], v[116:119], v[80:95]
	ds_read_b64_tr_b16 v[222:223], v137 offset:0
	ds_read_b64_tr_b16 v[224:225], v137 offset:2048
	s_nop 3
	v_exp_f32_e32 v96, v96
	v_exp_f32_e32 v97, v97
	v_exp_f32_e32 v98, v98
	v_exp_f32_e32 v99, v99
	v_exp_f32_e32 v104, v104
	v_exp_f32_e32 v105, v105
	s_waitcnt lgkmcnt(3)
	v_mfma_f32_32x32x16_bf16 v[80:95], v[242:245], v[120:123], v[80:95]
	ds_read_b64_tr_b16 v[238:239], v137 offset:512
	ds_read_b64_tr_b16 v[240:241], v137 offset:2560
	v_exp_f32_e32 v100, v100
	v_exp_f32_e32 v101, v101
	v_exp_f32_e32 v102, v102
	v_exp_f32_e32 v103, v103
	v_exp_f32_e32 v106, v106
	v_exp_f32_e32 v107, v107
	s_waitcnt lgkmcnt(4)
	v_mfma_f32_32x32x16_bf16 v[80:95], v[246:249], v[124:127], v[80:95]
	ds_read_b64_tr_b16 v[242:243], v137 offset:1024
	ds_read_b64_tr_b16 v[244:245], v137 offset:3072
	v_cvt_pk_bf16_f32 v206, v96, v97
	v_cvt_pk_bf16_f32 v207, v98, v99
	v_cvt_pk_bf16_f32 v208, v100, v101
	v_cvt_pk_bf16_f32 v209, v102, v103
	v_exp_f32_e32 v108, v108
	v_exp_f32_e32 v109, v109
	v_add_f32_e32 v96, 0, v96
	v_add_f32_e32 v96, v97, v96
	s_waitcnt lgkmcnt(4)
	v_mfma_f32_32x32x16_bf16 v[16:31], v[206:209], v[222:225], v[16:31]
	ds_read_b64_tr_b16 v[246:247], v137 offset:1536
	ds_read_b64_tr_b16 v[248:249], v137 offset:3584
	v_exp_f32_e32 v110, v110
	v_exp_f32_e32 v111, v111
	v_add_f32_e32 v96, v98, v96
	v_add_f32_e32 v96, v99, v96
	s_waitcnt lgkmcnt(4)
	v_mfma_f32_32x32x16_bf16 v[32:47], v[206:209], v[238:241], v[32:47]
	ds_read_b64_tr_b16 v[222:223], v137 offset:4096
	ds_read_b64_tr_b16 v[224:225], v137 offset:6144
	v_cvt_pk_bf16_f32 v210, v104, v105
	v_cvt_pk_bf16_f32 v211, v106, v107
	v_exp_f32_e32 v80, v80
	v_exp_f32_e32 v81, v81
	v_exp_f32_e32 v88, v88
	v_exp_f32_e32 v89, v89
	v_add_f32_e32 v96, v100, v96
	v_add_f32_e32 v96, v101, v96
	s_waitcnt lgkmcnt(4)
	v_mfma_f32_32x32x16_bf16 v[48:63], v[206:209], v[242:245], v[48:63]
	ds_read_b64_tr_b16 v[238:239], v137 offset:4608
	ds_read_b64_tr_b16 v[240:241], v137 offset:6656
	v_cvt_pk_bf16_f32 v212, v108, v109
	v_exp_f32_e32 v82, v82
	v_exp_f32_e32 v83, v83
	v_exp_f32_e32 v90, v90
	v_add_f32_e32 v96, v102, v96
	v_add_f32_e32 v96, v103, v96
	s_waitcnt lgkmcnt(4)
	v_mfma_f32_32x32x16_bf16 v[64:79], v[206:209], v[246:249], v[64:79]
	ds_read_b64_tr_b16 v[242:243], v137 offset:5120
	ds_read_b64_tr_b16 v[244:245], v137 offset:7168
	v_cvt_pk_bf16_f32 v213, v110, v111
	v_exp_f32_e32 v84, v84
	v_exp_f32_e32 v85, v85
	v_exp_f32_e32 v91, v91
	v_add_f32_e32 v96, v104, v96
	v_add_f32_e32 v96, v105, v96
	s_waitcnt lgkmcnt(4)
	v_mfma_f32_32x32x16_bf16 v[16:31], v[210:213], v[222:225], v[16:31]
	ds_read_b64_tr_b16 v[246:247], v137 offset:5632
	ds_read_b64_tr_b16 v[248:249], v137 offset:7680
	v_exp_f32_e32 v86, v86
	v_exp_f32_e32 v87, v87
	v_exp_f32_e32 v92, v92
	v_add_f32_e32 v96, v106, v96
	v_add_f32_e32 v96, v107, v96
	s_waitcnt lgkmcnt(4)
	v_mfma_f32_32x32x16_bf16 v[32:47], v[210:213], v[238:241], v[32:47]
	ds_read_b64_tr_b16 v[222:223], v137 offset:8192
	ds_read_b64_tr_b16 v[224:225], v137 offset:10240
	v_cvt_pk_bf16_f32 v214, v80, v81
	v_cvt_pk_bf16_f32 v215, v82, v83
	v_exp_f32_e32 v93, v93
	v_add_f32_e32 v96, v108, v96
	v_add_f32_e32 v96, v109, v96
	s_waitcnt lgkmcnt(4)
	v_mfma_f32_32x32x16_bf16 v[48:63], v[210:213], v[242:245], v[48:63]
	ds_read_b64_tr_b16 v[238:239], v137 offset:8704
	ds_read_b64_tr_b16 v[240:241], v137 offset:10752
	v_cvt_pk_bf16_f32 v216, v84, v85
	v_exp_f32_e32 v94, v94
	v_add_f32_e32 v96, v110, v96
	v_add_f32_e32 v96, v111, v96
	s_waitcnt lgkmcnt(4)
	v_mfma_f32_32x32x16_bf16 v[64:79], v[210:213], v[246:249], v[64:79]
	ds_read_b64_tr_b16 v[242:243], v137 offset:9216
	ds_read_b64_tr_b16 v[244:245], v137 offset:11264
	v_cvt_pk_bf16_f32 v217, v86, v87
	v_exp_f32_e32 v95, v95
	v_add_f32_e32 v80, v80, v96
	v_add_f32_e32 v80, v81, v80
	s_waitcnt lgkmcnt(4)
	v_mfma_f32_32x32x16_bf16 v[16:31], v[214:217], v[222:225], v[16:31]
	ds_read_b64_tr_b16 v[246:247], v137 offset:9728
	ds_read_b64_tr_b16 v[248:249], v137 offset:11776
	v_cvt_pk_bf16_f32 v218, v88, v89
	v_add_f32_e32 v80, v82, v80
	v_add_f32_e32 v80, v83, v80
	v_add_f32_e32 v80, v84, v80
	s_waitcnt lgkmcnt(4)
	v_mfma_f32_32x32x16_bf16 v[32:47], v[214:217], v[238:241], v[32:47]
	ds_read_b64_tr_b16 v[222:223], v137 offset:12288
	ds_read_b64_tr_b16 v[224:225], v137 offset:14336
	v_cvt_pk_bf16_f32 v219, v90, v91
	v_add_f32_e32 v80, v85, v80
	v_add_f32_e32 v80, v86, v80
	v_add_f32_e32 v80, v87, v80
	s_waitcnt lgkmcnt(4)
	v_mfma_f32_32x32x16_bf16 v[48:63], v[214:217], v[242:245], v[48:63]
	ds_read_b64_tr_b16 v[238:239], v137 offset:12800
	ds_read_b64_tr_b16 v[240:241], v137 offset:14848
	v_cvt_pk_bf16_f32 v220, v92, v93
	s_waitcnt lgkmcnt(4)
	v_mfma_f32_32x32x16_bf16 v[64:79], v[214:217], v[246:249], v[64:79]
	ds_read_b64_tr_b16 v[242:243], v137 offset:13312
	ds_read_b64_tr_b16 v[244:245], v137 offset:15360
	v_cvt_pk_bf16_f32 v221, v94, v95
	v_add_f32_e32 v80, v88, v80
	v_add_f32_e32 v80, v89, v80
	v_add_f32_e32 v80, v90, v80
	s_waitcnt lgkmcnt(4)
	v_mfma_f32_32x32x16_bf16 v[16:31], v[218:221], v[222:225], v[16:31]
	ds_read_b64_tr_b16 v[246:247], v137 offset:13824
	ds_read_b64_tr_b16 v[248:249], v137 offset:15872
	s_mul_i32 s42, s33, 0x6000
	v_add_u32_e32 v206, s42, v145
	v_add_u32_e32 v207, s42, v161
	v_add_u32_e32 v208, s42, v198
	v_add_u32_e32 v209, s42, v199
	v_add_f32_e32 v80, v91, v80
	v_add_f32_e32 v80, v92, v80
	v_add_f32_e32 v80, v93, v80
	v_add_f32_e32 v80, v94, v80
	s_waitcnt lgkmcnt(4)
	v_mfma_f32_32x32x16_bf16 v[32:47], v[218:221], v[238:241], v[32:47]
	ds_read_b128 v[222:225], v206 offset:49152
	v_add_f32_e32 v80, v95, v80
	s_waitcnt lgkmcnt(3)
	v_mfma_f32_32x32x16_bf16 v[48:63], v[218:221], v[242:245], v[48:63]
	ds_read_b128 v[238:241], v207 offset:49152
	s_waitcnt lgkmcnt(2)
	v_mfma_f32_32x32x16_bf16 v[64:79], v[218:221], v[246:249], v[64:79]
	ds_read_b128 v[242:245], v208 offset:49152
	s_mov_b32 s35, s5
	s_mov_b32 s5, s33
	s_mov_b32 s33, s20
	s_mov_b32 s20, s35
	s_mul_i32 s35, s5, 0x6000
	s_add_i32 s35, s35, 0
	s_lshl_b32 s41, s5, 14
	s_lshl_b32 s100, s20, 14
	s_add_i32 s100, s100, s4
	s_mul_i32 s101, s20, 0x6000
	s_add_i32 s101, s101, s3
	s_add_i32 s21, s21, 1
	s_add_i32 s42, s21, 3
	s_cmp_lt_i32 s42, s71
	s_cselect_b64 vcc, -1, 0
	v_add_u32_e32 v137, s41, v200
	v_add_f32_e32 v136, v136, v80
	s_cmp_lg_u32 s2, s21
	s_cbranch_scc0 .LBB0_160
	s_waitcnt vmcnt(0)
	s_barrier
	s_branch .LBB0_155
; #define LAS __attribute__((address_space(3)))
; __device__ __forceinline__ int crow(int r, int hi) { return (r & 3) + 8 * (r >> 2) + 4 * hi; }
; __device__ __forceinline__ void row_recip(float l_reg, float (&rli)[16], LAS float* li, int r32, int hi) {
;     { auto rr = __builtin_amdgcn_permlane32_swap(__float_as_uint(l_reg), __float_as_uint(l_reg), false, false);
;       l_reg = __uint_as_float(rr[0]) + __uint_as_float(rr[1]); }
;     if (hi == 0) li[r32] = l_reg;
;     asm volatile("s_waitcnt lgkmcnt(0)" ::: "memory");
; #pragma unroll
;     for (int r = 0; r < 16; ++r) rli[r] = __builtin_amdgcn_rcpf(li[crow(r, hi)]);
;     asm volatile("s_waitcnt lgkmcnt(0)" ::: "memory");
; }
; __device__ __forceinline__ void attn_item(const AttnBufs& T, int type, int b, int h, int qrow0, int NT, LAS char* lds, int tid_) {
;     ...
;         att::row_recip(l_reg, rli, li, r32, hi);
;         f32x4* scr = (f32x4*)(T.SCR + ((size_t)blockIdx.x * 512 + tid) * 64);
; #pragma unroll
;         for (int d0 = 0; d0 < 4; ++d0)
; #pragma unroll
;             for (int q = 0; q < 4; ++q) scr[d0 * 4 + q] = (f32x4){o[d0][q * 4] * rli[q * 4], o[d0][q * 4 + 1] * rli[q * 4 + 1], o[d0][q * 4 + 2] * rli[q * 4 + 2], o[d0][q * 4 + 3] * rli[q * 4 + 3]};
;         att::attn_pass<64, ATT_DBL>(T.QC + (size_t)qrow0 * 1024 + h * 128 + 64, 1024, T.KC + h * 128 + 64, 1024, T.VC + h * 128, 1024, rowc, rowl, NT,
;                            T.lamv[3], o, l_reg, lds, tid);
.LBB0_160:
	s_waitcnt lgkmcnt(0)
	s_nop 11
	v_mov_b32_e32 v0, v136
	s_nop 1
	v_permlane32_swap_b32_e32 v136, v0
	v_cmp_gt_u32_e32 vcc, 32, v182
	s_and_saveexec_b64 s[56:57], vcc
	v_lshl_add_u32 v1, v181, 2, s90
	v_add_f32_e32 v0, v136, v0
	ds_write_b32 v1, v0
	s_or_b64 exec, exec, s[56:57]
	s_waitcnt lgkmcnt(0)
	v_add_u32_e32 v201, s90, v144
	ds_read_b128 v[0:3], v201
	ds_read_b128 v[4:7], v201 offset:32
	v_readlane_b32 s4, v253, 11
	v_readlane_b32 s5, v253, 12
	v_readfirstlane_b32 s3, v164
	s_waitcnt lgkmcnt(0)
	v_rcp_f32_e32 v8, v0
	v_rcp_f32_e32 v9, v1
	v_rcp_f32_e32 v10, v2
	v_rcp_f32_e32 v11, v3
	ds_read_b128 v[0:3], v201 offset:64
	v_rcp_f32_e32 v12, v4
	v_rcp_f32_e32 v13, v5
	v_rcp_f32_e32 v14, v6
	v_rcp_f32_e32 v15, v7
	ds_read_b128 v[4:7], v201 offset:96
	s_waitcnt lgkmcnt(0)
	v_rcp_f32_e32 v80, v0
	v_rcp_f32_e32 v81, v1
	v_rcp_f32_e32 v82, v2
	v_rcp_f32_e32 v83, v3
	v_rcp_f32_e32 v4, v4
	v_rcp_f32_e32 v5, v5
	v_rcp_f32_e32 v6, v6
	v_rcp_f32_e32 v7, v7
	v_lshlrev_b64 v[0:1], 8, v[164:165]
	v_lshl_add_u64 v[136:137], s[4:5], 0, v[0:1]
	v_pk_mul_f32 v[0:1], v[16:17], v[8:9]
	v_pk_mul_f32 v[2:3], v[18:19], v[10:11]
	s_waitcnt lgkmcnt(0)
	global_store_dwordx4 v[136:137], v[0:3], off
	s_ashr_i32 s3, s3, 6
	s_mov_b32 s5, 1
	v_pk_mul_f32 v[0:1], v[20:21], v[12:13]
	v_pk_mul_f32 v[2:3], v[22:23], v[14:15]
	global_store_dwordx4 v[136:137], v[0:3], off offset:16
	s_nop 1
	v_pk_mul_f32 v[0:1], v[24:25], v[80:81]
	v_pk_mul_f32 v[2:3], v[26:27], v[82:83]
	global_store_dwordx4 v[136:137], v[0:3], off offset:32
	s_nop 1
	v_pk_mul_f32 v[0:1], v[28:29], v[4:5]
	v_pk_mul_f32 v[2:3], v[30:31], v[6:7]
	global_store_dwordx4 v[136:137], v[0:3], off offset:48
	s_nop 1
	v_pk_mul_f32 v[0:1], v[32:33], v[8:9]
	v_pk_mul_f32 v[2:3], v[34:35], v[10:11]
	global_store_dwordx4 v[136:137], v[0:3], off offset:64
	s_nop 1
	v_pk_mul_f32 v[0:1], v[36:37], v[12:13]
	v_pk_mul_f32 v[2:3], v[38:39], v[14:15]
	global_store_dwordx4 v[136:137], v[0:3], off offset:80
	s_nop 1
	v_pk_mul_f32 v[0:1], v[40:41], v[80:81]
	v_pk_mul_f32 v[2:3], v[42:43], v[82:83]
	global_store_dwordx4 v[136:137], v[0:3], off offset:96
	s_nop 1
	v_pk_mul_f32 v[0:1], v[44:45], v[4:5]
	v_pk_mul_f32 v[2:3], v[46:47], v[6:7]
	global_store_dwordx4 v[136:137], v[0:3], off offset:112
	s_nop 1
	v_pk_mul_f32 v[0:1], v[48:49], v[8:9]
	v_pk_mul_f32 v[2:3], v[50:51], v[10:11]
	global_store_dwordx4 v[136:137], v[0:3], off offset:128
	s_nop 1
	v_pk_mul_f32 v[0:1], v[52:53], v[12:13]
	v_pk_mul_f32 v[2:3], v[54:55], v[14:15]
	global_store_dwordx4 v[136:137], v[0:3], off offset:144
	s_nop 1
	v_pk_mul_f32 v[0:1], v[56:57], v[80:81]
	v_pk_mul_f32 v[2:3], v[58:59], v[82:83]
	global_store_dwordx4 v[136:137], v[0:3], off offset:160
	s_nop 1
	v_pk_mul_f32 v[0:1], v[60:61], v[4:5]
	v_pk_mul_f32 v[2:3], v[62:63], v[6:7]
	global_store_dwordx4 v[136:137], v[0:3], off offset:176
	s_nop 1
	v_pk_mul_f32 v[0:1], v[64:65], v[8:9]
	v_pk_mul_f32 v[2:3], v[66:67], v[10:11]
	global_store_dwordx4 v[136:137], v[0:3], off offset:192
	s_nop 1
	v_pk_mul_f32 v[0:1], v[68:69], v[12:13]
	v_pk_mul_f32 v[2:3], v[70:71], v[14:15]
	global_store_dwordx4 v[136:137], v[0:3], off offset:208
	s_nop 1
	v_pk_mul_f32 v[0:1], v[72:73], v[80:81]
	v_pk_mul_f32 v[2:3], v[74:75], v[82:83]
	global_store_dwordx4 v[136:137], v[0:3], off offset:224
	s_nop 1
	v_pk_mul_f32 v[0:1], v[76:77], v[4:5]
	v_pk_mul_f32 v[2:3], v[78:79], v[6:7]
	global_store_dwordx4 v[136:137], v[0:3], off offset:240
	global_load_dword v48, v177, s[14:15] offset:12
	s_waitcnt vmcnt(0)
	v_mov_b32_e32 v49, v48
	v_lshl_or_b32 v0, s3, 5, v181
	v_ashrrev_i32_e32 v1, 31, v0
	v_lshlrev_b64 v[0:1], 11, v[0:1]
	s_lshl_b32 s3, s3, 10
	v_lshl_add_u64 v[0:1], s[50:51], 0, v[0:1]
	v_lshlrev_b32_e32 v2, 1, v172
	v_mov_b32_e32 v3, v177
	s_add_i32 s4, s3, 0
	v_lshl_add_u64 v[0:1], v[0:1], 0, v[2:3]
	s_mov_b32 m0, s4
	s_add_i32 s20, s4, 0x2000
	global_load_dwordx4 v[112:115], v[0:1], off offset:128
	global_load_dwordx4 v[116:119], v[0:1], off offset:160
	global_load_dwordx4 v[120:123], v[0:1], off offset:192
	global_load_dwordx4 v[124:127], v[0:1], off offset:224
	s_barrier
	global_load_lds_dwordx4 v[140:141], off
	s_mov_b32 m0, s20
	s_add_i32 s21, s4, 0xc000
	global_load_lds_dwordx4 v[142:143], off
	v_lshl_add_u64 v[0:1], v[146:147], 0, s[0:1]
	s_mov_b32 m0, s21
	v_mov_b32_e32 v50, v48
	global_load_lds_dwordx4 v[0:1], off
	s_add_i32 m0, s4, 0x4000
	v_lshl_add_u64 v[0:1], v[152:153], 0, s[0:1]
	global_load_lds_dwordx4 v[148:149], off
	s_add_i32 m0, s4, 0x6000
	v_mov_b32_e32 v51, v48
	global_load_lds_dwordx4 v[150:151], off
	s_add_i32 m0, s4, 0x12000
	v_mov_b32_e32 v52, v48
	global_load_lds_dwordx4 v[0:1], off
	s_add_i32 m0, s4, 0x8000
	s_waitcnt vmcnt(0)
	s_waitcnt vmcnt(0) lgkmcnt(0)
	s_barrier
; template <int D0> __device__ __forceinline__ void pv_one(f32x16& od, unsigned vb, bf16x8 pa0, bf16x8 pa1, bf16x8 pa2, bf16x8 pa3) {
;     const s16x4 l0 = tr_read<v_rd_off(D0, 0, 0)>(vb), h0 = tr_read<v_rd_off(D0, 0, 1)>(vb), l1 = tr_read<v_rd_off(D0, 1, 0)>(vb), h1 = tr_read<v_rd_off(D0, 1, 1)>(vb);
;     const s16x4 l2 = tr_read<v_rd_off(D0, 2, 0)>(vb), h2 = tr_read<v_rd_off(D0, 2, 1)>(vb), l3 = tr_read<v_rd_off(D0, 3, 0)>(vb), h3 = tr_read<v_rd_off(D0, 3, 1)>(vb);
;     asm volatile("s_waitcnt lgkmcnt(0)" ::: "memory"); SBAR();
;     ...
;     od = __builtin_amdgcn_mfma_f32_32x32x16_bf16(pa0, PK(l0, h0), od, 0, 0, 0);
;     od = __builtin_amdgcn_mfma_f32_32x32x16_bf16(pa1, PK(l1, h1), od, 0, 0, 0);
;     od = __builtin_amdgcn_mfma_f32_32x32x16_bf16(pa2, PK(l2, h2), od, 0, 0, 0);
;     od = __builtin_amdgcn_mfma_f32_32x32x16_bf16(pa3, PK(l3, h3), od, 0, 0, 0);
;     ...
; }
; __device__ __forceinline__ void pv_d0(f32x16 (&o)[4], unsigned vb, bf16x8 pa0, bf16x8 pa1, bf16x8 pa2, bf16x8 pa3) {
; __device__ __forceinline__ void partialSM(f32x16& p0, f32x16& p1) {
; #pragma unroll
;     for (int r = 0; r < 16; ++r) p0[r] = __builtin_amdgcn_exp2f(p0[r]);
; }
; __device__ __forceinline__ void finishSM(f32x16& p0, f32x16& p1, float& l_reg, bf16x8& pa0, bf16x8& pa1, bf16x8& pa2, bf16x8& pa3) {
; #pragma unroll
;     for (int r = 0; r < 16; ++r) p1[r] = __builtin_amdgcn_exp2f(p1[r]);
;     float ps = 0;
; #pragma unroll
;     for (int r = 0; r < 16; ++r) ps += p0[r];
; #pragma unroll
;     for (int r = 0; r < 16; ++r) ps += p1[r];
;     l_reg += ps;
;     ...
;     PK8(p0, 0, pa0); PK8(p0, 8, pa1); PK8(p1, 0, pa2); PK8(p1, 8, pa3);
;     ...
; }
; template <int DQK>
; __device__ __forceinline__ void qkt(f32x16& p0, f32x16& p1, const LAS char* Ks, const bf16x8 (&qr)[DQK / 16], const int (&ka)[8], float nMB) {
;     constexpr int RB = DQK * 2, NA = (RB == 256) ? 8 : 4;
; #pragma unroll
;     for (int r = 0; r < 16; ++r) { p0[r] = nMB; p1[r] = nMB; }
; #pragma unroll
;     for (int d0 = 0; d0 < DQK / 16; ++d0) {
;         const LAS char* a = Ks + ka[d0 % NA] + (d0 / NA) * (NA * 32);
;         const bf16x8 b0 = *(const LAS bf16x8*)(a);
;         const bf16x8 b1 = *(const LAS bf16x8*)(a + 32 * RB);
;         p0 = __builtin_amdgcn_mfma_f32_32x32x16_bf16(b0, qr[d0], p0, 0, 0, 0);
;         p1 = __builtin_amdgcn_mfma_f32_32x32x16_bf16(b1, qr[d0], p1, 0, 0, 0); }
; }
	global_load_lds_dwordx4 v[154:155], off
	s_add_i32 m0, s4, 0xa000
	v_lshl_add_u64 v[0:1], v[158:159], 0, s[0:1]
	global_load_lds_dwordx4 v[156:157], off
	s_add_i32 m0, s4, 0x18000
	v_mov_b32_e32 v53, v48
	global_load_lds_dwordx4 v[0:1], off
	v_mov_b32_e32 v54, v48
	v_mov_b32_e32 v55, v48
	v_mov_b32_e32 v56, v48
	v_mov_b32_e32 v57, v48
	v_mov_b32_e32 v58, v48
	v_mov_b32_e32 v59, v48
	v_mov_b32_e32 v60, v48
	v_mov_b32_e32 v61, v48
	v_mov_b32_e32 v62, v48
	v_mov_b32_e32 v63, v48
	ds_read_b128 v[0:3], v202 offset:49152
	ds_read_b128 v[32:35], v202 offset:53248
	s_waitcnt lgkmcnt(0)
	v_mfma_f32_32x32x16_bf16 v[16:31], v[0:3], v[112:115], v[48:63]
	v_mfma_f32_32x32x16_bf16 v[0:15], v[32:35], v[112:115], v[48:63]
	ds_read_b128 v[32:35], v203 offset:49152
	ds_read_b128 v[36:39], v203 offset:53248
	s_waitcnt lgkmcnt(0)
	v_mfma_f32_32x32x16_bf16 v[16:31], v[32:35], v[116:119], v[16:31]
	v_mfma_f32_32x32x16_bf16 v[0:15], v[36:39], v[116:119], v[0:15]
	ds_read_b128 v[32:35], v204 offset:49152
	ds_read_b128 v[36:39], v204 offset:53248
	s_waitcnt lgkmcnt(0)
	v_mfma_f32_32x32x16_bf16 v[16:31], v[32:35], v[120:123], v[16:31]
	v_mfma_f32_32x32x16_bf16 v[0:15], v[36:39], v[120:123], v[0:15]
	ds_read_b128 v[32:35], v205 offset:49152
	ds_read_b128 v[36:39], v205 offset:53248
	s_waitcnt lgkmcnt(0)
	v_mfma_f32_32x32x16_bf16 v[16:31], v[32:35], v[124:127], v[16:31]
	v_mfma_f32_32x32x16_bf16 v[0:15], v[36:39], v[124:127], v[0:15]
	s_nop 10
	v_exp_f32_e32 v16, v16
	v_exp_f32_e32 v17, v17
	v_exp_f32_e32 v18, v18
	v_exp_f32_e32 v19, v19
	v_exp_f32_e32 v20, v20
	v_exp_f32_e32 v21, v21
	v_exp_f32_e32 v22, v22
	v_exp_f32_e32 v32, v0
	v_add_f32_e32 v0, 0, v16
	v_add_f32_e32 v0, v17, v0
	v_add_f32_e32 v0, v18, v0
	v_exp_f32_e32 v23, v23
	v_add_f32_e32 v0, v19, v0
	v_exp_f32_e32 v24, v24
	v_add_f32_e32 v0, v20, v0
	v_exp_f32_e32 v25, v25
	v_add_f32_e32 v0, v21, v0
	v_exp_f32_e32 v26, v26
	v_add_f32_e32 v0, v22, v0
	v_exp_f32_e32 v27, v27
	v_add_f32_e32 v0, v23, v0
	v_exp_f32_e32 v28, v28
	v_add_f32_e32 v0, v24, v0
	v_exp_f32_e32 v29, v29
	v_add_f32_e32 v0, v25, v0
	v_exp_f32_e32 v30, v30
	v_add_f32_e32 v0, v26, v0
	v_exp_f32_e32 v31, v31
	v_add_f32_e32 v0, v27, v0
	v_add_f32_e32 v0, v28, v0
	v_exp_f32_e32 v33, v1
	v_add_f32_e32 v0, v29, v0
	v_exp_f32_e32 v34, v2
	v_add_f32_e32 v0, v30, v0
	v_exp_f32_e32 v35, v3
	v_add_f32_e32 v0, v31, v0
	v_exp_f32_e32 v4, v4
	v_add_f32_e32 v0, v32, v0
	v_exp_f32_e32 v5, v5
	v_add_f32_e32 v0, v33, v0
	v_exp_f32_e32 v6, v6
	v_add_f32_e32 v0, v34, v0
	v_exp_f32_e32 v7, v7
	v_add_f32_e32 v0, v35, v0
	v_exp_f32_e32 v8, v8
	v_add_f32_e32 v0, v4, v0
	v_exp_f32_e32 v9, v9
	v_add_f32_e32 v0, v5, v0
	v_exp_f32_e32 v10, v10
	v_add_f32_e32 v0, v6, v0
	v_exp_f32_e32 v11, v11
	v_add_f32_e32 v0, v7, v0
	v_exp_f32_e32 v12, v12
	v_add_f32_e32 v0, v8, v0
	v_exp_f32_e32 v13, v13
	v_add_f32_e32 v0, v9, v0
	v_exp_f32_e32 v14, v14
	v_add_f32_e32 v0, v10, v0
	v_exp_f32_e32 v15, v15
	v_add_f32_e32 v0, v11, v0
	v_add_f32_e32 v0, v12, v0
	v_add_f32_e32 v0, v13, v0
	v_add_f32_e32 v0, v14, v0
	v_add_f32_e32 v0, v15, v0
	v_add_f32_e32 v140, 0, v0
	v_cvt_pk_bf16_f32 v0, v16, v17
	v_cvt_pk_bf16_f32 v1, v18, v19
	v_cvt_pk_bf16_f32 v2, v20, v21
	v_cvt_pk_bf16_f32 v3, v22, v23
	v_cvt_pk_bf16_f32 v80, v24, v25
	v_cvt_pk_bf16_f32 v81, v26, v27
	v_cvt_pk_bf16_f32 v82, v28, v29
	v_cvt_pk_bf16_f32 v83, v30, v31
	v_cvt_pk_bf16_f32 v84, v32, v33
	v_cvt_pk_bf16_f32 v85, v34, v35
	v_cvt_pk_bf16_f32 v86, v4, v5
	v_cvt_pk_bf16_f32 v87, v6, v7
	v_cvt_pk_bf16_f32 v88, v8, v9
	v_cvt_pk_bf16_f32 v89, v10, v11
	v_cvt_pk_bf16_f32 v90, v12, v13
	v_cvt_pk_bf16_f32 v91, v14, v15
	ds_read_b64_tr_b16 v[4:5], v200 offset:0
	ds_read_b64_tr_b16 v[6:7], v200 offset:0x800
	ds_read_b64_tr_b16 v[8:9], v200 offset:0x1000
	ds_read_b64_tr_b16 v[10:11], v200 offset:0x1800
	ds_read_b64_tr_b16 v[12:13], v200 offset:0x2000
	ds_read_b64_tr_b16 v[14:15], v200 offset:0x2800
	ds_read_b64_tr_b16 v[16:17], v200 offset:0x3000
	ds_read_b64_tr_b16 v[18:19], v200 offset:0x3800
	s_waitcnt lgkmcnt(0)
	s_nop 0
	v_mfma_f32_32x32x16_bf16 v[64:79], v[0:3], v[4:7], 0
	ds_read_b64_tr_b16 v[4:5], v200 offset:0x200
	ds_read_b64_tr_b16 v[6:7], v200 offset:0xa00
	v_mfma_f32_32x32x16_bf16 v[64:79], v[80:83], v[8:11], v[64:79]
	ds_read_b64_tr_b16 v[8:9], v200 offset:0x1200
	ds_read_b64_tr_b16 v[10:11], v200 offset:0x1a00
	v_mfma_f32_32x32x16_bf16 v[64:79], v[84:87], v[12:15], v[64:79]
	ds_read_b64_tr_b16 v[12:13], v200 offset:0x2200
	ds_read_b64_tr_b16 v[14:15], v200 offset:0x2a00
	v_mfma_f32_32x32x16_bf16 v[64:79], v[88:91], v[16:19], v[64:79]
	ds_read_b64_tr_b16 v[16:17], v200 offset:0x3200
	ds_read_b64_tr_b16 v[18:19], v200 offset:0x3a00
	s_waitcnt lgkmcnt(0)
	v_mfma_f32_32x32x16_bf16 v[32:47], v[0:3], v[4:7], 0
	ds_read_b64_tr_b16 v[4:5], v200 offset:0x400
	ds_read_b64_tr_b16 v[6:7], v200 offset:0xc00
	v_mfma_f32_32x32x16_bf16 v[32:47], v[80:83], v[8:11], v[32:47]
	ds_read_b64_tr_b16 v[8:9], v200 offset:0x1400
	ds_read_b64_tr_b16 v[10:11], v200 offset:0x1c00
	v_mfma_f32_32x32x16_bf16 v[32:47], v[84:87], v[12:15], v[32:47]
	ds_read_b64_tr_b16 v[12:13], v200 offset:0x2400
	ds_read_b64_tr_b16 v[14:15], v200 offset:0x2c00
	ds_read_b64_tr_b16 v[92:93], v200 offset:0x3400
	ds_read_b64_tr_b16 v[94:95], v200 offset:0x3c00
	s_waitcnt lgkmcnt(0)
	v_mfma_f32_32x32x16_bf16 v[32:47], v[88:91], v[16:19], v[32:47]
	v_mfma_f32_32x32x16_bf16 v[16:31], v[0:3], v[4:7], 0
	ds_read_b64_tr_b16 v[4:5], v200 offset:0x600
	ds_read_b64_tr_b16 v[6:7], v200 offset:0xe00
	v_mfma_f32_32x32x16_bf16 v[16:31], v[80:83], v[8:11], v[16:31]
	v_mfma_f32_32x32x16_bf16 v[16:31], v[84:87], v[12:15], v[16:31]
	v_mfma_f32_32x32x16_bf16 v[16:31], v[88:91], v[92:95], v[16:31]
	ds_read_b64_tr_b16 v[92:93], v200 offset:0x1600
	ds_read_b64_tr_b16 v[94:95], v200 offset:0x1e00
	ds_read_b64_tr_b16 v[96:97], v200 offset:0x2600
	ds_read_b64_tr_b16 v[98:99], v200 offset:0x2e00
	ds_read_b64_tr_b16 v[100:101], v200 offset:0x3600
	ds_read_b64_tr_b16 v[102:103], v200 offset:0x3e00
	s_waitcnt lgkmcnt(0)
	v_mfma_f32_32x32x16_bf16 v[0:15], v[0:3], v[4:7], 0
	s_mov_b32 m0, s4
	s_waitcnt vmcnt(0)
	s_waitcnt vmcnt(0)
	s_barrier
; #define SBAR() __builtin_amdgcn_sched_barrier(0)
; #define VMW0() asm volatile("s_waitcnt vmcnt(0)" ::: "memory")
; template <int DQK, bool DOUBLE> ...
;     ...
;         for (int j = 0; j < NT; ++j) {
;             SBAR(); qkt<DQK>(p0, p1, K_lds + bc * K_STRIDE, qr, ka, nMB);
;             partialSM(p0, p1); finishSM(p0, p1, l_reg, pa0, pa1, pa2, pa3); SBAR();
;             pv_d0(o, vb0 + bc * V_BYTES, pa0, pa1, pa2, pa3);
;             if (j + 1 < NT) { VMW0(); __syncthreads(); if (j + 3 < NT) DMA(j + 3, bc); }
;             { const int _t = bc; bc = bn; bn = bf; bf = _t; }
	global_load_lds_dwordx4 v[166:167], off
	s_mov_b32 m0, s20
	v_mfma_f32_32x32x16_bf16 v[0:15], v[80:83], v[92:95], v[0:15]
	global_load_lds_dwordx4 v[168:169], off
	v_lshl_add_u64 v[80:81], v[170:171], 0, s[0:1]
	s_mov_b32 m0, s21
	s_mov_b32 s21, 2
	global_load_lds_dwordx4 v[80:81], off
	v_mfma_f32_32x32x16_bf16 v[0:15], v[84:87], v[96:99], v[0:15]
	s_mov_b32 s20, 0
	s_mov_b32 s50, s44
	s_mov_b32 s35, 0
	v_mfma_f32_32x32x16_bf16 v[0:15], v[88:91], v[100:103], v[0:15]
	s_waitcnt lgkmcnt(0)
	s_mov_b32 s33, s21
	s_mov_b32 s21, s35
	s_mul_i32 s35, s5, 0x6000
	s_add_i32 s35, s35, 0
	s_lshl_b32 s41, s5, 14
	s_lshl_b32 s100, s21, 14
	s_add_i32 s100, s100, s4
	s_mul_i32 s101, s21, 0x6000
	s_add_i32 s101, s101, s3
	s_mov_b64 vcc, 0
	v_add_u32_e32 v141, s41, v200
	s_mul_i32 s42, s5, 0x6000
	v_add_u32_e32 v146, s42, v145
	v_add_u32_e32 v147, s42, v161
	v_add_u32_e32 v148, s42, v198
	v_add_u32_e32 v149, s42, v199
	ds_read_b128 v[202:205], v146 offset:49152
	ds_read_b128 v[206:209], v147 offset:49152
	ds_read_b128 v[210:213], v148 offset:49152
.LBB0_163:
	s_waitcnt lgkmcnt(2)
	v_mfma_f32_32x32x16_bf16 v[96:111], v[202:205], v[112:115], v[48:63]
	ds_read_b128 v[214:217], v149 offset:49152
	s_waitcnt lgkmcnt(2)
	v_mfma_f32_32x32x16_bf16 v[96:111], v[206:209], v[116:119], v[96:111]
	ds_read_b128 v[202:205], v146 offset:53248
	s_cbranch_vccz .Lattn_dma_C2_1
	s_ashr_i32 s51, s50, 31
	v_lshl_add_u64 v[142:143], s[50:51], 0, v[128:129]
	v_lshlrev_b64 v[142:143], 11, v[142:143]
	v_lshl_add_u64 v[142:143], v[138:139], 0, v[142:143]
	s_mov_b32 m0, s100
	s_nop 0
	global_load_lds_dwordx4 v[142:143], off

; template <int D0> __device__ __forceinline__ void pv_one(f32x16& od, unsigned vb, bf16x8 pa0, bf16x8 pa1, bf16x8 pa2, bf16x8 pa3) {
;     const s16x4 l0 = tr_read<v_rd_off(D0, 0, 0)>(vb), h0 = tr_read<v_rd_off(D0, 0, 1)>(vb), l1 = tr_read<v_rd_off(D0, 1, 0)>(vb), h1 = tr_read<v_rd_off(D0, 1, 1)>(vb);
;     const s16x4 l2 = tr_read<v_rd_off(D0, 2, 0)>(vb), h2 = tr_read<v_rd_off(D0, 2, 1)>(vb), l3 = tr_read<v_rd_off(D0, 3, 0)>(vb), h3 = tr_read<v_rd_off(D0, 3, 1)>(vb);
;     asm volatile("s_waitcnt lgkmcnt(0)" ::: "memory"); SBAR();
;     ...
;     od = __builtin_amdgcn_mfma_f32_32x32x16_bf16(pa0, PK(l0, h0), od, 0, 0, 0);
;     od = __builtin_amdgcn_mfma_f32_32x32x16_bf16(pa1, PK(l1, h1), od, 0, 0, 0);
;     od = __builtin_amdgcn_mfma_f32_32x32x16_bf16(pa2, PK(l2, h2), od, 0, 0, 0);
;     od = __builtin_amdgcn_mfma_f32_32x32x16_bf16(pa3, PK(l3, h3), od, 0, 0, 0);
;     ...
; }
; __device__ __forceinline__ void pv_d0(f32x16 (&o)[4], unsigned vb, bf16x8 pa0, bf16x8 pa1, bf16x8 pa2, bf16x8 pa3) {
;     pv_one<0>(o[0], vb, pa0, pa1, pa2, pa3); pv_one<1>(o[1], vb, pa0, pa1, pa2, pa3); pv_one<2>(o[2], vb, pa0, pa1, pa2, pa3); pv_one<3>(o[3], vb, pa0, pa1, pa2, pa3);
; }
; __device__ __forceinline__ void partialSM(f32x16& p0, f32x16& p1) {
; #pragma unroll
;     for (int r = 0; r < 16; ++r) p0[r] = __builtin_amdgcn_exp2f(p0[r]);
; }
; __device__ __forceinline__ void finishSM(f32x16& p0, f32x16& p1, float& l_reg, bf16x8& pa0, bf16x8& pa1, bf16x8& pa2, bf16x8& pa3) {
; #pragma unroll
;     for (int r = 0; r < 16; ++r) p1[r] = __builtin_amdgcn_exp2f(p1[r]);
;     float ps = 0;
; #pragma unroll
;     for (int r = 0; r < 16; ++r) ps += p0[r];
; #pragma unroll
;     for (int r = 0; r < 16; ++r) ps += p1[r];
;     l_reg += ps;
;     ...
;     PK8(p0, 0, pa0); PK8(p0, 8, pa1); PK8(p1, 0, pa2); PK8(p1, 8, pa3);
;     ...
; }
; template <int DQK>
; __device__ __forceinline__ void qkt(f32x16& p0, f32x16& p1, const LAS char* Ks, const bf16x8 (&qr)[DQK / 16], const int (&ka)[8], float nMB) {
;     constexpr int RB = DQK * 2, NA = (RB == 256) ? 8 : 4;
; #pragma unroll
;     for (int r = 0; r < 16; ++r) { p0[r] = nMB; p1[r] = nMB; }
; #pragma unroll
;     for (int d0 = 0; d0 < DQK / 16; ++d0) {
;         const LAS char* a = Ks + ka[d0 % NA] + (d0 / NA) * (NA * 32);
;         const bf16x8 b0 = *(const LAS bf16x8*)(a);
;         const bf16x8 b1 = *(const LAS bf16x8*)(a + 32 * RB);
.Lattn_dma_C2_3:
	s_waitcnt lgkmcnt(2)
	v_mfma_f32_32x32x16_bf16 v[80:95], v[202:205], v[112:115], v[48:63]
	ds_read_b128 v[214:217], v149 offset:53248
	s_waitcnt lgkmcnt(2)
	v_mfma_f32_32x32x16_bf16 v[80:95], v[206:209], v[116:119], v[80:95]
	ds_read_b64_tr_b16 v[202:203], v141 offset:0
	ds_read_b64_tr_b16 v[204:205], v141 offset:2048
	s_nop 3
	v_exp_f32_e32 v96, v96
	v_exp_f32_e32 v97, v97
	v_exp_f32_e32 v98, v98
	v_exp_f32_e32 v99, v99
	v_exp_f32_e32 v104, v104
	v_exp_f32_e32 v105, v105
	s_waitcnt lgkmcnt(3)
	v_mfma_f32_32x32x16_bf16 v[80:95], v[210:213], v[120:123], v[80:95]
	ds_read_b64_tr_b16 v[206:207], v141 offset:512
	ds_read_b64_tr_b16 v[208:209], v141 offset:2560
	v_exp_f32_e32 v100, v100
	v_exp_f32_e32 v101, v101
	v_exp_f32_e32 v102, v102
	v_exp_f32_e32 v103, v103
	v_exp_f32_e32 v106, v106
	v_exp_f32_e32 v107, v107
	s_waitcnt lgkmcnt(4)
	v_mfma_f32_32x32x16_bf16 v[80:95], v[214:217], v[124:127], v[80:95]
	ds_read_b64_tr_b16 v[210:211], v141 offset:1024
	ds_read_b64_tr_b16 v[212:213], v141 offset:3072
	v_cvt_pk_bf16_f32 v146, v96, v97
	v_cvt_pk_bf16_f32 v147, v98, v99
	v_cvt_pk_bf16_f32 v148, v100, v101
	v_cvt_pk_bf16_f32 v149, v102, v103
	v_exp_f32_e32 v108, v108
	v_exp_f32_e32 v109, v109
	v_add_f32_e32 v96, 0, v96
	v_add_f32_e32 v96, v97, v96
	s_waitcnt lgkmcnt(4)
	v_mfma_f32_32x32x16_bf16 v[64:79], v[146:149], v[202:205], v[64:79]
	ds_read_b64_tr_b16 v[214:215], v141 offset:1536
	ds_read_b64_tr_b16 v[216:217], v141 offset:3584
	v_exp_f32_e32 v110, v110
	v_exp_f32_e32 v111, v111
	v_add_f32_e32 v96, v98, v96
	v_add_f32_e32 v96, v99, v96
	s_waitcnt lgkmcnt(4)
	v_mfma_f32_32x32x16_bf16 v[32:47], v[146:149], v[206:209], v[32:47]
	ds_read_b64_tr_b16 v[202:203], v141 offset:4096
	ds_read_b64_tr_b16 v[204:205], v141 offset:6144
	v_cvt_pk_bf16_f32 v150, v104, v105
	v_cvt_pk_bf16_f32 v151, v106, v107
	v_exp_f32_e32 v80, v80
	v_exp_f32_e32 v81, v81
	v_exp_f32_e32 v88, v88
	v_exp_f32_e32 v89, v89
	v_add_f32_e32 v96, v100, v96
	v_add_f32_e32 v96, v101, v96
	s_waitcnt lgkmcnt(4)
	v_mfma_f32_32x32x16_bf16 v[16:31], v[146:149], v[210:213], v[16:31]
	ds_read_b64_tr_b16 v[206:207], v141 offset:4608
	ds_read_b64_tr_b16 v[208:209], v141 offset:6656
	v_cvt_pk_bf16_f32 v152, v108, v109
	v_exp_f32_e32 v82, v82
	v_exp_f32_e32 v83, v83
	v_exp_f32_e32 v90, v90
	v_add_f32_e32 v96, v102, v96
	v_add_f32_e32 v96, v103, v96
	s_waitcnt lgkmcnt(4)
	v_mfma_f32_32x32x16_bf16 v[0:15], v[146:149], v[214:217], v[0:15]
	ds_read_b64_tr_b16 v[210:211], v141 offset:5120
	ds_read_b64_tr_b16 v[212:213], v141 offset:7168
	v_cvt_pk_bf16_f32 v153, v110, v111
	v_exp_f32_e32 v84, v84
	v_exp_f32_e32 v85, v85
	v_exp_f32_e32 v91, v91
	v_add_f32_e32 v96, v104, v96
	v_add_f32_e32 v96, v105, v96
	s_waitcnt lgkmcnt(4)
	v_mfma_f32_32x32x16_bf16 v[64:79], v[150:153], v[202:205], v[64:79]
	ds_read_b64_tr_b16 v[214:215], v141 offset:5632
	ds_read_b64_tr_b16 v[216:217], v141 offset:7680
	v_exp_f32_e32 v86, v86
	v_exp_f32_e32 v87, v87
	v_exp_f32_e32 v92, v92
	v_add_f32_e32 v96, v106, v96
	v_add_f32_e32 v96, v107, v96
	s_waitcnt lgkmcnt(4)
	v_mfma_f32_32x32x16_bf16 v[32:47], v[150:153], v[206:209], v[32:47]
	ds_read_b64_tr_b16 v[202:203], v141 offset:8192
	ds_read_b64_tr_b16 v[204:205], v141 offset:10240
	v_cvt_pk_bf16_f32 v154, v80, v81
	v_cvt_pk_bf16_f32 v155, v82, v83
	v_exp_f32_e32 v93, v93
	v_add_f32_e32 v96, v108, v96
	v_add_f32_e32 v96, v109, v96
	s_waitcnt lgkmcnt(4)
	v_mfma_f32_32x32x16_bf16 v[16:31], v[150:153], v[210:213], v[16:31]
	ds_read_b64_tr_b16 v[206:207], v141 offset:8704
	ds_read_b64_tr_b16 v[208:209], v141 offset:10752
	v_cvt_pk_bf16_f32 v156, v84, v85
	v_exp_f32_e32 v94, v94
	v_add_f32_e32 v96, v110, v96
	v_add_f32_e32 v96, v111, v96
	s_waitcnt lgkmcnt(4)
	v_mfma_f32_32x32x16_bf16 v[0:15], v[150:153], v[214:217], v[0:15]
	ds_read_b64_tr_b16 v[210:211], v141 offset:9216
	ds_read_b64_tr_b16 v[212:213], v141 offset:11264
	v_cvt_pk_bf16_f32 v157, v86, v87
	v_exp_f32_e32 v95, v95
	v_add_f32_e32 v80, v80, v96
	v_add_f32_e32 v80, v81, v80
	s_waitcnt lgkmcnt(4)
	v_mfma_f32_32x32x16_bf16 v[64:79], v[154:157], v[202:205], v[64:79]
	ds_read_b64_tr_b16 v[214:215], v141 offset:9728
	ds_read_b64_tr_b16 v[216:217], v141 offset:11776
	v_cvt_pk_bf16_f32 v166, v88, v89
	v_add_f32_e32 v80, v82, v80
	v_add_f32_e32 v80, v83, v80
	v_add_f32_e32 v80, v84, v80
	s_waitcnt lgkmcnt(4)
	v_mfma_f32_32x32x16_bf16 v[32:47], v[154:157], v[206:209], v[32:47]
	ds_read_b64_tr_b16 v[202:203], v141 offset:12288
	ds_read_b64_tr_b16 v[204:205], v141 offset:14336
	v_cvt_pk_bf16_f32 v167, v90, v91
	v_add_f32_e32 v80, v85, v80
	v_add_f32_e32 v80, v86, v80
	v_add_f32_e32 v80, v87, v80
	s_waitcnt lgkmcnt(4)
	v_mfma_f32_32x32x16_bf16 v[16:31], v[154:157], v[210:213], v[16:31]
	ds_read_b64_tr_b16 v[206:207], v141 offset:12800
	ds_read_b64_tr_b16 v[208:209], v141 offset:14848
	v_cvt_pk_bf16_f32 v168, v92, v93
	s_waitcnt lgkmcnt(4)
	v_mfma_f32_32x32x16_bf16 v[0:15], v[154:157], v[214:217], v[0:15]
	ds_read_b64_tr_b16 v[210:211], v141 offset:13312
	ds_read_b64_tr_b16 v[212:213], v141 offset:15360
	v_cvt_pk_bf16_f32 v169, v94, v95
	v_add_f32_e32 v80, v88, v80
	v_add_f32_e32 v80, v89, v80
	v_add_f32_e32 v80, v90, v80
	s_waitcnt lgkmcnt(4)
	v_mfma_f32_32x32x16_bf16 v[64:79], v[166:169], v[202:205], v[64:79]
	ds_read_b64_tr_b16 v[214:215], v141 offset:13824
	ds_read_b64_tr_b16 v[216:217], v141 offset:15872
	s_mul_i32 s42, s33, 0x6000
	v_add_u32_e32 v146, s42, v145
	v_add_u32_e32 v147, s42, v161
	v_add_u32_e32 v148, s42, v198
	v_add_u32_e32 v149, s42, v199
	v_add_f32_e32 v80, v91, v80
	v_add_f32_e32 v80, v92, v80
	v_add_f32_e32 v80, v93, v80
	v_add_f32_e32 v80, v94, v80
	s_waitcnt lgkmcnt(4)
	v_mfma_f32_32x32x16_bf16 v[32:47], v[166:169], v[206:209], v[32:47]
	ds_read_b128 v[202:205], v146 offset:49152
	v_add_f32_e32 v80, v95, v80
	s_waitcnt lgkmcnt(3)
	v_mfma_f32_32x32x16_bf16 v[16:31], v[166:169], v[210:213], v[16:31]
	ds_read_b128 v[206:209], v147 offset:49152
	s_waitcnt lgkmcnt(2)
	v_mfma_f32_32x32x16_bf16 v[0:15], v[166:169], v[214:217], v[0:15]
	ds_read_b128 v[210:213], v148 offset:49152
	s_mov_b32 s35, s5
	s_mov_b32 s5, s33
	s_mov_b32 s33, s21
	s_mov_b32 s21, s35
	s_mul_i32 s35, s5, 0x6000
	s_add_i32 s35, s35, 0
	s_lshl_b32 s41, s5, 14
	s_lshl_b32 s100, s21, 14
	s_add_i32 s100, s100, s4
	s_mul_i32 s101, s21, 0x6000
	s_add_i32 s101, s101, s3
	s_add_i32 s20, s20, 1
	s_add_i32 s42, s20, 3
	s_cmp_lt_i32 s42, s71
	s_cselect_b64 vcc, -1, 0
	v_add_u32_e32 v141, s41, v200
	v_add_f32_e32 v140, v140, v80
	s_cmp_lg_u32 s2, s20
	s_cbranch_scc0 .LBB0_168
	s_waitcnt vmcnt(0)
	s_barrier
	s_branch .LBB0_163

; #define LAS __attribute__((address_space(3)))
; __device__ __forceinline__ int v_rd_base(int lane) { return ((lane & 3) << 3) | (((lane >> 2) & 3) << 6) | (((lane >> 4) & 1) << 5) | (((lane >> 5) & 1) << 8); }
; #define VMW0() asm volatile("s_waitcnt vmcnt(0)" ::: "memory")
; template <int DQK, bool DOUBLE> ...
;     ...
;     const int wid = __builtin_amdgcn_readfirstlane(tid >> 6), lane = tid & 63, r32 = lane & 31, hi = lane >> 5;
;     LAS char* V_lds = lds; LAS char* K_lds = lds + K_OFF;
;     bf16x8 qr[DQK / 16];
;     { const bf16_t* Qw = Q + (size_t)(wid * 32 + r32) * ldq + hi * 8;
; #pragma unroll
;       for (int d0 = 0; d0 < DQK / 16; ++d0) qr[d0] = *(const bf16x8*)(Qw + d0 * 16); }
; #pragma unroll
;     for (int d = 0; d < 4; ++d) o[d] = f32x16{};
;     l_reg = 0.f;
;     int vrow[2], vcol[2], krow[NLD], kcol[NLD];
; #pragma unroll
;     for (int i = 0; i < 2; ++i) { const int q = tid + 512 * i, sub = q >> 5, within = q & 31, kk = (sub >> 2) * 8 + (within >> 2);
;         vrow[i] = kk; vcol[i] = (sub & 3) * 32 + (within & 3) * 8; }
; #pragma unroll
;     for (int i = 0; i < NLD; ++i) { const int q = tid + 512 * i, row = q / NCH, chp = q % NCH; const int x = (RB == 256) ? (row & 15) : ((row >> 1) & 7);
;         krow[i] = row; kcol[i] = (chp ^ x) * 8; }
;     const unsigned vb0 = (unsigned)(uintptr_t)V_lds + v_rd_base(lane);
;     int ka[8];
; #pragma unroll
;     for (int q = 0; q < 8; ++q) ka[q] = kswz<RB>(r32, q * 32 + hi * 16);
;     ...
;     bf16x8 pa0, pa1, pa2, pa3;
;     __syncthreads();
;     DMA(0, 0); DMA(1, 1); VMW0(); __syncthreads();
; __device__ __forceinline__ void attn_item(const AttnBufs& T, int type, int b, int h, int qrow0, int NT, LAS char* lds, int tid_) {
;     ...
;     if (type == 0 && (MK_ATYPE & 1)) {
;         f32x16 o[4]; float l_reg; float rli[16];
;         att::attn_pass<128, ATT_DBL>(T.QA + (size_t)qrow0 * 1024 + h * 128, 1024, T.KA + (h >> 2) * 128, 256, T.VA + (h >> 2) * 128, 256, rowc, rowl, NT,
;                             T.lamv[1], o, l_reg, lds, tid);
.LBB0_171:
	s_and_b64 vcc, exec, s[48:49]
	s_cbranch_vccz .LBB0_108
	s_lshl_b64 s[2:3], s[30:31], 11
	v_readlane_b32 s4, v251, 26
	v_readlane_b32 s5, v251, 27
	s_add_u32 s4, s4, s2
	s_addc_u32 s5, s5, s3
	s_lshl_b32 s48, s72, 7
	s_ashr_i32 s49, s48, 31
	s_lshl_b64 s[2:3], s[48:49], 1
	s_add_u32 s2, s4, s2
	s_addc_u32 s3, s5, s3
	s_lshl_b32 s4, s72, 5
	s_and_b32 s4, s4, 0xffffff80
	s_ashr_i32 s5, s4, 31
	s_lshl_b64 s[4:5], s[4:5], 1
	v_readlane_b32 s20, v251, 28
	v_readlane_b32 s21, v251, 29
	s_add_u32 s50, s20, s4
	s_addc_u32 s51, s21, s5
	v_readlane_b32 s20, v251, 30
	v_readlane_b32 s21, v251, 31
	s_add_u32 s56, s20, s4
	v_readfirstlane_b32 s4, v164
	s_addc_u32 s57, s21, s5
	s_ashr_i32 s4, s4, 6
	v_lshl_or_b32 v2, s4, 5, v181
	v_bfi_b32 v146, -8, v195, v196
	v_ashrrev_i32_e32 v3, 31, v2
	s_ashr_i32 s47, s46, 31
	v_ashrrev_i32_e32 v147, 31, v146
	v_lshlrev_b64 v[2:3], 11, v[2:3]
	v_lshl_add_u64 v[6:7], v[146:147], 0, s[46:47]
	v_lshl_add_u64 v[2:3], s[2:3], 0, v[2:3]
	v_lshrrev_b32_e32 v1, 28, v165
	s_lshl_b32 s2, s4, 10
	v_lshlrev_b64 v[6:7], 9, v[6:7]
	v_mov_b32_e32 v145, v177
	v_bfi_b32 v148, -8, v197, v196
	v_add_u32_e32 v1, v164, v1
	s_add_i32 s3, s2, 0
	v_lshl_add_u64 v[6:7], s[56:57], 0, v[6:7]
	v_lshlrev_b32_e32 v80, 1, v193
	v_mov_b32_e32 v81, v177
	v_lshl_add_u64 v[2:3], v[2:3], 0, v[144:145]
	v_ashrrev_i32_e32 v150, 4, v1
	v_and_b32_e32 v1, 0x1ffffff0, v1
	v_lshl_add_u64 v[6:7], v[6:7], 0, v[80:81]
	s_mov_b32 m0, s3
	v_ashrrev_i32_e32 v149, 31, v148
	global_load_dword v0, v177, s[14:15] offset:4
	global_load_dwordx4 v[112:115], v[2:3], off
	global_load_dwordx4 v[116:119], v[2:3], off offset:32
	global_load_dwordx4 v[120:123], v[2:3], off offset:64
	global_load_dwordx4 v[124:127], v[2:3], off offset:96
	s_waitcnt lgkmcnt(0)
	global_load_dwordx4 v[128:131], v[2:3], off offset:128
	global_load_dwordx4 v[132:135], v[2:3], off offset:160
	global_load_dwordx4 v[136:139], v[2:3], off offset:192
	global_load_dwordx4 v[140:143], v[2:3], off offset:224
	v_sub_u32_e32 v1, v164, v1
	s_barrier
	global_load_lds_dwordx4 v[6:7], off
	v_lshl_add_u64 v[6:7], v[148:149], 0, s[46:47]
	v_bitop3_b32 v1, v150, v1, 15 bitop3:0x6c
	v_lshlrev_b64 v[6:7], 9, v[6:7]
	v_lshlrev_b32_e32 v2, 3, v1
	v_ashrrev_i32_e32 v1, 31, v194
	v_lshl_add_u64 v[6:7], s[56:57], 0, v[6:7]
	s_add_i32 s21, s3, 0x2000
	v_lshrrev_b32_e32 v1, 28, v1
	v_lshl_add_u64 v[6:7], v[6:7], 0, v[80:81]
	s_mov_b32 m0, s21
	v_ashrrev_i32_e32 v151, 31, v150
	v_add_u32_e32 v1, v194, v1
	global_load_lds_dwordx4 v[6:7], off
	v_lshl_add_u64 v[6:7], v[150:151], 0, s[46:47]
	v_ashrrev_i32_e32 v152, 4, v1
	v_and_b32_e32 v1, 0x1ffffff0, v1
	v_lshlrev_b64 v[6:7], 9, v[6:7]
	v_ashrrev_i32_e32 v3, 31, v2
	v_sub_u32_e32 v1, v194, v1
	s_add_i32 s20, s3, 0xc000
	v_lshl_add_u64 v[6:7], s[50:51], 0, v[6:7]
	v_lshlrev_b64 v[82:83], 1, v[2:3]
	v_bitop3_b32 v1, v152, v1, 15 bitop3:0x6c
	v_lshl_add_u64 v[2:3], v[6:7], 0, v[82:83]
	s_mov_b32 m0, s20
	v_ashrrev_i32_e32 v153, 31, v152
	v_lshlrev_b32_e32 v4, 3, v1
	global_load_lds_dwordx4 v[2:3], off
	v_lshl_add_u64 v[2:3], v[152:153], 0, s[46:47]
	v_lshlrev_b64 v[2:3], 9, v[2:3]
	v_ashrrev_i32_e32 v5, 31, v4
	v_lshl_add_u64 v[2:3], s[50:51], 0, v[2:3]
	v_lshlrev_b64 v[84:85], 1, v[4:5]
	s_add_i32 s31, s3, 0xe000
	s_add_i32 s4, s45, 0x4040
	v_lshl_add_u64 v[2:3], v[2:3], 0, v[84:85]
	s_mov_b32 m0, s31
	s_ashr_i32 s5, s4, 31
	global_load_lds_dwordx4 v[2:3], off
	v_lshl_add_u64 v[2:3], v[146:147], 0, s[4:5]
	v_lshlrev_b64 v[2:3], 9, v[2:3]
	v_lshl_add_u64 v[2:3], s[56:57], 0, v[2:3]
	s_add_i32 m0, s3, 0x4000
	v_lshl_add_u64 v[2:3], v[2:3], 0, v[80:81]
	global_load_lds_dwordx4 v[2:3], off
	v_lshl_add_u64 v[2:3], v[148:149], 0, s[4:5]
	v_lshlrev_b64 v[2:3], 9, v[2:3]
	v_lshl_add_u64 v[2:3], s[56:57], 0, v[2:3]
	v_lshl_add_u64 v[2:3], v[2:3], 0, v[80:81]
	s_add_i32 m0, s3, 0x6000
	v_lshlrev_b32_e32 v1, 8, v181
	global_load_lds_dwordx4 v[2:3], off
	v_lshl_add_u64 v[2:3], v[150:151], 0, s[4:5]
	v_lshlrev_b64 v[2:3], 9, v[2:3]
	v_lshl_add_u64 v[2:3], s[50:51], 0, v[2:3]
	s_add_i32 m0, s3, 0x12000
	v_lshl_add_u64 v[2:3], v[2:3], 0, v[82:83]
	global_load_lds_dwordx4 v[2:3], off
	v_lshl_add_u64 v[2:3], v[152:153], 0, s[4:5]
	v_lshlrev_b64 v[2:3], 9, v[2:3]
	v_lshl_add_u64 v[2:3], s[50:51], 0, v[2:3]
	s_add_i32 s4, s45, 0x4080
	v_lshl_add_u64 v[2:3], v[2:3], 0, v[84:85]
	s_add_i32 m0, s3, 0x14000
	s_ashr_i32 s5, s4, 31
	global_load_lds_dwordx4 v[2:3], off
	v_lshl_add_u64 v[2:3], v[146:147], 0, s[4:5]
	v_lshlrev_b64 v[2:3], 9, v[2:3]
	v_lshl_add_u64 v[2:3], s[56:57], 0, v[2:3]
	s_add_i32 m0, s3, 0x8000
	v_lshl_add_u64 v[2:3], v[2:3], 0, v[80:81]
	s_waitcnt vmcnt(0)
	s_waitcnt vmcnt(0) lgkmcnt(0)
	s_barrier
; #define LAS __attribute__((address_space(3)))
; #define SBAR() __builtin_amdgcn_sched_barrier(0)
; #define PK8(P, BASE, OUT) do { u32x4 w = {cvt_pk_bf16(P[BASE + 0], P[BASE + 1]), cvt_pk_bf16(P[BASE + 2], P[BASE + 3]), cvt_pk_bf16(P[BASE + 4], P[BASE + 5]), cvt_pk_bf16(P[BASE + 6], P[BASE + 7])}; \
;     OUT = *reinterpret_cast<bf16x8*>(&w); } while (0)
; __device__ __forceinline__ void partialSM(f32x16& p0, f32x16& p1) {
; #pragma unroll
;     for (int r = 0; r < 16; ++r) p0[r] = __builtin_amdgcn_exp2f(p0[r]);
; }
; __device__ __forceinline__ void finishSM(f32x16& p0, f32x16& p1, float& l_reg, bf16x8& pa0, bf16x8& pa1, bf16x8& pa2, bf16x8& pa3) {
; #pragma unroll
;     for (int r = 0; r < 16; ++r) p1[r] = __builtin_amdgcn_exp2f(p1[r]);
;     float ps = 0;
; #pragma unroll
;     for (int r = 0; r < 16; ++r) ps += p0[r];
; #pragma unroll
;     for (int r = 0; r < 16; ++r) ps += p1[r];
;     l_reg += ps;
;     ...
;     PK8(p0, 0, pa0); PK8(p0, 8, pa1); PK8(p1, 0, pa2); PK8(p1, 8, pa3);
;     ...
; }
; template <int DQK>
; __device__ __forceinline__ void qkt(f32x16& p0, f32x16& p1, const LAS char* Ks, const bf16x8 (&qr)[DQK / 16], const int (&ka)[8], float nMB) {
;     constexpr int RB = DQK * 2, NA = (RB == 256) ? 8 : 4;
; #pragma unroll
;     for (int r = 0; r < 16; ++r) { p0[r] = nMB; p1[r] = nMB; }
; #pragma unroll
;     for (int d0 = 0; d0 < DQK / 16; ++d0) {
;         const LAS char* a = Ks + ka[d0 % NA] + (d0 / NA) * (NA * 32);
;         const bf16x8 b0 = *(const LAS bf16x8*)(a);
;         const bf16x8 b1 = *(const LAS bf16x8*)(a + 32 * RB);
;         p0 = __builtin_amdgcn_mfma_f32_32x32x16_bf16(b0, qr[d0], p0, 0, 0, 0);
;         p1 = __builtin_amdgcn_mfma_f32_32x32x16_bf16(b1, qr[d0], p1, 0, 0, 0); }
; }
; template <int DQK, bool DOUBLE> ...
;     ...
;         DMA(2, 2);
;         int bc = 0, bn = 1, bf = 2;
;         for (int j = 0; j < NT; ++j) {
;             SBAR(); qkt<DQK>(p0, p1, K_lds + bc * K_STRIDE, qr, ka, nMB);
;             partialSM(p0, p1); finishSM(p0, p1, l_reg, pa0, pa1, pa2, pa3); SBAR();
	global_load_lds_dwordx4 v[2:3], off
	v_lshl_add_u64 v[2:3], v[148:149], 0, s[4:5]
	v_lshlrev_b64 v[2:3], 9, v[2:3]
	v_lshl_add_u64 v[2:3], s[56:57], 0, v[2:3]
	v_lshl_add_u64 v[2:3], v[2:3], 0, v[80:81]
	s_add_i32 m0, s3, 0xa000
	s_movk_i32 s33, 0x118
	global_load_lds_dwordx4 v[2:3], off
	v_lshl_add_u64 v[2:3], v[150:151], 0, s[4:5]
	v_lshlrev_b64 v[2:3], 9, v[2:3]
	v_lshl_add_u64 v[2:3], s[50:51], 0, v[2:3]
	s_add_i32 m0, s3, 0x18000
	v_lshl_add_u64 v[2:3], v[2:3], 0, v[82:83]
	global_load_lds_dwordx4 v[2:3], off
	v_lshl_add_u64 v[2:3], v[152:153], 0, s[4:5]
	v_lshlrev_b64 v[2:3], 9, v[2:3]
	v_lshl_add_u64 v[2:3], s[50:51], 0, v[2:3]
	v_lshl_add_u64 v[2:3], v[2:3], 0, v[84:85]
	s_add_i32 m0, s3, 0x1a000
	s_mov_b32 s5, 1
	global_load_lds_dwordx4 v[2:3], off
	v_lshlrev_b32_e32 v2, 4, v181
	v_and_b32_e32 v2, 0xf0, v2
	v_or_b32_e32 v3, 0x80, v144
	v_bitop3_b32 v166, v3, v1, v2 bitop3:0xde
	v_or_b32_e32 v3, 0xa0, v144
	v_bitop3_b32 v167, v3, v1, v2 bitop3:0xde
	v_or_b32_e32 v3, 0xc0, v144
	v_bitop3_b32 v168, v3, v1, v2 bitop3:0xde
	v_or_b32_e32 v3, 0xe0, v144
	v_bitop3_b32 v145, v144, v1, v2 bitop3:0xde
	v_bitop3_b32 v161, v187, v1, v2 bitop3:0xde
	v_bitop3_b32 v164, v191, v1, v2 bitop3:0xde
	v_bitop3_b32 v165, v192, v1, v2 bitop3:0xde
	v_bitop3_b32 v169, v3, v1, v2 bitop3:0xde
	v_and_b32_e32 v1, 32, v175
	v_and_or_b32 v16, v174, s33, v1
	s_mov_b32 s4, 2
	v_mov_b32_e32 v1, v0
	v_mov_b32_e32 v2, v0
	v_mov_b32_e32 v3, v0
	v_mov_b32_e32 v4, v0
	v_mov_b32_e32 v5, v0
	v_mov_b32_e32 v6, v0
	v_mov_b32_e32 v7, v0
	v_mov_b32_e32 v8, v0
	v_mov_b32_e32 v9, v0
	v_mov_b32_e32 v10, v0
	v_mov_b32_e32 v11, v0
	v_mov_b32_e32 v12, v0
	v_mov_b32_e32 v13, v0
	v_mov_b32_e32 v14, v0
	v_mov_b32_e32 v15, v0
	v_add3_u32 v170, v173, 0, v16
	s_add_i32 s46, s45, 0x40c0
	v_add_u32_e32 v20, 0, v145
	ds_read_b128 v[16:19], v20 offset:49152
	ds_read_b128 v[48:51], v20 offset:57344
	v_add_u32_e32 v52, 0, v161
	s_waitcnt lgkmcnt(0)
	v_mfma_f32_32x32x16_bf16 v[32:47], v[16:19], v[112:115], v[0:15]
	v_mfma_f32_32x32x16_bf16 v[16:31], v[48:51], v[112:115], v[0:15]
	ds_read_b128 v[48:51], v52 offset:49152
	ds_read_b128 v[52:55], v52 offset:57344
	s_waitcnt lgkmcnt(0)
	v_mfma_f32_32x32x16_bf16 v[32:47], v[48:51], v[116:119], v[32:47]
	v_mfma_f32_32x32x16_bf16 v[16:31], v[52:55], v[116:119], v[16:31]
	v_add_u32_e32 v52, 0, v164
	ds_read_b128 v[48:51], v52 offset:49152
	ds_read_b128 v[52:55], v52 offset:57344
	s_waitcnt lgkmcnt(0)
	v_mfma_f32_32x32x16_bf16 v[32:47], v[48:51], v[120:123], v[32:47]
	v_mfma_f32_32x32x16_bf16 v[16:31], v[52:55], v[120:123], v[16:31]
	v_add_u32_e32 v52, 0, v165
	ds_read_b128 v[48:51], v52 offset:49152
	ds_read_b128 v[52:55], v52 offset:57344
	s_waitcnt lgkmcnt(0)
	v_mfma_f32_32x32x16_bf16 v[32:47], v[48:51], v[124:127], v[32:47]
	v_mfma_f32_32x32x16_bf16 v[16:31], v[52:55], v[124:127], v[16:31]
	v_add_u32_e32 v52, 0, v166
	ds_read_b128 v[48:51], v52 offset:49152
	ds_read_b128 v[52:55], v52 offset:57344
	s_waitcnt lgkmcnt(0)
	v_mfma_f32_32x32x16_bf16 v[32:47], v[48:51], v[128:131], v[32:47]
	v_mfma_f32_32x32x16_bf16 v[16:31], v[52:55], v[128:131], v[16:31]
	v_add_u32_e32 v52, 0, v167
	ds_read_b128 v[48:51], v52 offset:49152
	ds_read_b128 v[52:55], v52 offset:57344
	s_waitcnt lgkmcnt(0)
	v_mfma_f32_32x32x16_bf16 v[32:47], v[48:51], v[132:135], v[32:47]
	v_mfma_f32_32x32x16_bf16 v[16:31], v[52:55], v[132:135], v[16:31]
	v_add_u32_e32 v52, 0, v168
	ds_read_b128 v[48:51], v52 offset:49152
	ds_read_b128 v[52:55], v52 offset:57344
	s_waitcnt lgkmcnt(0)
	v_mfma_f32_32x32x16_bf16 v[32:47], v[48:51], v[136:139], v[32:47]
	v_mfma_f32_32x32x16_bf16 v[16:31], v[52:55], v[136:139], v[16:31]
	v_add_u32_e32 v52, 0, v169
	ds_read_b128 v[48:51], v52 offset:49152
	ds_read_b128 v[52:55], v52 offset:57344
	s_waitcnt lgkmcnt(0)
	v_mfma_f32_32x32x16_bf16 v[32:47], v[48:51], v[140:143], v[32:47]
	v_mfma_f32_32x32x16_bf16 v[16:31], v[52:55], v[140:143], v[16:31]
	s_nop 10
	v_exp_f32_e32 v32, v32
	v_exp_f32_e32 v33, v33
	v_exp_f32_e32 v34, v34
	v_exp_f32_e32 v35, v35
	v_exp_f32_e32 v36, v36
	v_add_f32_e32 v48, 0, v32
	v_exp_f32_e32 v37, v37
	v_add_f32_e32 v48, v33, v48
	v_exp_f32_e32 v38, v38
	v_add_f32_e32 v48, v34, v48
	v_exp_f32_e32 v39, v39
	v_add_f32_e32 v48, v35, v48
	v_exp_f32_e32 v40, v40
	v_add_f32_e32 v48, v36, v48
	v_exp_f32_e32 v41, v41
	v_add_f32_e32 v48, v37, v48
	v_exp_f32_e32 v42, v42
	v_add_f32_e32 v48, v38, v48
	v_exp_f32_e32 v43, v43
	v_add_f32_e32 v48, v39, v48
	v_exp_f32_e32 v44, v44
	v_add_f32_e32 v48, v40, v48
	v_exp_f32_e32 v45, v45
	v_add_f32_e32 v48, v41, v48
	v_exp_f32_e32 v46, v46
	v_add_f32_e32 v48, v42, v48
	v_exp_f32_e32 v47, v47
	v_add_f32_e32 v48, v43, v48
	v_exp_f32_e32 v16, v16
	v_add_f32_e32 v48, v44, v48
	v_exp_f32_e32 v17, v17
	v_add_f32_e32 v48, v45, v48
	v_exp_f32_e32 v18, v18
	v_add_f32_e32 v48, v46, v48
	v_exp_f32_e32 v19, v19
	v_add_f32_e32 v48, v47, v48
	v_exp_f32_e32 v20, v20
	v_add_f32_e32 v48, v16, v48
	v_exp_f32_e32 v21, v21
	v_add_f32_e32 v48, v17, v48
	v_exp_f32_e32 v22, v22
	v_add_f32_e32 v48, v18, v48
	v_exp_f32_e32 v23, v23
	v_add_f32_e32 v48, v19, v48
	v_exp_f32_e32 v24, v24
	v_add_f32_e32 v48, v20, v48
	v_exp_f32_e32 v25, v25
	v_add_f32_e32 v48, v21, v48
	v_exp_f32_e32 v26, v26
	v_add_f32_e32 v48, v22, v48
	v_exp_f32_e32 v27, v27
	v_add_f32_e32 v48, v23, v48
	v_exp_f32_e32 v28, v28
	v_add_f32_e32 v48, v24, v48
	v_exp_f32_e32 v29, v29
	v_add_f32_e32 v48, v25, v48
	v_exp_f32_e32 v30, v30
	v_add_f32_e32 v48, v26, v48
	v_exp_f32_e32 v31, v31
	v_add_f32_e32 v48, v27, v48
	v_add_f32_e32 v48, v28, v48
	v_add_f32_e32 v48, v29, v48
	v_add_f32_e32 v48, v30, v48
	v_add_f32_e32 v48, v31, v48
	v_add_f32_e32 v171, 0, v48
	v_cvt_pk_bf16_f32 v64, v32, v33
	v_cvt_pk_bf16_f32 v65, v34, v35
	v_cvt_pk_bf16_f32 v66, v36, v37
	v_cvt_pk_bf16_f32 v67, v38, v39
	v_cvt_pk_bf16_f32 v86, v40, v41
	v_cvt_pk_bf16_f32 v87, v42, v43
	v_cvt_pk_bf16_f32 v88, v44, v45
	v_cvt_pk_bf16_f32 v89, v46, v47
	v_cvt_pk_bf16_f32 v90, v16, v17
	v_cvt_pk_bf16_f32 v91, v18, v19
	v_cvt_pk_bf16_f32 v92, v20, v21
	v_cvt_pk_bf16_f32 v93, v22, v23
	v_cvt_pk_bf16_f32 v94, v24, v25
	v_cvt_pk_bf16_f32 v95, v26, v27
	v_cvt_pk_bf16_f32 v96, v28, v29
	v_cvt_pk_bf16_f32 v97, v30, v31
	ds_read_b64_tr_b16 v[16:17], v170 offset:0
	ds_read_b64_tr_b16 v[18:19], v170 offset:0x800
	ds_read_b64_tr_b16 v[32:33], v170 offset:0x1000
	ds_read_b64_tr_b16 v[34:35], v170 offset:0x1800
	ds_read_b64_tr_b16 v[36:37], v170 offset:0x2000
	ds_read_b64_tr_b16 v[38:39], v170 offset:0x2800
	ds_read_b64_tr_b16 v[40:41], v170 offset:0x3000
	ds_read_b64_tr_b16 v[42:43], v170 offset:0x3800
	s_waitcnt lgkmcnt(0)
; #define SBAR() __builtin_amdgcn_sched_barrier(0)
; #define VMW0() asm volatile("s_waitcnt vmcnt(0)" ::: "memory")
; template <int D0> __device__ __forceinline__ void pv_one(f32x16& od, unsigned vb, bf16x8 pa0, bf16x8 pa1, bf16x8 pa2, bf16x8 pa3) {
;     const s16x4 l0 = tr_read<v_rd_off(D0, 0, 0)>(vb), h0 = tr_read<v_rd_off(D0, 0, 1)>(vb), l1 = tr_read<v_rd_off(D0, 1, 0)>(vb), h1 = tr_read<v_rd_off(D0, 1, 1)>(vb);
;     const s16x4 l2 = tr_read<v_rd_off(D0, 2, 0)>(vb), h2 = tr_read<v_rd_off(D0, 2, 1)>(vb), l3 = tr_read<v_rd_off(D0, 3, 0)>(vb), h3 = tr_read<v_rd_off(D0, 3, 1)>(vb);
;     asm volatile("s_waitcnt lgkmcnt(0)" ::: "memory"); SBAR();
;     ...
;     od = __builtin_amdgcn_mfma_f32_32x32x16_bf16(pa0, PK(l0, h0), od, 0, 0, 0);
;     od = __builtin_amdgcn_mfma_f32_32x32x16_bf16(pa1, PK(l1, h1), od, 0, 0, 0);
;     od = __builtin_amdgcn_mfma_f32_32x32x16_bf16(pa2, PK(l2, h2), od, 0, 0, 0);
;     od = __builtin_amdgcn_mfma_f32_32x32x16_bf16(pa3, PK(l3, h3), od, 0, 0, 0);
;     ...
; }
; __device__ __forceinline__ void pv_d0(f32x16 (&o)[4], unsigned vb, bf16x8 pa0, bf16x8 pa1, bf16x8 pa2, bf16x8 pa3) {
;     pv_one<0>(o[0], vb, pa0, pa1, pa2, pa3); pv_one<1>(o[1], vb, pa0, pa1, pa2, pa3); pv_one<2>(o[2], vb, pa0, pa1, pa2, pa3); pv_one<3>(o[3], vb, pa0, pa1, pa2, pa3);
; }
; template <int DQK, bool DOUBLE> ...
;     ...
;         for (int j = 0; j < NT; ++j) {
;             SBAR(); qkt<DQK>(p0, p1, K_lds + bc * K_STRIDE, qr, ka, nMB);
;             partialSM(p0, p1); finishSM(p0, p1, l_reg, pa0, pa1, pa2, pa3); SBAR();
;             pv_d0(o, vb0 + bc * V_BYTES, pa0, pa1, pa2, pa3);
;             if (j + 1 < NT) { VMW0(); __syncthreads(); if (j + 3 < NT) DMA(j + 3, bc); }
;             { const int _t = bc; bc = bn; bn = bf; bf = _t; }
	s_nop 0
	v_mfma_f32_32x32x16_bf16 v[16:31], v[64:67], v[16:19], 0
	v_mfma_f32_32x32x16_bf16 v[16:31], v[86:89], v[32:35], v[16:31]
	ds_read_b64_tr_b16 v[32:33], v170 offset:0x200
	ds_read_b64_tr_b16 v[34:35], v170 offset:0xa00
	ds_read_b64_tr_b16 v[48:49], v170 offset:0x1200
	ds_read_b64_tr_b16 v[50:51], v170 offset:0x1a00
	ds_read_b64_tr_b16 v[52:53], v170 offset:0x2200
	ds_read_b64_tr_b16 v[54:55], v170 offset:0x2a00
	ds_read_b64_tr_b16 v[56:57], v170 offset:0x3200
	v_mfma_f32_32x32x16_bf16 v[16:31], v[90:93], v[36:39], v[16:31]
	ds_read_b64_tr_b16 v[58:59], v170 offset:0x3a00
	s_waitcnt lgkmcnt(0)
	v_mfma_f32_32x32x16_bf16 v[16:31], v[94:97], v[40:43], v[16:31]
	v_mfma_f32_32x32x16_bf16 v[32:47], v[64:67], v[32:35], 0
	v_mfma_f32_32x32x16_bf16 v[32:47], v[86:89], v[48:51], v[32:47]
	ds_read_b64_tr_b16 v[48:49], v170 offset:0x400
	ds_read_b64_tr_b16 v[50:51], v170 offset:0xc00
	ds_read_b64_tr_b16 v[68:69], v170 offset:0x1400
	ds_read_b64_tr_b16 v[70:71], v170 offset:0x1c00
	ds_read_b64_tr_b16 v[72:73], v170 offset:0x2400
	ds_read_b64_tr_b16 v[74:75], v170 offset:0x2c00
	ds_read_b64_tr_b16 v[76:77], v170 offset:0x3400
	v_mfma_f32_32x32x16_bf16 v[32:47], v[90:93], v[52:55], v[32:47]
	ds_read_b64_tr_b16 v[78:79], v170 offset:0x3c00
	s_waitcnt lgkmcnt(0)
	v_mfma_f32_32x32x16_bf16 v[32:47], v[94:97], v[56:59], v[32:47]
	v_mfma_f32_32x32x16_bf16 v[48:63], v[64:67], v[48:51], 0
	v_mfma_f32_32x32x16_bf16 v[48:63], v[86:89], v[68:71], v[48:63]
	ds_read_b64_tr_b16 v[68:69], v170 offset:0x600
	ds_read_b64_tr_b16 v[70:71], v170 offset:0xe00
	ds_read_b64_tr_b16 v[98:99], v170 offset:0x1600
	ds_read_b64_tr_b16 v[100:101], v170 offset:0x1e00
	ds_read_b64_tr_b16 v[102:103], v170 offset:0x2600
	ds_read_b64_tr_b16 v[104:105], v170 offset:0x2e00
	ds_read_b64_tr_b16 v[106:107], v170 offset:0x3600
	v_mfma_f32_32x32x16_bf16 v[48:63], v[90:93], v[72:75], v[48:63]
	ds_read_b64_tr_b16 v[108:109], v170 offset:0x3e00
	s_waitcnt lgkmcnt(0)
	v_mfma_f32_32x32x16_bf16 v[48:63], v[94:97], v[76:79], v[48:63]
	v_mfma_f32_32x32x16_bf16 v[64:79], v[64:67], v[68:71], 0
	s_ashr_i32 s47, s46, 31
	v_lshl_add_u64 v[110:111], v[146:147], 0, s[46:47]
	v_lshlrev_b64 v[110:111], 9, v[110:111]
	v_lshl_add_u64 v[110:111], s[56:57], 0, v[110:111]
	s_mov_b32 m0, s3
	v_lshl_add_u64 v[110:111], v[110:111], 0, v[80:81]
	s_waitcnt vmcnt(0)
	s_waitcnt vmcnt(0)
	s_barrier
	global_load_lds_dwordx4 v[110:111], off
	v_lshl_add_u64 v[110:111], v[148:149], 0, s[46:47]
	v_mfma_f32_32x32x16_bf16 v[64:79], v[86:89], v[98:101], v[64:79]
	v_lshlrev_b64 v[86:87], 9, v[110:111]
	v_lshl_add_u64 v[86:87], s[56:57], 0, v[86:87]
	v_lshl_add_u64 v[86:87], v[86:87], 0, v[80:81]
	s_mov_b32 m0, s21
	v_lshl_add_u64 v[154:155], s[56:57], 0, v[80:81]
	global_load_lds_dwordx4 v[86:87], off
	v_lshl_add_u64 v[86:87], v[150:151], 0, s[46:47]
	v_lshlrev_b64 v[86:87], 9, v[86:87]
	v_lshl_add_u64 v[86:87], s[50:51], 0, v[86:87]
	v_lshl_add_u64 v[86:87], v[86:87], 0, v[82:83]
	s_mov_b32 m0, s20
	v_mfma_f32_32x32x16_bf16 v[64:79], v[90:93], v[102:105], v[64:79]
	global_load_lds_dwordx4 v[86:87], off
	v_lshl_add_u64 v[86:87], v[152:153], 0, s[46:47]
	v_lshlrev_b64 v[86:87], 9, v[86:87]
	v_lshl_add_u64 v[86:87], s[50:51], 0, v[86:87]
	v_lshl_add_u64 v[86:87], v[86:87], 0, v[84:85]
	s_mov_b32 m0, s31
	v_mfma_f32_32x32x16_bf16 v[64:79], v[94:97], v[106:109], v[64:79]
	global_load_lds_dwordx4 v[86:87], off
	v_lshl_add_u64 v[156:157], s[50:51], 0, v[82:83]
	v_lshl_add_u64 v[158:159], s[50:51], 0, v[84:85]
	s_add_i32 s20, s71, -1
	s_mov_b32 s21, 0
	s_mov_b32 s33, 0
	s_waitcnt lgkmcnt(0)
	s_mov_b32 s31, s4
	s_mov_b32 s4, s33
	s_mul_i32 s33, s5, 0x6000
	s_add_i32 s33, s33, 0
	s_lshl_b32 s35, s5, 14
	s_lshl_b32 s100, s4, 14
	s_add_i32 s100, s100, s3
	s_mul_i32 s101, s4, 0x6000
	s_add_i32 s101, s101, s2
	s_mov_b64 vcc, 0
	v_add_u32_e32 v184, s35, v170
	s_mul_i32 s41, s5, 0x6000
	v_add_u32_e32 v174, s41, v145
	v_add_u32_e32 v175, s41, v161
	v_add_u32_e32 v192, s41, v164
	v_add_u32_e32 v193, s41, v165
	v_add_u32_e32 v194, s41, v166
	v_add_u32_e32 v195, s41, v167
	v_add_u32_e32 v196, s41, v168
	v_add_u32_e32 v197, s41, v169
	ds_read_b128 v[204:207], v174 offset:49152
	ds_read_b128 v[208:211], v175 offset:49152
	ds_read_b128 v[212:215], v192 offset:49152
.LBB0_173:
	s_waitcnt lgkmcnt(2)
	v_mfma_f32_32x32x16_bf16 v[96:111], v[204:207], v[112:115], v[0:15]
	ds_read_b128 v[216:219], v193 offset:49152
	s_waitcnt lgkmcnt(2)
	v_mfma_f32_32x32x16_bf16 v[96:111], v[208:211], v[116:119], v[96:111]
	ds_read_b128 v[204:207], v194 offset:49152
	s_cbranch_vccz .Lattn_dma_A_1
	s_ashr_i32 s45, s44, 31
	v_lshl_add_u64 v[172:173], s[44:45], 0, v[146:147]
	v_lshlrev_b64 v[172:173], 9, v[172:173]
	v_lshl_add_u64 v[172:173], v[154:155], 0, v[172:173]
	s_mov_b32 m0, s100
	s_nop 0
	global_load_lds_dwordx4 v[172:173], off

; template <int D0> __device__ __forceinline__ void pv_one(f32x16& od, unsigned vb, bf16x8 pa0, bf16x8 pa1, bf16x8 pa2, bf16x8 pa3) {
;     const s16x4 l0 = tr_read<v_rd_off(D0, 0, 0)>(vb), h0 = tr_read<v_rd_off(D0, 0, 1)>(vb), l1 = tr_read<v_rd_off(D0, 1, 0)>(vb), h1 = tr_read<v_rd_off(D0, 1, 1)>(vb);
;     const s16x4 l2 = tr_read<v_rd_off(D0, 2, 0)>(vb), h2 = tr_read<v_rd_off(D0, 2, 1)>(vb), l3 = tr_read<v_rd_off(D0, 3, 0)>(vb), h3 = tr_read<v_rd_off(D0, 3, 1)>(vb);
;     asm volatile("s_waitcnt lgkmcnt(0)" ::: "memory"); SBAR();
;     ...
;     od = __builtin_amdgcn_mfma_f32_32x32x16_bf16(pa0, PK(l0, h0), od, 0, 0, 0);
;     od = __builtin_amdgcn_mfma_f32_32x32x16_bf16(pa1, PK(l1, h1), od, 0, 0, 0);
;     od = __builtin_amdgcn_mfma_f32_32x32x16_bf16(pa2, PK(l2, h2), od, 0, 0, 0);
;     od = __builtin_amdgcn_mfma_f32_32x32x16_bf16(pa3, PK(l3, h3), od, 0, 0, 0);
;     ...
; }
; __device__ __forceinline__ void pv_d0(f32x16 (&o)[4], unsigned vb, bf16x8 pa0, bf16x8 pa1, bf16x8 pa2, bf16x8 pa3) {
;     pv_one<0>(o[0], vb, pa0, pa1, pa2, pa3); pv_one<1>(o[1], vb, pa0, pa1, pa2, pa3); pv_one<2>(o[2], vb, pa0, pa1, pa2, pa3); pv_one<3>(o[3], vb, pa0, pa1, pa2, pa3);
; }
; __device__ __forceinline__ void partialSM(f32x16& p0, f32x16& p1) {
; #pragma unroll
;     for (int r = 0; r < 16; ++r) p0[r] = __builtin_amdgcn_exp2f(p0[r]);
; }
; __device__ __forceinline__ void finishSM(f32x16& p0, f32x16& p1, float& l_reg, bf16x8& pa0, bf16x8& pa1, bf16x8& pa2, bf16x8& pa3) {
; #pragma unroll
;     for (int r = 0; r < 16; ++r) p1[r] = __builtin_amdgcn_exp2f(p1[r]);
;     float ps = 0;
; #pragma unroll
;     for (int r = 0; r < 16; ++r) ps += p0[r];
; #pragma unroll
;     for (int r = 0; r < 16; ++r) ps += p1[r];
;     l_reg += ps;
;     ...
;     PK8(p0, 0, pa0); PK8(p0, 8, pa1); PK8(p1, 0, pa2); PK8(p1, 8, pa3);
;     ...
; }
; template <int DQK>
; __device__ __forceinline__ void qkt(f32x16& p0, f32x16& p1, const LAS char* Ks, const bf16x8 (&qr)[DQK / 16], const int (&ka)[8], float nMB) {
;     constexpr int RB = DQK * 2, NA = (RB == 256) ? 8 : 4;
; #pragma unroll
;     for (int r = 0; r < 16; ++r) { p0[r] = nMB; p1[r] = nMB; }
; #pragma unroll
;     for (int d0 = 0; d0 < DQK / 16; ++d0) {
;         const LAS char* a = Ks + ka[d0 % NA] + (d0 / NA) * (NA * 32);
;         const bf16x8 b0 = *(const LAS bf16x8*)(a);
;         const bf16x8 b1 = *(const LAS bf16x8*)(a + 32 * RB);
.Lattn_dma_A_4:
	s_waitcnt lgkmcnt(2)
	v_mfma_f32_32x32x16_bf16 v[96:111], v[208:211], v[132:135], v[96:111]
	ds_read_b128 v[204:207], v174 offset:57344
	s_waitcnt lgkmcnt(2)
	v_mfma_f32_32x32x16_bf16 v[96:111], v[212:215], v[136:139], v[96:111]
	ds_read_b128 v[208:211], v175 offset:57344
	s_waitcnt lgkmcnt(2)
	v_mfma_f32_32x32x16_bf16 v[96:111], v[216:219], v[140:143], v[96:111]
	ds_read_b128 v[212:215], v192 offset:57344
	s_waitcnt lgkmcnt(2)
	v_mfma_f32_32x32x16_bf16 v[80:95], v[204:207], v[112:115], v[0:15]
	ds_read_b128 v[216:219], v193 offset:57344
	s_waitcnt lgkmcnt(2)
	v_mfma_f32_32x32x16_bf16 v[80:95], v[208:211], v[116:119], v[80:95]
	ds_read_b128 v[204:207], v194 offset:57344
	s_nop 4
	s_nop 3
	v_exp_f32_e32 v96, v96
	v_exp_f32_e32 v97, v97
	v_exp_f32_e32 v104, v104
	v_exp_f32_e32 v105, v105
	s_waitcnt lgkmcnt(2)
	v_mfma_f32_32x32x16_bf16 v[80:95], v[212:215], v[120:123], v[80:95]
	ds_read_b128 v[208:211], v195 offset:57344
	v_exp_f32_e32 v98, v98
	v_exp_f32_e32 v99, v99
	v_exp_f32_e32 v106, v106
	s_waitcnt lgkmcnt(2)
	v_mfma_f32_32x32x16_bf16 v[80:95], v[216:219], v[124:127], v[80:95]
	ds_read_b128 v[212:215], v196 offset:57344
	v_exp_f32_e32 v100, v100
	v_exp_f32_e32 v101, v101
	v_exp_f32_e32 v107, v107
	s_waitcnt lgkmcnt(2)
	v_mfma_f32_32x32x16_bf16 v[80:95], v[204:207], v[128:131], v[80:95]
	ds_read_b128 v[216:219], v197 offset:57344
	v_exp_f32_e32 v102, v102
	v_exp_f32_e32 v103, v103
	v_exp_f32_e32 v108, v108
	s_waitcnt lgkmcnt(2)
	v_mfma_f32_32x32x16_bf16 v[80:95], v[208:211], v[132:135], v[80:95]
	ds_read_b64_tr_b16 v[204:205], v184 offset:0
	ds_read_b64_tr_b16 v[206:207], v184 offset:2048
	v_cvt_pk_bf16_f32 v172, v96, v97
	v_cvt_pk_bf16_f32 v173, v98, v99
	v_exp_f32_e32 v109, v109
	s_waitcnt lgkmcnt(3)
	v_mfma_f32_32x32x16_bf16 v[80:95], v[212:215], v[136:139], v[80:95]
	ds_read_b64_tr_b16 v[208:209], v184 offset:512
	ds_read_b64_tr_b16 v[210:211], v184 offset:2560
	v_cvt_pk_bf16_f32 v174, v100, v101
	v_exp_f32_e32 v110, v110
	s_waitcnt lgkmcnt(4)
	v_mfma_f32_32x32x16_bf16 v[80:95], v[216:219], v[140:143], v[80:95]
	ds_read_b64_tr_b16 v[212:213], v184 offset:1024
	ds_read_b64_tr_b16 v[214:215], v184 offset:3072
	v_cvt_pk_bf16_f32 v175, v102, v103
	v_exp_f32_e32 v111, v111
	v_add_f32_e32 v96, 0, v96
	v_add_f32_e32 v96, v97, v96
	s_waitcnt lgkmcnt(4)
	v_mfma_f32_32x32x16_bf16 v[16:31], v[172:175], v[204:207], v[16:31]
	ds_read_b64_tr_b16 v[216:217], v184 offset:1536
	ds_read_b64_tr_b16 v[218:219], v184 offset:3584
	v_cvt_pk_bf16_f32 v192, v104, v105
	v_add_f32_e32 v96, v98, v96
	v_add_f32_e32 v96, v99, v96
	v_add_f32_e32 v96, v100, v96
	s_waitcnt lgkmcnt(4)
	v_mfma_f32_32x32x16_bf16 v[32:47], v[172:175], v[208:211], v[32:47]
	ds_read_b64_tr_b16 v[204:205], v184 offset:4096
	ds_read_b64_tr_b16 v[206:207], v184 offset:6144
	v_cvt_pk_bf16_f32 v193, v106, v107
	v_exp_f32_e32 v80, v80
	v_exp_f32_e32 v81, v81
	v_exp_f32_e32 v88, v88
	v_exp_f32_e32 v89, v89
	v_add_f32_e32 v96, v101, v96
	v_add_f32_e32 v96, v102, v96
	s_waitcnt lgkmcnt(4)
	v_mfma_f32_32x32x16_bf16 v[48:63], v[172:175], v[212:215], v[48:63]
	ds_read_b64_tr_b16 v[208:209], v184 offset:4608
	ds_read_b64_tr_b16 v[210:211], v184 offset:6656
	v_cvt_pk_bf16_f32 v194, v108, v109
	v_exp_f32_e32 v82, v82
	v_exp_f32_e32 v83, v83
	v_exp_f32_e32 v90, v90
	v_add_f32_e32 v96, v103, v96
	s_waitcnt lgkmcnt(4)
	v_mfma_f32_32x32x16_bf16 v[64:79], v[172:175], v[216:219], v[64:79]
	ds_read_b64_tr_b16 v[212:213], v184 offset:5120
	ds_read_b64_tr_b16 v[214:215], v184 offset:7168
	v_cvt_pk_bf16_f32 v195, v110, v111
	v_exp_f32_e32 v84, v84
	v_exp_f32_e32 v85, v85
	v_exp_f32_e32 v91, v91
	v_add_f32_e32 v96, v104, v96
	v_add_f32_e32 v96, v105, v96
	s_waitcnt lgkmcnt(4)
; #define SBAR() __builtin_amdgcn_sched_barrier(0)
; #define VMW0() asm volatile("s_waitcnt vmcnt(0)" ::: "memory")
; template <int D0> __device__ __forceinline__ void pv_one(f32x16& od, unsigned vb, bf16x8 pa0, bf16x8 pa1, bf16x8 pa2, bf16x8 pa3) {
;     const s16x4 l0 = tr_read<v_rd_off(D0, 0, 0)>(vb), h0 = tr_read<v_rd_off(D0, 0, 1)>(vb), l1 = tr_read<v_rd_off(D0, 1, 0)>(vb), h1 = tr_read<v_rd_off(D0, 1, 1)>(vb);
;     const s16x4 l2 = tr_read<v_rd_off(D0, 2, 0)>(vb), h2 = tr_read<v_rd_off(D0, 2, 1)>(vb), l3 = tr_read<v_rd_off(D0, 3, 0)>(vb), h3 = tr_read<v_rd_off(D0, 3, 1)>(vb);
;     asm volatile("s_waitcnt lgkmcnt(0)" ::: "memory"); SBAR();
;     ...
;     od = __builtin_amdgcn_mfma_f32_32x32x16_bf16(pa0, PK(l0, h0), od, 0, 0, 0);
;     od = __builtin_amdgcn_mfma_f32_32x32x16_bf16(pa1, PK(l1, h1), od, 0, 0, 0);
;     od = __builtin_amdgcn_mfma_f32_32x32x16_bf16(pa2, PK(l2, h2), od, 0, 0, 0);
;     od = __builtin_amdgcn_mfma_f32_32x32x16_bf16(pa3, PK(l3, h3), od, 0, 0, 0);
;     ...
; }
; __device__ __forceinline__ void pv_d0(f32x16 (&o)[4], unsigned vb, bf16x8 pa0, bf16x8 pa1, bf16x8 pa2, bf16x8 pa3) {
;     pv_one<0>(o[0], vb, pa0, pa1, pa2, pa3); pv_one<1>(o[1], vb, pa0, pa1, pa2, pa3); pv_one<2>(o[2], vb, pa0, pa1, pa2, pa3); pv_one<3>(o[3], vb, pa0, pa1, pa2, pa3);
; }
; template <int DQK, bool DOUBLE> ...
;     ...
;         for (int j = 0; j < NT; ++j) {
;             SBAR(); qkt<DQK>(p0, p1, K_lds + bc * K_STRIDE, qr, ka, nMB);
;             partialSM(p0, p1); finishSM(p0, p1, l_reg, pa0, pa1, pa2, pa3); SBAR();
;             pv_d0(o, vb0 + bc * V_BYTES, pa0, pa1, pa2, pa3);
;             if (j + 1 < NT) { VMW0(); __syncthreads(); if (j + 3 < NT) DMA(j + 3, bc); }
;             { const int _t = bc; bc = bn; bn = bf; bf = _t; }
;         }
	v_mfma_f32_32x32x16_bf16 v[16:31], v[192:195], v[204:207], v[16:31]
	ds_read_b64_tr_b16 v[216:217], v184 offset:5632
	ds_read_b64_tr_b16 v[218:219], v184 offset:7680
	v_exp_f32_e32 v86, v86
	v_exp_f32_e32 v87, v87
	v_exp_f32_e32 v92, v92
	v_add_f32_e32 v96, v106, v96
	v_add_f32_e32 v96, v107, v96
	s_waitcnt lgkmcnt(4)
	v_mfma_f32_32x32x16_bf16 v[32:47], v[192:195], v[208:211], v[32:47]
	ds_read_b64_tr_b16 v[204:205], v184 offset:8192
	ds_read_b64_tr_b16 v[206:207], v184 offset:10240
	v_cvt_pk_bf16_f32 v196, v80, v81
	v_cvt_pk_bf16_f32 v197, v82, v83
	v_exp_f32_e32 v93, v93
	v_add_f32_e32 v96, v108, v96
	v_add_f32_e32 v96, v109, v96
	s_waitcnt lgkmcnt(4)
	v_mfma_f32_32x32x16_bf16 v[48:63], v[192:195], v[212:215], v[48:63]
	ds_read_b64_tr_b16 v[208:209], v184 offset:8704
	ds_read_b64_tr_b16 v[210:211], v184 offset:10752
	v_cvt_pk_bf16_f32 v198, v84, v85
	v_exp_f32_e32 v94, v94
	v_add_f32_e32 v96, v110, v96
	v_add_f32_e32 v96, v111, v96
	s_waitcnt lgkmcnt(4)
	v_mfma_f32_32x32x16_bf16 v[64:79], v[192:195], v[216:219], v[64:79]
	ds_read_b64_tr_b16 v[212:213], v184 offset:9216
	ds_read_b64_tr_b16 v[214:215], v184 offset:11264
	v_cvt_pk_bf16_f32 v199, v86, v87
	v_exp_f32_e32 v95, v95
	v_add_f32_e32 v80, v80, v96
	v_add_f32_e32 v80, v81, v80
	s_waitcnt lgkmcnt(4)
	v_mfma_f32_32x32x16_bf16 v[16:31], v[196:199], v[204:207], v[16:31]
	ds_read_b64_tr_b16 v[216:217], v184 offset:9728
	ds_read_b64_tr_b16 v[218:219], v184 offset:11776
	v_cvt_pk_bf16_f32 v200, v88, v89
	v_add_f32_e32 v80, v82, v80
	v_add_f32_e32 v80, v83, v80
	v_add_f32_e32 v80, v84, v80
	s_waitcnt lgkmcnt(4)
	v_mfma_f32_32x32x16_bf16 v[32:47], v[196:199], v[208:211], v[32:47]
	ds_read_b64_tr_b16 v[204:205], v184 offset:12288
	ds_read_b64_tr_b16 v[206:207], v184 offset:14336
	v_cvt_pk_bf16_f32 v201, v90, v91
	v_add_f32_e32 v80, v85, v80
	v_add_f32_e32 v80, v86, v80
	v_add_f32_e32 v80, v87, v80
	s_waitcnt lgkmcnt(4)
	v_mfma_f32_32x32x16_bf16 v[48:63], v[196:199], v[212:215], v[48:63]
	ds_read_b64_tr_b16 v[208:209], v184 offset:12800
	ds_read_b64_tr_b16 v[210:211], v184 offset:14848
	v_cvt_pk_bf16_f32 v202, v92, v93
	s_waitcnt lgkmcnt(4)
	v_mfma_f32_32x32x16_bf16 v[64:79], v[196:199], v[216:219], v[64:79]
	ds_read_b64_tr_b16 v[212:213], v184 offset:13312
	ds_read_b64_tr_b16 v[214:215], v184 offset:15360
	v_cvt_pk_bf16_f32 v203, v94, v95
	v_add_f32_e32 v80, v88, v80
	v_add_f32_e32 v80, v89, v80
	v_add_f32_e32 v80, v90, v80
	s_waitcnt lgkmcnt(4)
	v_mfma_f32_32x32x16_bf16 v[16:31], v[200:203], v[204:207], v[16:31]
	ds_read_b64_tr_b16 v[216:217], v184 offset:13824
	ds_read_b64_tr_b16 v[218:219], v184 offset:15872
	s_mul_i32 s41, s31, 0x6000
	v_add_u32_e32 v174, s41, v145
	v_add_u32_e32 v175, s41, v161
	v_add_u32_e32 v192, s41, v164
	v_add_u32_e32 v193, s41, v165
	v_add_u32_e32 v194, s41, v166
	v_add_u32_e32 v195, s41, v167
	v_add_u32_e32 v196, s41, v168
	v_add_u32_e32 v197, s41, v169
	v_add_f32_e32 v80, v91, v80
	v_add_f32_e32 v80, v92, v80
	v_add_f32_e32 v80, v93, v80
	v_add_f32_e32 v80, v94, v80
	s_waitcnt lgkmcnt(4)
	v_mfma_f32_32x32x16_bf16 v[32:47], v[200:203], v[208:211], v[32:47]
	ds_read_b128 v[204:207], v174 offset:49152
	v_add_f32_e32 v80, v95, v80
	s_waitcnt lgkmcnt(3)
	v_mfma_f32_32x32x16_bf16 v[48:63], v[200:203], v[212:215], v[48:63]
	ds_read_b128 v[208:211], v175 offset:49152
	s_waitcnt lgkmcnt(2)
	v_mfma_f32_32x32x16_bf16 v[64:79], v[200:203], v[216:219], v[64:79]
	ds_read_b128 v[212:215], v192 offset:49152
	s_mov_b32 s33, s5
	s_mov_b32 s5, s31
	s_mov_b32 s31, s4
	s_mov_b32 s4, s33
	s_mul_i32 s33, s5, 0x6000
	s_add_i32 s33, s33, 0
	s_lshl_b32 s35, s5, 14
	s_lshl_b32 s100, s4, 14
	s_add_i32 s100, s100, s3
	s_mul_i32 s101, s4, 0x6000
	s_add_i32 s101, s101, s2
	s_add_i32 s21, s21, 1
	s_add_i32 s41, s21, 3
	s_cmp_lt_i32 s41, s71
	s_cselect_b64 vcc, -1, 0
	v_add_u32_e32 v184, s35, v170
	v_add_f32_e32 v171, v171, v80
	s_cmp_lg_u32 s20, s21
	s_cbranch_scc0 .LBB0_178
	s_waitcnt vmcnt(0)
	s_barrier
	s_branch .LBB0_173
